# EpiResid GEMM epilogues (w_out, FFN1-down, FFN2-down) rewritten: 12 loads in flight per wave, batched row reductions
# speedup vs baseline: 1.0048x; 1.0048x over previous
; __device__ __forceinline__ float bflo(unsigned u) { return __uint_as_float(u << 16); }
;     __device__ __forceinline__ void operator()(const f32x4 (&acc)[2][2][4][2], const Unit& u, int wr, int wc, int fr, int fq) const {
;         const int row0 = u.pm * BM + wr * 64 + fr, col0 = u.pn * BM + wc * 32 + 8 * fq;
; #pragma unroll
;         for (int ai = 0; ai < 2; ++ai)
; #pragma unroll
;             for (int m = 0; m < 4; ++m) {
;                 const int row = row0 + ai * HALF + m * 16;
;                 float rs = 0.f; if (GATED) rs = rsqrtf(row_ssq(ssq_in, 16, 4, row, fq) * (1.f / 1024.f) + EPS);
;                 float sq = 0.f;
; #pragma unroll
;                 for (int bj = 0; bj < 2; ++bj) {
;                     const size_t off = (size_t)row * DM + col0 + bj * HALF;
;                     const u32x4 hh = *(const u32x4*)(HI + off), ll = *(const u32x4*)(LO + off);
;                     float hv[8] = {bflo(hh.x) + bflo(ll.x), bfhi(hh.x) + bfhi(ll.x), bflo(hh.y) + bflo(ll.y), bfhi(hh.y) + bfhi(ll.y),
;                                    bflo(hh.z) + bflo(ll.z), bfhi(hh.z) + bfhi(ll.z), bflo(hh.w) + bflo(ll.w), bfhi(hh.w) + bfhi(ll.w)};
;                     float av[8] = {acc[ai][bj][m][0][0], acc[ai][bj][m][0][1], acc[ai][bj][m][0][2], acc[ai][bj][m][0][3], acc[ai][bj][m][1][0], acc[ai][bj][m][1][1], acc[ai][bj][m][1][2], acc[ai][bj][m][1][3]};
;                     if (GATED) { const u32x4 pp = *(const u32x4*)(PP + off);
;                         const float pv[8] = {bflo(pp.x), bfhi(pp.x), bflo(pp.y), bfhi(pp.y), bflo(pp.z), bfhi(pp.z), bflo(pp.w), bfhi(pp.w)};
; #pragma unroll
;                         for (int e = 0; e < 8; ++e) av[e] = fast_sigmoid(av[e] * rs) * pv[e]; }
;                     else {
; #pragma unroll
;                         for (int e = 0; e < 8; ++e) av[e] *= alpha; }
;                     float lo[8];
; #pragma unroll
;                     for (int e = 0; e < 8; ++e) { hv[e] += av[e]; sq += hv[e] * hv[e]; }
;                     u32x4 wh; wh.x = pk2(hv[0], hv[1]); wh.y = pk2(hv[2], hv[3]); wh.z = pk2(hv[4], hv[5]); wh.w = pk2(hv[6], hv[7]);
;                     lo[0] = hv[0] - bflo(wh.x); lo[1] = hv[1] - bfhi(wh.x); lo[2] = hv[2] - bflo(wh.y); lo[3] = hv[3] - bfhi(wh.y);
;                     lo[4] = hv[4] - bflo(wh.z); lo[5] = hv[5] - bfhi(wh.z); lo[6] = hv[6] - bflo(wh.w); lo[7] = hv[7] - bfhi(wh.w);
.LBB0_244:
	v_and_b32_e32 v158, 64, v241
	v_xor_b32_e32 v214, 16, v241
	v_add_u32_e32 v158, 64, v158
	v_cmp_lt_i32_e32 vcc, v214, v158
	v_lshl_add_u32 v156, s31, 8, v160
	v_lshl_or_b32 v157, s4, 8, v162
	v_cndmask_b32_e32 v214, v241, v214, vcc
	v_lshlrev_b32_e32 v214, 2, v214
	v_xor_b32_e32 v215, 32, v241
	v_cmp_lt_i32_e32 vcc, v215, v158
	v_readlane_b32 s6, v250, 49
	v_readlane_b32 s7, v250, 50
	v_readlane_b32 s10, v253, 35
	v_readlane_b32 s11, v253, 36
	s_nop 1
	v_cndmask_b32_e32 v215, v241, v215, vcc
	v_lshlrev_b32_e32 v215, 2, v215
	v_lshl_add_u32 v213, v156, 10, v157
	v_lshlrev_b32_e32 v213, 1, v213
	s_lshl_b32 s40, s4, 4
	s_lshl_b32 s52, s25, 2
	s_add_i32 s40, s40, s52
	v_lshlrev_b32_e32 v216, 6, v156
	v_add_u32_e32 v216, s40, v216
	v_add_u32_e32 v217, 0x2000, v216
	s_nop 1
	v_mov_b32_e32 v210, v213
	global_load_dwordx4 v[140:143], v210, s[38:39]
	global_load_dwordx4 v[144:147], v210, s[6:7]
	global_load_dwordx4 v[148:151], v210, s[38:39] offset:256
	global_load_dwordx4 v[152:155], v210, s[6:7] offset:256
	v_add_u32_e32 v211, 0x8000, v213
	global_load_dwordx4 v[164:167], v211, s[38:39]
	global_load_dwordx4 v[168:171], v211, s[6:7]
	global_load_dwordx4 v[172:175], v211, s[38:39] offset:256
	global_load_dwordx4 v[176:179], v211, s[6:7] offset:256
	v_add_u32_e32 v212, 0x10000, v213
	global_load_dwordx4 v[180:183], v212, s[38:39]
	global_load_dwordx4 v[184:187], v212, s[6:7]
	global_load_dwordx4 v[188:191], v212, s[38:39] offset:256
	global_load_dwordx4 v[192:195], v212, s[6:7] offset:256
	s_waitcnt vmcnt(10)
	v_lshlrev_b32_e32 v156, 16, v140
	v_and_b32_e32 v157, 0xffff0000, v140
	v_lshlrev_b32_e32 v158, 16, v144
	v_and_b32_e32 v159, 0xffff0000, v144
	v_pk_add_f32 v[156:157], v[156:157], v[158:159]
	v_pk_fma_f32 v[156:157], v[126:127], 0.5, v[156:157] op_sel_hi:[1,0,1]
	v_cvt_pk_bf16_f32 v140, v156, v157
	v_pk_mul_f32 v[198:199], v[156:157], v[156:157]
	v_lshlrev_b32_e32 v158, 16, v140
	v_and_b32_e32 v159, 0xffff0000, v140
	v_pk_add_f32 v[196:197], v[156:157], v[158:159] neg_lo:[0,1] neg_hi:[0,1]
	v_cvt_pk_bf16_f32 v144, v196, v197
	v_lshlrev_b32_e32 v156, 16, v141
	v_and_b32_e32 v157, 0xffff0000, v141
	v_lshlrev_b32_e32 v158, 16, v145
	v_and_b32_e32 v159, 0xffff0000, v145
	v_pk_add_f32 v[156:157], v[156:157], v[158:159]
	v_pk_fma_f32 v[156:157], v[128:129], 0.5, v[156:157] op_sel_hi:[1,0,1]
	v_cvt_pk_bf16_f32 v141, v156, v157
	v_pk_fma_f32 v[198:199], v[156:157], v[156:157], v[198:199]
	v_lshlrev_b32_e32 v158, 16, v141
	v_and_b32_e32 v159, 0xffff0000, v141
	v_pk_add_f32 v[196:197], v[156:157], v[158:159] neg_lo:[0,1] neg_hi:[0,1]
	v_cvt_pk_bf16_f32 v145, v196, v197
	v_lshlrev_b32_e32 v156, 16, v142
	v_and_b32_e32 v157, 0xffff0000, v142
	v_lshlrev_b32_e32 v158, 16, v146
	v_and_b32_e32 v159, 0xffff0000, v146
	v_pk_add_f32 v[156:157], v[156:157], v[158:159]
	v_pk_fma_f32 v[156:157], v[122:123], 0.5, v[156:157] op_sel_hi:[1,0,1]
	v_cvt_pk_bf16_f32 v142, v156, v157
	v_pk_fma_f32 v[198:199], v[156:157], v[156:157], v[198:199]
	v_lshlrev_b32_e32 v158, 16, v142
	v_and_b32_e32 v159, 0xffff0000, v142
	v_pk_add_f32 v[196:197], v[156:157], v[158:159] neg_lo:[0,1] neg_hi:[0,1]
	v_cvt_pk_bf16_f32 v146, v196, v197
	v_lshlrev_b32_e32 v156, 16, v143
	v_and_b32_e32 v157, 0xffff0000, v143
	v_lshlrev_b32_e32 v158, 16, v147
	v_and_b32_e32 v159, 0xffff0000, v147
	v_pk_add_f32 v[156:157], v[156:157], v[158:159]
	v_pk_fma_f32 v[156:157], v[124:125], 0.5, v[156:157] op_sel_hi:[1,0,1]
	v_cvt_pk_bf16_f32 v143, v156, v157
	v_pk_fma_f32 v[198:199], v[156:157], v[156:157], v[198:199]
	v_lshlrev_b32_e32 v158, 16, v143
	v_and_b32_e32 v159, 0xffff0000, v143
	v_pk_add_f32 v[196:197], v[156:157], v[158:159] neg_lo:[0,1] neg_hi:[0,1]
	v_cvt_pk_bf16_f32 v147, v196, v197
	global_store_dwordx4 v210, v[140:143], s[10:11]
	global_store_dwordx4 v210, v[144:147], s[6:7]
	s_waitcnt vmcnt(10)
	v_lshlrev_b32_e32 v156, 16, v148
	v_and_b32_e32 v157, 0xffff0000, v148
	v_lshlrev_b32_e32 v158, 16, v152
	v_and_b32_e32 v159, 0xffff0000, v152
	v_pk_add_f32 v[156:157], v[156:157], v[158:159]
	v_pk_fma_f32 v[156:157], v[118:119], 0.5, v[156:157] op_sel_hi:[1,0,1]
	v_cvt_pk_bf16_f32 v148, v156, v157
	v_pk_fma_f32 v[198:199], v[156:157], v[156:157], v[198:199]
	v_lshlrev_b32_e32 v158, 16, v148
	v_and_b32_e32 v159, 0xffff0000, v148
	v_pk_add_f32 v[196:197], v[156:157], v[158:159] neg_lo:[0,1] neg_hi:[0,1]
	v_cvt_pk_bf16_f32 v152, v196, v197
	v_lshlrev_b32_e32 v156, 16, v149
	v_and_b32_e32 v157, 0xffff0000, v149
	v_lshlrev_b32_e32 v158, 16, v153
	v_and_b32_e32 v159, 0xffff0000, v153
	v_pk_add_f32 v[156:157], v[156:157], v[158:159]
	v_pk_fma_f32 v[156:157], v[120:121], 0.5, v[156:157] op_sel_hi:[1,0,1]
	v_cvt_pk_bf16_f32 v149, v156, v157
	v_pk_fma_f32 v[198:199], v[156:157], v[156:157], v[198:199]
	v_lshlrev_b32_e32 v158, 16, v149
	v_and_b32_e32 v159, 0xffff0000, v149
	v_pk_add_f32 v[196:197], v[156:157], v[158:159] neg_lo:[0,1] neg_hi:[0,1]
	v_cvt_pk_bf16_f32 v153, v196, v197
	v_lshlrev_b32_e32 v156, 16, v150
	v_and_b32_e32 v157, 0xffff0000, v150
	v_lshlrev_b32_e32 v158, 16, v154
	v_and_b32_e32 v159, 0xffff0000, v154
	v_pk_add_f32 v[156:157], v[156:157], v[158:159]
	v_pk_fma_f32 v[156:157], v[114:115], 0.5, v[156:157] op_sel_hi:[1,0,1]
	v_cvt_pk_bf16_f32 v150, v156, v157
	v_pk_fma_f32 v[198:199], v[156:157], v[156:157], v[198:199]
	v_lshlrev_b32_e32 v158, 16, v150
	v_and_b32_e32 v159, 0xffff0000, v150
	v_pk_add_f32 v[196:197], v[156:157], v[158:159] neg_lo:[0,1] neg_hi:[0,1]
	v_cvt_pk_bf16_f32 v154, v196, v197
	v_lshlrev_b32_e32 v156, 16, v151
	v_and_b32_e32 v157, 0xffff0000, v151
	v_lshlrev_b32_e32 v158, 16, v155
	v_and_b32_e32 v159, 0xffff0000, v155
	v_pk_add_f32 v[156:157], v[156:157], v[158:159]
	v_pk_fma_f32 v[156:157], v[116:117], 0.5, v[156:157] op_sel_hi:[1,0,1]
	v_cvt_pk_bf16_f32 v151, v156, v157
	v_pk_fma_f32 v[198:199], v[156:157], v[156:157], v[198:199]
	v_lshlrev_b32_e32 v158, 16, v151
	v_and_b32_e32 v159, 0xffff0000, v151
	v_pk_add_f32 v[196:197], v[156:157], v[158:159] neg_lo:[0,1] neg_hi:[0,1]
	v_cvt_pk_bf16_f32 v155, v196, v197
	global_store_dwordx4 v210, v[148:151], s[10:11] offset:256
	global_store_dwordx4 v210, v[152:155], s[6:7] offset:256
	v_add_f32_e32 v200, v198, v199
	s_nop 0
	v_add_u32_e32 v210, 0x18000, v213
	global_load_dwordx4 v[140:143], v210, s[38:39]
	global_load_dwordx4 v[144:147], v210, s[6:7]
	global_load_dwordx4 v[148:151], v210, s[38:39] offset:256
	global_load_dwordx4 v[152:155], v210, s[6:7] offset:256
	s_waitcnt vmcnt(14)
; __device__ __forceinline__ unsigned pk2(float lo, float hi) { f32x2_t v = {lo, hi}; bf16x2_t b = __builtin_convertvector(v, bf16x2_t); return __builtin_bit_cast(unsigned, b); }
; __device__ __forceinline__ float bflo(unsigned u) { return __uint_as_float(u << 16); }
; __device__ __forceinline__ float bfhi(unsigned u) { return __uint_as_float(u & 0xffff0000u); }
;     __device__ __forceinline__ void operator()(const f32x4 (&acc)[2][2][4][2], const Unit& u, int wr, int wc, int fr, int fq) const {
;     ...
;                     const size_t off = (size_t)row * DM + col0 + bj * HALF;
;                     const u32x4 hh = *(const u32x4*)(HI + off), ll = *(const u32x4*)(LO + off);
;                     float hv[8] = {bflo(hh.x) + bflo(ll.x), bfhi(hh.x) + bfhi(ll.x), bflo(hh.y) + bflo(ll.y), bfhi(hh.y) + bfhi(ll.y),
;                                    bflo(hh.z) + bflo(ll.z), bfhi(hh.z) + bfhi(ll.z), bflo(hh.w) + bflo(ll.w), bfhi(hh.w) + bfhi(ll.w)};
;                     float av[8] = {acc[ai][bj][m][0][0], acc[ai][bj][m][0][1], acc[ai][bj][m][0][2], acc[ai][bj][m][0][3], acc[ai][bj][m][1][0], acc[ai][bj][m][1][1], acc[ai][bj][m][1][2], acc[ai][bj][m][1][3]};
;                     if (GATED) { const u32x4 pp = *(const u32x4*)(PP + off);
;                         const float pv[8] = {bflo(pp.x), bfhi(pp.x), bflo(pp.y), bfhi(pp.y), bflo(pp.z), bfhi(pp.z), bflo(pp.w), bfhi(pp.w)};
; #pragma unroll
;                         for (int e = 0; e < 8; ++e) av[e] = fast_sigmoid(av[e] * rs) * pv[e]; }
;                     else {
; #pragma unroll
;                         for (int e = 0; e < 8; ++e) av[e] *= alpha; }
;                     float lo[8];
; #pragma unroll
;                     for (int e = 0; e < 8; ++e) { hv[e] += av[e]; sq += hv[e] * hv[e]; }
;                     u32x4 wh; wh.x = pk2(hv[0], hv[1]); wh.y = pk2(hv[2], hv[3]); wh.z = pk2(hv[4], hv[5]); wh.w = pk2(hv[6], hv[7]);
;                     lo[0] = hv[0] - bflo(wh.x); lo[1] = hv[1] - bfhi(wh.x); lo[2] = hv[2] - bflo(wh.y); lo[3] = hv[3] - bfhi(wh.y);
;                     lo[4] = hv[4] - bflo(wh.z); lo[5] = hv[5] - bfhi(wh.z); lo[6] = hv[6] - bflo(wh.w); lo[7] = hv[7] - bfhi(wh.w);
;                     u32x4 wl; wl.x = pk2(lo[0], lo[1]); wl.y = pk2(lo[2], lo[3]); wl.z = pk2(lo[4], lo[5]); wl.w = pk2(lo[6], lo[7]);
;                     *(u32x4*)(HO + off) = wh; *(u32x4*)(LO + off) = wl;
	v_lshlrev_b32_e32 v156, 16, v164
	v_and_b32_e32 v157, 0xffff0000, v164
	v_lshlrev_b32_e32 v158, 16, v168
	v_and_b32_e32 v159, 0xffff0000, v168
	v_pk_add_f32 v[156:157], v[156:157], v[158:159]
	v_pk_fma_f32 v[156:157], v[110:111], 0.5, v[156:157] op_sel_hi:[1,0,1]
	v_cvt_pk_bf16_f32 v164, v156, v157
	v_pk_mul_f32 v[198:199], v[156:157], v[156:157]
	v_lshlrev_b32_e32 v158, 16, v164
	v_and_b32_e32 v159, 0xffff0000, v164
	v_pk_add_f32 v[196:197], v[156:157], v[158:159] neg_lo:[0,1] neg_hi:[0,1]
	v_cvt_pk_bf16_f32 v168, v196, v197
	v_lshlrev_b32_e32 v156, 16, v165
	v_and_b32_e32 v157, 0xffff0000, v165
	v_lshlrev_b32_e32 v158, 16, v169
	v_and_b32_e32 v159, 0xffff0000, v169
	v_pk_add_f32 v[156:157], v[156:157], v[158:159]
	v_pk_fma_f32 v[156:157], v[112:113], 0.5, v[156:157] op_sel_hi:[1,0,1]
	v_cvt_pk_bf16_f32 v165, v156, v157
	v_pk_fma_f32 v[198:199], v[156:157], v[156:157], v[198:199]
	v_lshlrev_b32_e32 v158, 16, v165
	v_and_b32_e32 v159, 0xffff0000, v165
	v_pk_add_f32 v[196:197], v[156:157], v[158:159] neg_lo:[0,1] neg_hi:[0,1]
	v_cvt_pk_bf16_f32 v169, v196, v197
	v_lshlrev_b32_e32 v156, 16, v166
	v_and_b32_e32 v157, 0xffff0000, v166
	v_lshlrev_b32_e32 v158, 16, v170
	v_and_b32_e32 v159, 0xffff0000, v170
	v_pk_add_f32 v[156:157], v[156:157], v[158:159]
	v_pk_fma_f32 v[156:157], v[106:107], 0.5, v[156:157] op_sel_hi:[1,0,1]
	v_cvt_pk_bf16_f32 v166, v156, v157
	v_pk_fma_f32 v[198:199], v[156:157], v[156:157], v[198:199]
	v_lshlrev_b32_e32 v158, 16, v166
	v_and_b32_e32 v159, 0xffff0000, v166
	v_pk_add_f32 v[196:197], v[156:157], v[158:159] neg_lo:[0,1] neg_hi:[0,1]
	v_cvt_pk_bf16_f32 v170, v196, v197
	v_lshlrev_b32_e32 v156, 16, v167
	v_and_b32_e32 v157, 0xffff0000, v167
	v_lshlrev_b32_e32 v158, 16, v171
	v_and_b32_e32 v159, 0xffff0000, v171
	v_pk_add_f32 v[156:157], v[156:157], v[158:159]
	v_pk_fma_f32 v[156:157], v[108:109], 0.5, v[156:157] op_sel_hi:[1,0,1]
	v_cvt_pk_bf16_f32 v167, v156, v157
	v_pk_fma_f32 v[198:199], v[156:157], v[156:157], v[198:199]
	v_lshlrev_b32_e32 v158, 16, v167
	v_and_b32_e32 v159, 0xffff0000, v167
	v_pk_add_f32 v[196:197], v[156:157], v[158:159] neg_lo:[0,1] neg_hi:[0,1]
	v_cvt_pk_bf16_f32 v171, v196, v197
	global_store_dwordx4 v211, v[164:167], s[10:11]
	global_store_dwordx4 v211, v[168:171], s[6:7]
	s_waitcnt vmcnt(14)
	v_lshlrev_b32_e32 v156, 16, v172
	v_and_b32_e32 v157, 0xffff0000, v172
	v_lshlrev_b32_e32 v158, 16, v176
	v_and_b32_e32 v159, 0xffff0000, v176
	v_pk_add_f32 v[156:157], v[156:157], v[158:159]
	v_pk_fma_f32 v[156:157], v[102:103], 0.5, v[156:157] op_sel_hi:[1,0,1]
	v_cvt_pk_bf16_f32 v172, v156, v157
	v_pk_fma_f32 v[198:199], v[156:157], v[156:157], v[198:199]
	v_lshlrev_b32_e32 v158, 16, v172
	v_and_b32_e32 v159, 0xffff0000, v172
	v_pk_add_f32 v[196:197], v[156:157], v[158:159] neg_lo:[0,1] neg_hi:[0,1]
	v_cvt_pk_bf16_f32 v176, v196, v197
	v_lshlrev_b32_e32 v156, 16, v173
	v_and_b32_e32 v157, 0xffff0000, v173
	v_lshlrev_b32_e32 v158, 16, v177
	v_and_b32_e32 v159, 0xffff0000, v177
	v_pk_add_f32 v[156:157], v[156:157], v[158:159]
	v_pk_fma_f32 v[156:157], v[104:105], 0.5, v[156:157] op_sel_hi:[1,0,1]
	v_cvt_pk_bf16_f32 v173, v156, v157
	v_pk_fma_f32 v[198:199], v[156:157], v[156:157], v[198:199]
	v_lshlrev_b32_e32 v158, 16, v173
	v_and_b32_e32 v159, 0xffff0000, v173
	v_pk_add_f32 v[196:197], v[156:157], v[158:159] neg_lo:[0,1] neg_hi:[0,1]
	v_cvt_pk_bf16_f32 v177, v196, v197
	v_lshlrev_b32_e32 v156, 16, v174
	v_and_b32_e32 v157, 0xffff0000, v174
	v_lshlrev_b32_e32 v158, 16, v178
	v_and_b32_e32 v159, 0xffff0000, v178
	v_pk_add_f32 v[156:157], v[156:157], v[158:159]
	v_pk_fma_f32 v[156:157], v[98:99], 0.5, v[156:157] op_sel_hi:[1,0,1]
	v_cvt_pk_bf16_f32 v174, v156, v157
	v_pk_fma_f32 v[198:199], v[156:157], v[156:157], v[198:199]
	v_lshlrev_b32_e32 v158, 16, v174
	v_and_b32_e32 v159, 0xffff0000, v174
	v_pk_add_f32 v[196:197], v[156:157], v[158:159] neg_lo:[0,1] neg_hi:[0,1]
	v_cvt_pk_bf16_f32 v178, v196, v197
	v_lshlrev_b32_e32 v156, 16, v175
	v_and_b32_e32 v157, 0xffff0000, v175
	v_lshlrev_b32_e32 v158, 16, v179
	v_and_b32_e32 v159, 0xffff0000, v179
	v_pk_add_f32 v[156:157], v[156:157], v[158:159]
	v_pk_fma_f32 v[156:157], v[100:101], 0.5, v[156:157] op_sel_hi:[1,0,1]
	v_cvt_pk_bf16_f32 v175, v156, v157
	v_pk_fma_f32 v[198:199], v[156:157], v[156:157], v[198:199]
	v_lshlrev_b32_e32 v158, 16, v175
	v_and_b32_e32 v159, 0xffff0000, v175
	v_pk_add_f32 v[196:197], v[156:157], v[158:159] neg_lo:[0,1] neg_hi:[0,1]
	v_cvt_pk_bf16_f32 v179, v196, v197
	global_store_dwordx4 v211, v[172:175], s[10:11] offset:256
	global_store_dwordx4 v211, v[176:179], s[6:7] offset:256
	v_add_f32_e32 v201, v198, v199
	s_nop 0
	v_add_u32_e32 v211, 0x40000, v213
	global_load_dwordx4 v[164:167], v211, s[38:39]
	global_load_dwordx4 v[168:171], v211, s[6:7]
	global_load_dwordx4 v[172:175], v211, s[38:39] offset:256
	global_load_dwordx4 v[176:179], v211, s[6:7] offset:256
	s_waitcnt vmcnt(18)
; __device__ __forceinline__ unsigned pk2(float lo, float hi) { f32x2_t v = {lo, hi}; bf16x2_t b = __builtin_convertvector(v, bf16x2_t); return __builtin_bit_cast(unsigned, b); }
; __device__ __forceinline__ float bflo(unsigned u) { return __uint_as_float(u << 16); }
; __device__ __forceinline__ float bfhi(unsigned u) { return __uint_as_float(u & 0xffff0000u); }
;     __device__ __forceinline__ void operator()(const f32x4 (&acc)[2][2][4][2], const Unit& u, int wr, int wc, int fr, int fq) const {
;     ...
;                     const size_t off = (size_t)row * DM + col0 + bj * HALF;
;                     const u32x4 hh = *(const u32x4*)(HI + off), ll = *(const u32x4*)(LO + off);
;                     float hv[8] = {bflo(hh.x) + bflo(ll.x), bfhi(hh.x) + bfhi(ll.x), bflo(hh.y) + bflo(ll.y), bfhi(hh.y) + bfhi(ll.y),
;                                    bflo(hh.z) + bflo(ll.z), bfhi(hh.z) + bfhi(ll.z), bflo(hh.w) + bflo(ll.w), bfhi(hh.w) + bfhi(ll.w)};
;                     float av[8] = {acc[ai][bj][m][0][0], acc[ai][bj][m][0][1], acc[ai][bj][m][0][2], acc[ai][bj][m][0][3], acc[ai][bj][m][1][0], acc[ai][bj][m][1][1], acc[ai][bj][m][1][2], acc[ai][bj][m][1][3]};
;                     if (GATED) { const u32x4 pp = *(const u32x4*)(PP + off);
;                         const float pv[8] = {bflo(pp.x), bfhi(pp.x), bflo(pp.y), bfhi(pp.y), bflo(pp.z), bfhi(pp.z), bflo(pp.w), bfhi(pp.w)};
; #pragma unroll
;                         for (int e = 0; e < 8; ++e) av[e] = fast_sigmoid(av[e] * rs) * pv[e]; }
;                     else {
; #pragma unroll
;                         for (int e = 0; e < 8; ++e) av[e] *= alpha; }
;                     float lo[8];
; #pragma unroll
;                     for (int e = 0; e < 8; ++e) { hv[e] += av[e]; sq += hv[e] * hv[e]; }
;                     u32x4 wh; wh.x = pk2(hv[0], hv[1]); wh.y = pk2(hv[2], hv[3]); wh.z = pk2(hv[4], hv[5]); wh.w = pk2(hv[6], hv[7]);
;                     lo[0] = hv[0] - bflo(wh.x); lo[1] = hv[1] - bfhi(wh.x); lo[2] = hv[2] - bflo(wh.y); lo[3] = hv[3] - bfhi(wh.y);
;                     lo[4] = hv[4] - bflo(wh.z); lo[5] = hv[5] - bfhi(wh.z); lo[6] = hv[6] - bflo(wh.w); lo[7] = hv[7] - bfhi(wh.w);
;                     u32x4 wl; wl.x = pk2(lo[0], lo[1]); wl.y = pk2(lo[2], lo[3]); wl.z = pk2(lo[4], lo[5]); wl.w = pk2(lo[6], lo[7]);
;                     *(u32x4*)(HO + off) = wh; *(u32x4*)(LO + off) = wl;
	v_lshlrev_b32_e32 v156, 16, v180
	v_and_b32_e32 v157, 0xffff0000, v180
	v_lshlrev_b32_e32 v158, 16, v184
	v_and_b32_e32 v159, 0xffff0000, v184
	v_pk_add_f32 v[156:157], v[156:157], v[158:159]
	v_pk_fma_f32 v[156:157], v[94:95], 0.5, v[156:157] op_sel_hi:[1,0,1]
	v_cvt_pk_bf16_f32 v180, v156, v157
	v_pk_mul_f32 v[198:199], v[156:157], v[156:157]
	v_lshlrev_b32_e32 v158, 16, v180
	v_and_b32_e32 v159, 0xffff0000, v180
	v_pk_add_f32 v[196:197], v[156:157], v[158:159] neg_lo:[0,1] neg_hi:[0,1]
	v_cvt_pk_bf16_f32 v184, v196, v197
	v_lshlrev_b32_e32 v156, 16, v181
	v_and_b32_e32 v157, 0xffff0000, v181
	v_lshlrev_b32_e32 v158, 16, v185
	v_and_b32_e32 v159, 0xffff0000, v185
	v_pk_add_f32 v[156:157], v[156:157], v[158:159]
	v_pk_fma_f32 v[156:157], v[96:97], 0.5, v[156:157] op_sel_hi:[1,0,1]
	v_cvt_pk_bf16_f32 v181, v156, v157
	v_pk_fma_f32 v[198:199], v[156:157], v[156:157], v[198:199]
	v_lshlrev_b32_e32 v158, 16, v181
	v_and_b32_e32 v159, 0xffff0000, v181
	v_pk_add_f32 v[196:197], v[156:157], v[158:159] neg_lo:[0,1] neg_hi:[0,1]
	v_cvt_pk_bf16_f32 v185, v196, v197
	v_lshlrev_b32_e32 v156, 16, v182
	v_and_b32_e32 v157, 0xffff0000, v182
	v_lshlrev_b32_e32 v158, 16, v186
	v_and_b32_e32 v159, 0xffff0000, v186
	v_pk_add_f32 v[156:157], v[156:157], v[158:159]
	v_pk_fma_f32 v[156:157], v[90:91], 0.5, v[156:157] op_sel_hi:[1,0,1]
	v_cvt_pk_bf16_f32 v182, v156, v157
	v_pk_fma_f32 v[198:199], v[156:157], v[156:157], v[198:199]
	v_lshlrev_b32_e32 v158, 16, v182
	v_and_b32_e32 v159, 0xffff0000, v182
	v_pk_add_f32 v[196:197], v[156:157], v[158:159] neg_lo:[0,1] neg_hi:[0,1]
	v_cvt_pk_bf16_f32 v186, v196, v197
	v_lshlrev_b32_e32 v156, 16, v183
	v_and_b32_e32 v157, 0xffff0000, v183
	v_lshlrev_b32_e32 v158, 16, v187
	v_and_b32_e32 v159, 0xffff0000, v187
	v_pk_add_f32 v[156:157], v[156:157], v[158:159]
	v_pk_fma_f32 v[156:157], v[92:93], 0.5, v[156:157] op_sel_hi:[1,0,1]
	v_cvt_pk_bf16_f32 v183, v156, v157
	v_pk_fma_f32 v[198:199], v[156:157], v[156:157], v[198:199]
	v_lshlrev_b32_e32 v158, 16, v183
	v_and_b32_e32 v159, 0xffff0000, v183
	v_pk_add_f32 v[196:197], v[156:157], v[158:159] neg_lo:[0,1] neg_hi:[0,1]
	v_cvt_pk_bf16_f32 v187, v196, v197
	global_store_dwordx4 v212, v[180:183], s[10:11]
	global_store_dwordx4 v212, v[184:187], s[6:7]
	s_waitcnt vmcnt(18)
	v_lshlrev_b32_e32 v156, 16, v188
	v_and_b32_e32 v157, 0xffff0000, v188
	v_lshlrev_b32_e32 v158, 16, v192
	v_and_b32_e32 v159, 0xffff0000, v192
	v_pk_add_f32 v[156:157], v[156:157], v[158:159]
	v_pk_fma_f32 v[156:157], v[86:87], 0.5, v[156:157] op_sel_hi:[1,0,1]
	v_cvt_pk_bf16_f32 v188, v156, v157
	v_pk_fma_f32 v[198:199], v[156:157], v[156:157], v[198:199]
	v_lshlrev_b32_e32 v158, 16, v188
	v_and_b32_e32 v159, 0xffff0000, v188
	v_pk_add_f32 v[196:197], v[156:157], v[158:159] neg_lo:[0,1] neg_hi:[0,1]
	v_cvt_pk_bf16_f32 v192, v196, v197
	v_lshlrev_b32_e32 v156, 16, v189
	v_and_b32_e32 v157, 0xffff0000, v189
	v_lshlrev_b32_e32 v158, 16, v193
	v_and_b32_e32 v159, 0xffff0000, v193
	v_pk_add_f32 v[156:157], v[156:157], v[158:159]
	v_pk_fma_f32 v[156:157], v[88:89], 0.5, v[156:157] op_sel_hi:[1,0,1]
	v_cvt_pk_bf16_f32 v189, v156, v157
	v_pk_fma_f32 v[198:199], v[156:157], v[156:157], v[198:199]
	v_lshlrev_b32_e32 v158, 16, v189
	v_and_b32_e32 v159, 0xffff0000, v189
	v_pk_add_f32 v[196:197], v[156:157], v[158:159] neg_lo:[0,1] neg_hi:[0,1]
	v_cvt_pk_bf16_f32 v193, v196, v197
	v_lshlrev_b32_e32 v156, 16, v190
	v_and_b32_e32 v157, 0xffff0000, v190
	v_lshlrev_b32_e32 v158, 16, v194
	v_and_b32_e32 v159, 0xffff0000, v194
	v_pk_add_f32 v[156:157], v[156:157], v[158:159]
	v_pk_fma_f32 v[156:157], v[82:83], 0.5, v[156:157] op_sel_hi:[1,0,1]
	v_cvt_pk_bf16_f32 v190, v156, v157
	v_pk_fma_f32 v[198:199], v[156:157], v[156:157], v[198:199]
	v_lshlrev_b32_e32 v158, 16, v190
	v_and_b32_e32 v159, 0xffff0000, v190
	v_pk_add_f32 v[196:197], v[156:157], v[158:159] neg_lo:[0,1] neg_hi:[0,1]
	v_cvt_pk_bf16_f32 v194, v196, v197
	v_lshlrev_b32_e32 v156, 16, v191
	v_and_b32_e32 v157, 0xffff0000, v191
	v_lshlrev_b32_e32 v158, 16, v195
	v_and_b32_e32 v159, 0xffff0000, v195
	v_pk_add_f32 v[156:157], v[156:157], v[158:159]
	v_pk_fma_f32 v[156:157], v[84:85], 0.5, v[156:157] op_sel_hi:[1,0,1]
	v_cvt_pk_bf16_f32 v191, v156, v157
	v_pk_fma_f32 v[198:199], v[156:157], v[156:157], v[198:199]
	v_lshlrev_b32_e32 v158, 16, v191
	v_and_b32_e32 v159, 0xffff0000, v191
	v_pk_add_f32 v[196:197], v[156:157], v[158:159] neg_lo:[0,1] neg_hi:[0,1]
	v_cvt_pk_bf16_f32 v195, v196, v197
	global_store_dwordx4 v212, v[188:191], s[10:11] offset:256
	global_store_dwordx4 v212, v[192:195], s[6:7] offset:256
	v_add_f32_e32 v202, v198, v199
	s_nop 0
	v_add_u32_e32 v212, 0x48000, v213
	global_load_dwordx4 v[180:183], v212, s[38:39]
	global_load_dwordx4 v[184:187], v212, s[6:7]
	global_load_dwordx4 v[188:191], v212, s[38:39] offset:256
	global_load_dwordx4 v[192:195], v212, s[6:7] offset:256
	s_waitcnt vmcnt(18)
; __device__ __forceinline__ unsigned pk2(float lo, float hi) { f32x2_t v = {lo, hi}; bf16x2_t b = __builtin_convertvector(v, bf16x2_t); return __builtin_bit_cast(unsigned, b); }
; __device__ __forceinline__ float bflo(unsigned u) { return __uint_as_float(u << 16); }
; __device__ __forceinline__ float bfhi(unsigned u) { return __uint_as_float(u & 0xffff0000u); }
;     __device__ __forceinline__ void operator()(const f32x4 (&acc)[2][2][4][2], const Unit& u, int wr, int wc, int fr, int fq) const {
;     ...
;                     const size_t off = (size_t)row * DM + col0 + bj * HALF;
;                     const u32x4 hh = *(const u32x4*)(HI + off), ll = *(const u32x4*)(LO + off);
;                     float hv[8] = {bflo(hh.x) + bflo(ll.x), bfhi(hh.x) + bfhi(ll.x), bflo(hh.y) + bflo(ll.y), bfhi(hh.y) + bfhi(ll.y),
;                                    bflo(hh.z) + bflo(ll.z), bfhi(hh.z) + bfhi(ll.z), bflo(hh.w) + bflo(ll.w), bfhi(hh.w) + bfhi(ll.w)};
;                     float av[8] = {acc[ai][bj][m][0][0], acc[ai][bj][m][0][1], acc[ai][bj][m][0][2], acc[ai][bj][m][0][3], acc[ai][bj][m][1][0], acc[ai][bj][m][1][1], acc[ai][bj][m][1][2], acc[ai][bj][m][1][3]};
;                     if (GATED) { const u32x4 pp = *(const u32x4*)(PP + off);
;                         const float pv[8] = {bflo(pp.x), bfhi(pp.x), bflo(pp.y), bfhi(pp.y), bflo(pp.z), bfhi(pp.z), bflo(pp.w), bfhi(pp.w)};
; #pragma unroll
;                         for (int e = 0; e < 8; ++e) av[e] = fast_sigmoid(av[e] * rs) * pv[e]; }
;                     else {
; #pragma unroll
;                         for (int e = 0; e < 8; ++e) av[e] *= alpha; }
;                     float lo[8];
; #pragma unroll
;                     for (int e = 0; e < 8; ++e) { hv[e] += av[e]; sq += hv[e] * hv[e]; }
;                     u32x4 wh; wh.x = pk2(hv[0], hv[1]); wh.y = pk2(hv[2], hv[3]); wh.z = pk2(hv[4], hv[5]); wh.w = pk2(hv[6], hv[7]);
;                     lo[0] = hv[0] - bflo(wh.x); lo[1] = hv[1] - bfhi(wh.x); lo[2] = hv[2] - bflo(wh.y); lo[3] = hv[3] - bfhi(wh.y);
;                     lo[4] = hv[4] - bflo(wh.z); lo[5] = hv[5] - bfhi(wh.z); lo[6] = hv[6] - bflo(wh.w); lo[7] = hv[7] - bfhi(wh.w);
;                     u32x4 wl; wl.x = pk2(lo[0], lo[1]); wl.y = pk2(lo[2], lo[3]); wl.z = pk2(lo[4], lo[5]); wl.w = pk2(lo[6], lo[7]);
;                     *(u32x4*)(HO + off) = wh; *(u32x4*)(LO + off) = wl;
	v_lshlrev_b32_e32 v156, 16, v140
	v_and_b32_e32 v157, 0xffff0000, v140
	v_lshlrev_b32_e32 v158, 16, v144
	v_and_b32_e32 v159, 0xffff0000, v144
	v_pk_add_f32 v[156:157], v[156:157], v[158:159]
	v_pk_fma_f32 v[156:157], v[78:79], 0.5, v[156:157] op_sel_hi:[1,0,1]
	v_cvt_pk_bf16_f32 v140, v156, v157
	v_pk_mul_f32 v[198:199], v[156:157], v[156:157]
	v_lshlrev_b32_e32 v158, 16, v140
	v_and_b32_e32 v159, 0xffff0000, v140
	v_pk_add_f32 v[196:197], v[156:157], v[158:159] neg_lo:[0,1] neg_hi:[0,1]
	v_cvt_pk_bf16_f32 v144, v196, v197
	v_lshlrev_b32_e32 v156, 16, v141
	v_and_b32_e32 v157, 0xffff0000, v141
	v_lshlrev_b32_e32 v158, 16, v145
	v_and_b32_e32 v159, 0xffff0000, v145
	v_pk_add_f32 v[156:157], v[156:157], v[158:159]
	v_pk_fma_f32 v[156:157], v[80:81], 0.5, v[156:157] op_sel_hi:[1,0,1]
	v_cvt_pk_bf16_f32 v141, v156, v157
	v_pk_fma_f32 v[198:199], v[156:157], v[156:157], v[198:199]
	v_lshlrev_b32_e32 v158, 16, v141
	v_and_b32_e32 v159, 0xffff0000, v141
	v_pk_add_f32 v[196:197], v[156:157], v[158:159] neg_lo:[0,1] neg_hi:[0,1]
	v_cvt_pk_bf16_f32 v145, v196, v197
	v_lshlrev_b32_e32 v156, 16, v142
	v_and_b32_e32 v157, 0xffff0000, v142
	v_lshlrev_b32_e32 v158, 16, v146
	v_and_b32_e32 v159, 0xffff0000, v146
	v_pk_add_f32 v[156:157], v[156:157], v[158:159]
	v_pk_fma_f32 v[156:157], v[74:75], 0.5, v[156:157] op_sel_hi:[1,0,1]
	v_cvt_pk_bf16_f32 v142, v156, v157
	v_pk_fma_f32 v[198:199], v[156:157], v[156:157], v[198:199]
	v_lshlrev_b32_e32 v158, 16, v142
	v_and_b32_e32 v159, 0xffff0000, v142
	v_pk_add_f32 v[196:197], v[156:157], v[158:159] neg_lo:[0,1] neg_hi:[0,1]
	v_cvt_pk_bf16_f32 v146, v196, v197
	v_lshlrev_b32_e32 v156, 16, v143
	v_and_b32_e32 v157, 0xffff0000, v143
	v_lshlrev_b32_e32 v158, 16, v147
	v_and_b32_e32 v159, 0xffff0000, v147
	v_pk_add_f32 v[156:157], v[156:157], v[158:159]
	v_pk_fma_f32 v[156:157], v[76:77], 0.5, v[156:157] op_sel_hi:[1,0,1]
	v_cvt_pk_bf16_f32 v143, v156, v157
	v_pk_fma_f32 v[198:199], v[156:157], v[156:157], v[198:199]
	v_lshlrev_b32_e32 v158, 16, v143
	v_and_b32_e32 v159, 0xffff0000, v143
	v_pk_add_f32 v[196:197], v[156:157], v[158:159] neg_lo:[0,1] neg_hi:[0,1]
	v_cvt_pk_bf16_f32 v147, v196, v197
	global_store_dwordx4 v210, v[140:143], s[10:11]
	global_store_dwordx4 v210, v[144:147], s[6:7]
	s_waitcnt vmcnt(18)
	v_lshlrev_b32_e32 v156, 16, v148
	v_and_b32_e32 v157, 0xffff0000, v148
	v_lshlrev_b32_e32 v158, 16, v152
	v_and_b32_e32 v159, 0xffff0000, v152
	v_pk_add_f32 v[156:157], v[156:157], v[158:159]
	v_pk_fma_f32 v[156:157], v[70:71], 0.5, v[156:157] op_sel_hi:[1,0,1]
	v_cvt_pk_bf16_f32 v148, v156, v157
	v_pk_fma_f32 v[198:199], v[156:157], v[156:157], v[198:199]
	v_lshlrev_b32_e32 v158, 16, v148
	v_and_b32_e32 v159, 0xffff0000, v148
	v_pk_add_f32 v[196:197], v[156:157], v[158:159] neg_lo:[0,1] neg_hi:[0,1]
	v_cvt_pk_bf16_f32 v152, v196, v197
	v_lshlrev_b32_e32 v156, 16, v149
	v_and_b32_e32 v157, 0xffff0000, v149
	v_lshlrev_b32_e32 v158, 16, v153
	v_and_b32_e32 v159, 0xffff0000, v153
	v_pk_add_f32 v[156:157], v[156:157], v[158:159]
	v_pk_fma_f32 v[156:157], v[72:73], 0.5, v[156:157] op_sel_hi:[1,0,1]
	v_cvt_pk_bf16_f32 v149, v156, v157
	v_pk_fma_f32 v[198:199], v[156:157], v[156:157], v[198:199]
	v_lshlrev_b32_e32 v158, 16, v149
	v_and_b32_e32 v159, 0xffff0000, v149
	v_pk_add_f32 v[196:197], v[156:157], v[158:159] neg_lo:[0,1] neg_hi:[0,1]
	v_cvt_pk_bf16_f32 v153, v196, v197
	v_lshlrev_b32_e32 v156, 16, v150
	v_and_b32_e32 v157, 0xffff0000, v150
	v_lshlrev_b32_e32 v158, 16, v154
	v_and_b32_e32 v159, 0xffff0000, v154
	v_pk_add_f32 v[156:157], v[156:157], v[158:159]
	v_pk_fma_f32 v[156:157], v[66:67], 0.5, v[156:157] op_sel_hi:[1,0,1]
	v_cvt_pk_bf16_f32 v150, v156, v157
	v_pk_fma_f32 v[198:199], v[156:157], v[156:157], v[198:199]
	v_lshlrev_b32_e32 v158, 16, v150
	v_and_b32_e32 v159, 0xffff0000, v150
	v_pk_add_f32 v[196:197], v[156:157], v[158:159] neg_lo:[0,1] neg_hi:[0,1]
	v_cvt_pk_bf16_f32 v154, v196, v197
	v_lshlrev_b32_e32 v156, 16, v151
	v_and_b32_e32 v157, 0xffff0000, v151
	v_lshlrev_b32_e32 v158, 16, v155
	v_and_b32_e32 v159, 0xffff0000, v155
	v_pk_add_f32 v[156:157], v[156:157], v[158:159]
	v_pk_fma_f32 v[156:157], v[68:69], 0.5, v[156:157] op_sel_hi:[1,0,1]
	v_cvt_pk_bf16_f32 v151, v156, v157
	v_pk_fma_f32 v[198:199], v[156:157], v[156:157], v[198:199]
	v_lshlrev_b32_e32 v158, 16, v151
	v_and_b32_e32 v159, 0xffff0000, v151
	v_pk_add_f32 v[196:197], v[156:157], v[158:159] neg_lo:[0,1] neg_hi:[0,1]
	v_cvt_pk_bf16_f32 v155, v196, v197
	global_store_dwordx4 v210, v[148:151], s[10:11] offset:256
	global_store_dwordx4 v210, v[152:155], s[6:7] offset:256
	v_add_f32_e32 v203, v198, v199
	s_nop 0
	v_add_u32_e32 v210, 0x50000, v213
	global_load_dwordx4 v[140:143], v210, s[38:39]
	global_load_dwordx4 v[144:147], v210, s[6:7]
	global_load_dwordx4 v[148:151], v210, s[38:39] offset:256
	global_load_dwordx4 v[152:155], v210, s[6:7] offset:256
	s_waitcnt vmcnt(18)
; __device__ __forceinline__ unsigned pk2(float lo, float hi) { f32x2_t v = {lo, hi}; bf16x2_t b = __builtin_convertvector(v, bf16x2_t); return __builtin_bit_cast(unsigned, b); }
; __device__ __forceinline__ float bflo(unsigned u) { return __uint_as_float(u << 16); }
; __device__ __forceinline__ float bfhi(unsigned u) { return __uint_as_float(u & 0xffff0000u); }
;     __device__ __forceinline__ void operator()(const f32x4 (&acc)[2][2][4][2], const Unit& u, int wr, int wc, int fr, int fq) const {
;     ...
;                     const size_t off = (size_t)row * DM + col0 + bj * HALF;
;                     const u32x4 hh = *(const u32x4*)(HI + off), ll = *(const u32x4*)(LO + off);
;                     float hv[8] = {bflo(hh.x) + bflo(ll.x), bfhi(hh.x) + bfhi(ll.x), bflo(hh.y) + bflo(ll.y), bfhi(hh.y) + bfhi(ll.y),
;                                    bflo(hh.z) + bflo(ll.z), bfhi(hh.z) + bfhi(ll.z), bflo(hh.w) + bflo(ll.w), bfhi(hh.w) + bfhi(ll.w)};
;                     float av[8] = {acc[ai][bj][m][0][0], acc[ai][bj][m][0][1], acc[ai][bj][m][0][2], acc[ai][bj][m][0][3], acc[ai][bj][m][1][0], acc[ai][bj][m][1][1], acc[ai][bj][m][1][2], acc[ai][bj][m][1][3]};
;                     if (GATED) { const u32x4 pp = *(const u32x4*)(PP + off);
;                         const float pv[8] = {bflo(pp.x), bfhi(pp.x), bflo(pp.y), bfhi(pp.y), bflo(pp.z), bfhi(pp.z), bflo(pp.w), bfhi(pp.w)};
; #pragma unroll
;                         for (int e = 0; e < 8; ++e) av[e] = fast_sigmoid(av[e] * rs) * pv[e]; }
;                     else {
; #pragma unroll
;                         for (int e = 0; e < 8; ++e) av[e] *= alpha; }
;                     float lo[8];
; #pragma unroll
;                     for (int e = 0; e < 8; ++e) { hv[e] += av[e]; sq += hv[e] * hv[e]; }
;                     u32x4 wh; wh.x = pk2(hv[0], hv[1]); wh.y = pk2(hv[2], hv[3]); wh.z = pk2(hv[4], hv[5]); wh.w = pk2(hv[6], hv[7]);
;                     lo[0] = hv[0] - bflo(wh.x); lo[1] = hv[1] - bfhi(wh.x); lo[2] = hv[2] - bflo(wh.y); lo[3] = hv[3] - bfhi(wh.y);
;                     lo[4] = hv[4] - bflo(wh.z); lo[5] = hv[5] - bfhi(wh.z); lo[6] = hv[6] - bflo(wh.w); lo[7] = hv[7] - bfhi(wh.w);
;                     u32x4 wl; wl.x = pk2(lo[0], lo[1]); wl.y = pk2(lo[2], lo[3]); wl.z = pk2(lo[4], lo[5]); wl.w = pk2(lo[6], lo[7]);
;                     *(u32x4*)(HO + off) = wh; *(u32x4*)(LO + off) = wl;
	v_lshlrev_b32_e32 v156, 16, v164
	v_and_b32_e32 v157, 0xffff0000, v164
	v_lshlrev_b32_e32 v158, 16, v168
	v_and_b32_e32 v159, 0xffff0000, v168
	v_pk_add_f32 v[156:157], v[156:157], v[158:159]
	v_pk_fma_f32 v[156:157], v[62:63], 0.5, v[156:157] op_sel_hi:[1,0,1]
	v_cvt_pk_bf16_f32 v164, v156, v157
	v_pk_mul_f32 v[198:199], v[156:157], v[156:157]
	v_lshlrev_b32_e32 v158, 16, v164
	v_and_b32_e32 v159, 0xffff0000, v164
	v_pk_add_f32 v[196:197], v[156:157], v[158:159] neg_lo:[0,1] neg_hi:[0,1]
	v_cvt_pk_bf16_f32 v168, v196, v197
	v_lshlrev_b32_e32 v156, 16, v165
	v_and_b32_e32 v157, 0xffff0000, v165
	v_lshlrev_b32_e32 v158, 16, v169
	v_and_b32_e32 v159, 0xffff0000, v169
	v_pk_add_f32 v[156:157], v[156:157], v[158:159]
	v_pk_fma_f32 v[156:157], v[64:65], 0.5, v[156:157] op_sel_hi:[1,0,1]
	v_cvt_pk_bf16_f32 v165, v156, v157
	v_pk_fma_f32 v[198:199], v[156:157], v[156:157], v[198:199]
	v_lshlrev_b32_e32 v158, 16, v165
	v_and_b32_e32 v159, 0xffff0000, v165
	v_pk_add_f32 v[196:197], v[156:157], v[158:159] neg_lo:[0,1] neg_hi:[0,1]
	v_cvt_pk_bf16_f32 v169, v196, v197
	v_lshlrev_b32_e32 v156, 16, v166
	v_and_b32_e32 v157, 0xffff0000, v166
	v_lshlrev_b32_e32 v158, 16, v170
	v_and_b32_e32 v159, 0xffff0000, v170
	v_pk_add_f32 v[156:157], v[156:157], v[158:159]
	v_pk_fma_f32 v[156:157], v[58:59], 0.5, v[156:157] op_sel_hi:[1,0,1]
	v_cvt_pk_bf16_f32 v166, v156, v157
	v_pk_fma_f32 v[198:199], v[156:157], v[156:157], v[198:199]
	v_lshlrev_b32_e32 v158, 16, v166
	v_and_b32_e32 v159, 0xffff0000, v166
	v_pk_add_f32 v[196:197], v[156:157], v[158:159] neg_lo:[0,1] neg_hi:[0,1]
	v_cvt_pk_bf16_f32 v170, v196, v197
	v_lshlrev_b32_e32 v156, 16, v167
	v_and_b32_e32 v157, 0xffff0000, v167
	v_lshlrev_b32_e32 v158, 16, v171
	v_and_b32_e32 v159, 0xffff0000, v171
	v_pk_add_f32 v[156:157], v[156:157], v[158:159]
	v_pk_fma_f32 v[156:157], v[60:61], 0.5, v[156:157] op_sel_hi:[1,0,1]
	v_cvt_pk_bf16_f32 v167, v156, v157
	v_pk_fma_f32 v[198:199], v[156:157], v[156:157], v[198:199]
	v_lshlrev_b32_e32 v158, 16, v167
	v_and_b32_e32 v159, 0xffff0000, v167
	v_pk_add_f32 v[196:197], v[156:157], v[158:159] neg_lo:[0,1] neg_hi:[0,1]
	v_cvt_pk_bf16_f32 v171, v196, v197
	global_store_dwordx4 v211, v[164:167], s[10:11]
	global_store_dwordx4 v211, v[168:171], s[6:7]
	s_waitcnt vmcnt(18)
	v_lshlrev_b32_e32 v156, 16, v172
	v_and_b32_e32 v157, 0xffff0000, v172
	v_lshlrev_b32_e32 v158, 16, v176
	v_and_b32_e32 v159, 0xffff0000, v176
	v_pk_add_f32 v[156:157], v[156:157], v[158:159]
	v_pk_fma_f32 v[156:157], v[54:55], 0.5, v[156:157] op_sel_hi:[1,0,1]
	v_cvt_pk_bf16_f32 v172, v156, v157
	v_pk_fma_f32 v[198:199], v[156:157], v[156:157], v[198:199]
	v_lshlrev_b32_e32 v158, 16, v172
	v_and_b32_e32 v159, 0xffff0000, v172
	v_pk_add_f32 v[196:197], v[156:157], v[158:159] neg_lo:[0,1] neg_hi:[0,1]
	v_cvt_pk_bf16_f32 v176, v196, v197
	v_lshlrev_b32_e32 v156, 16, v173
	v_and_b32_e32 v157, 0xffff0000, v173
	v_lshlrev_b32_e32 v158, 16, v177
	v_and_b32_e32 v159, 0xffff0000, v177
	v_pk_add_f32 v[156:157], v[156:157], v[158:159]
	v_pk_fma_f32 v[156:157], v[56:57], 0.5, v[156:157] op_sel_hi:[1,0,1]
	v_cvt_pk_bf16_f32 v173, v156, v157
	v_pk_fma_f32 v[198:199], v[156:157], v[156:157], v[198:199]
	v_lshlrev_b32_e32 v158, 16, v173
	v_and_b32_e32 v159, 0xffff0000, v173
	v_pk_add_f32 v[196:197], v[156:157], v[158:159] neg_lo:[0,1] neg_hi:[0,1]
	v_cvt_pk_bf16_f32 v177, v196, v197
	v_lshlrev_b32_e32 v156, 16, v174
	v_and_b32_e32 v157, 0xffff0000, v174
	v_lshlrev_b32_e32 v158, 16, v178
	v_and_b32_e32 v159, 0xffff0000, v178
	v_pk_add_f32 v[156:157], v[156:157], v[158:159]
	v_pk_fma_f32 v[156:157], v[50:51], 0.5, v[156:157] op_sel_hi:[1,0,1]
	v_cvt_pk_bf16_f32 v174, v156, v157
	v_pk_fma_f32 v[198:199], v[156:157], v[156:157], v[198:199]
	v_lshlrev_b32_e32 v158, 16, v174
	v_and_b32_e32 v159, 0xffff0000, v174
	v_pk_add_f32 v[196:197], v[156:157], v[158:159] neg_lo:[0,1] neg_hi:[0,1]
	v_cvt_pk_bf16_f32 v178, v196, v197
	v_lshlrev_b32_e32 v156, 16, v175
	v_and_b32_e32 v157, 0xffff0000, v175
	v_lshlrev_b32_e32 v158, 16, v179
	v_and_b32_e32 v159, 0xffff0000, v179
	v_pk_add_f32 v[156:157], v[156:157], v[158:159]
	v_pk_fma_f32 v[156:157], v[52:53], 0.5, v[156:157] op_sel_hi:[1,0,1]
	v_cvt_pk_bf16_f32 v175, v156, v157
	v_pk_fma_f32 v[198:199], v[156:157], v[156:157], v[198:199]
	v_lshlrev_b32_e32 v158, 16, v175
	v_and_b32_e32 v159, 0xffff0000, v175
	v_pk_add_f32 v[196:197], v[156:157], v[158:159] neg_lo:[0,1] neg_hi:[0,1]
	v_cvt_pk_bf16_f32 v179, v196, v197
	global_store_dwordx4 v211, v[172:175], s[10:11] offset:256
	global_store_dwordx4 v211, v[176:179], s[6:7] offset:256
	v_add_f32_e32 v206, v198, v199
	s_nop 0
	v_add_u32_e32 v211, 0x58000, v213
	global_load_dwordx4 v[164:167], v211, s[38:39]
	global_load_dwordx4 v[168:171], v211, s[6:7]
	global_load_dwordx4 v[172:175], v211, s[38:39] offset:256
	global_load_dwordx4 v[176:179], v211, s[6:7] offset:256
	s_waitcnt vmcnt(18)
; __device__ __forceinline__ unsigned pk2(float lo, float hi) { f32x2_t v = {lo, hi}; bf16x2_t b = __builtin_convertvector(v, bf16x2_t); return __builtin_bit_cast(unsigned, b); }
; __device__ __forceinline__ float bflo(unsigned u) { return __uint_as_float(u << 16); }
; __device__ __forceinline__ float bfhi(unsigned u) { return __uint_as_float(u & 0xffff0000u); }
;     __device__ __forceinline__ void operator()(const f32x4 (&acc)[2][2][4][2], const Unit& u, int wr, int wc, int fr, int fq) const {
;     ...
;                     const size_t off = (size_t)row * DM + col0 + bj * HALF;
;                     const u32x4 hh = *(const u32x4*)(HI + off), ll = *(const u32x4*)(LO + off);
;                     float hv[8] = {bflo(hh.x) + bflo(ll.x), bfhi(hh.x) + bfhi(ll.x), bflo(hh.y) + bflo(ll.y), bfhi(hh.y) + bfhi(ll.y),
;                                    bflo(hh.z) + bflo(ll.z), bfhi(hh.z) + bfhi(ll.z), bflo(hh.w) + bflo(ll.w), bfhi(hh.w) + bfhi(ll.w)};
;                     float av[8] = {acc[ai][bj][m][0][0], acc[ai][bj][m][0][1], acc[ai][bj][m][0][2], acc[ai][bj][m][0][3], acc[ai][bj][m][1][0], acc[ai][bj][m][1][1], acc[ai][bj][m][1][2], acc[ai][bj][m][1][3]};
;                     if (GATED) { const u32x4 pp = *(const u32x4*)(PP + off);
;                         const float pv[8] = {bflo(pp.x), bfhi(pp.x), bflo(pp.y), bfhi(pp.y), bflo(pp.z), bfhi(pp.z), bflo(pp.w), bfhi(pp.w)};
; #pragma unroll
;                         for (int e = 0; e < 8; ++e) av[e] = fast_sigmoid(av[e] * rs) * pv[e]; }
;                     else {
; #pragma unroll
;                         for (int e = 0; e < 8; ++e) av[e] *= alpha; }
;                     float lo[8];
; #pragma unroll
;                     for (int e = 0; e < 8; ++e) { hv[e] += av[e]; sq += hv[e] * hv[e]; }
;                     u32x4 wh; wh.x = pk2(hv[0], hv[1]); wh.y = pk2(hv[2], hv[3]); wh.z = pk2(hv[4], hv[5]); wh.w = pk2(hv[6], hv[7]);
;                     lo[0] = hv[0] - bflo(wh.x); lo[1] = hv[1] - bfhi(wh.x); lo[2] = hv[2] - bflo(wh.y); lo[3] = hv[3] - bfhi(wh.y);
;                     lo[4] = hv[4] - bflo(wh.z); lo[5] = hv[5] - bfhi(wh.z); lo[6] = hv[6] - bflo(wh.w); lo[7] = hv[7] - bfhi(wh.w);
;                     u32x4 wl; wl.x = pk2(lo[0], lo[1]); wl.y = pk2(lo[2], lo[3]); wl.z = pk2(lo[4], lo[5]); wl.w = pk2(lo[6], lo[7]);
;                     *(u32x4*)(HO + off) = wh; *(u32x4*)(LO + off) = wl;
	v_lshlrev_b32_e32 v156, 16, v180
	v_and_b32_e32 v157, 0xffff0000, v180
	v_lshlrev_b32_e32 v158, 16, v184
	v_and_b32_e32 v159, 0xffff0000, v184
	v_pk_add_f32 v[156:157], v[156:157], v[158:159]
	v_pk_fma_f32 v[156:157], v[46:47], 0.5, v[156:157] op_sel_hi:[1,0,1]
	v_cvt_pk_bf16_f32 v180, v156, v157
	v_pk_mul_f32 v[198:199], v[156:157], v[156:157]
	v_lshlrev_b32_e32 v158, 16, v180
	v_and_b32_e32 v159, 0xffff0000, v180
	v_pk_add_f32 v[196:197], v[156:157], v[158:159] neg_lo:[0,1] neg_hi:[0,1]
	v_cvt_pk_bf16_f32 v184, v196, v197
	v_lshlrev_b32_e32 v156, 16, v181
	v_and_b32_e32 v157, 0xffff0000, v181
	v_lshlrev_b32_e32 v158, 16, v185
	v_and_b32_e32 v159, 0xffff0000, v185
	v_pk_add_f32 v[156:157], v[156:157], v[158:159]
	v_pk_fma_f32 v[156:157], v[48:49], 0.5, v[156:157] op_sel_hi:[1,0,1]
	v_cvt_pk_bf16_f32 v181, v156, v157
	v_pk_fma_f32 v[198:199], v[156:157], v[156:157], v[198:199]
	v_lshlrev_b32_e32 v158, 16, v181
	v_and_b32_e32 v159, 0xffff0000, v181
	v_pk_add_f32 v[196:197], v[156:157], v[158:159] neg_lo:[0,1] neg_hi:[0,1]
	v_cvt_pk_bf16_f32 v185, v196, v197
	v_lshlrev_b32_e32 v156, 16, v182
	v_and_b32_e32 v157, 0xffff0000, v182
	v_lshlrev_b32_e32 v158, 16, v186
	v_and_b32_e32 v159, 0xffff0000, v186
	v_pk_add_f32 v[156:157], v[156:157], v[158:159]
	v_pk_fma_f32 v[156:157], v[42:43], 0.5, v[156:157] op_sel_hi:[1,0,1]
	v_cvt_pk_bf16_f32 v182, v156, v157
	v_pk_fma_f32 v[198:199], v[156:157], v[156:157], v[198:199]
	v_lshlrev_b32_e32 v158, 16, v182
	v_and_b32_e32 v159, 0xffff0000, v182
	v_pk_add_f32 v[196:197], v[156:157], v[158:159] neg_lo:[0,1] neg_hi:[0,1]
	v_cvt_pk_bf16_f32 v186, v196, v197
	v_lshlrev_b32_e32 v156, 16, v183
	v_and_b32_e32 v157, 0xffff0000, v183
	v_lshlrev_b32_e32 v158, 16, v187
	v_and_b32_e32 v159, 0xffff0000, v187
	v_pk_add_f32 v[156:157], v[156:157], v[158:159]
	v_pk_fma_f32 v[156:157], v[44:45], 0.5, v[156:157] op_sel_hi:[1,0,1]
	v_cvt_pk_bf16_f32 v183, v156, v157
	v_pk_fma_f32 v[198:199], v[156:157], v[156:157], v[198:199]
	v_lshlrev_b32_e32 v158, 16, v183
	v_and_b32_e32 v159, 0xffff0000, v183
	v_pk_add_f32 v[196:197], v[156:157], v[158:159] neg_lo:[0,1] neg_hi:[0,1]
	v_cvt_pk_bf16_f32 v187, v196, v197
	global_store_dwordx4 v212, v[180:183], s[10:11]
	global_store_dwordx4 v212, v[184:187], s[6:7]
	s_waitcnt vmcnt(18)
	v_lshlrev_b32_e32 v156, 16, v188
	v_and_b32_e32 v157, 0xffff0000, v188
	v_lshlrev_b32_e32 v158, 16, v192
	v_and_b32_e32 v159, 0xffff0000, v192
	v_pk_add_f32 v[156:157], v[156:157], v[158:159]
	v_pk_fma_f32 v[156:157], v[38:39], 0.5, v[156:157] op_sel_hi:[1,0,1]
	v_cvt_pk_bf16_f32 v188, v156, v157
	v_pk_fma_f32 v[198:199], v[156:157], v[156:157], v[198:199]
	v_lshlrev_b32_e32 v158, 16, v188
	v_and_b32_e32 v159, 0xffff0000, v188
	v_pk_add_f32 v[196:197], v[156:157], v[158:159] neg_lo:[0,1] neg_hi:[0,1]
	v_cvt_pk_bf16_f32 v192, v196, v197
	v_lshlrev_b32_e32 v156, 16, v189
	v_and_b32_e32 v157, 0xffff0000, v189
	v_lshlrev_b32_e32 v158, 16, v193
	v_and_b32_e32 v159, 0xffff0000, v193
	v_pk_add_f32 v[156:157], v[156:157], v[158:159]
	v_pk_fma_f32 v[156:157], v[40:41], 0.5, v[156:157] op_sel_hi:[1,0,1]
	v_cvt_pk_bf16_f32 v189, v156, v157
	v_pk_fma_f32 v[198:199], v[156:157], v[156:157], v[198:199]
	v_lshlrev_b32_e32 v158, 16, v189
	v_and_b32_e32 v159, 0xffff0000, v189
	v_pk_add_f32 v[196:197], v[156:157], v[158:159] neg_lo:[0,1] neg_hi:[0,1]
	v_cvt_pk_bf16_f32 v193, v196, v197
	v_lshlrev_b32_e32 v156, 16, v190
	v_and_b32_e32 v157, 0xffff0000, v190
	v_lshlrev_b32_e32 v158, 16, v194
	v_and_b32_e32 v159, 0xffff0000, v194
	v_pk_add_f32 v[156:157], v[156:157], v[158:159]
	v_pk_fma_f32 v[156:157], v[34:35], 0.5, v[156:157] op_sel_hi:[1,0,1]
	v_cvt_pk_bf16_f32 v190, v156, v157
	v_pk_fma_f32 v[198:199], v[156:157], v[156:157], v[198:199]
	v_lshlrev_b32_e32 v158, 16, v190
	v_and_b32_e32 v159, 0xffff0000, v190
	v_pk_add_f32 v[196:197], v[156:157], v[158:159] neg_lo:[0,1] neg_hi:[0,1]
	v_cvt_pk_bf16_f32 v194, v196, v197
	v_lshlrev_b32_e32 v156, 16, v191
	v_and_b32_e32 v157, 0xffff0000, v191
	v_lshlrev_b32_e32 v158, 16, v195
	v_and_b32_e32 v159, 0xffff0000, v195
	v_pk_add_f32 v[156:157], v[156:157], v[158:159]
	v_pk_fma_f32 v[156:157], v[36:37], 0.5, v[156:157] op_sel_hi:[1,0,1]
	v_cvt_pk_bf16_f32 v191, v156, v157
	v_pk_fma_f32 v[198:199], v[156:157], v[156:157], v[198:199]
	v_lshlrev_b32_e32 v158, 16, v191
	v_and_b32_e32 v159, 0xffff0000, v191
	v_pk_add_f32 v[196:197], v[156:157], v[158:159] neg_lo:[0,1] neg_hi:[0,1]
	v_cvt_pk_bf16_f32 v195, v196, v197
	global_store_dwordx4 v212, v[188:191], s[10:11] offset:256
	global_store_dwordx4 v212, v[192:195], s[6:7] offset:256
	v_add_f32_e32 v207, v198, v199
	s_waitcnt vmcnt(14)
; __device__ __forceinline__ unsigned pk2(float lo, float hi) { f32x2_t v = {lo, hi}; bf16x2_t b = __builtin_convertvector(v, bf16x2_t); return __builtin_bit_cast(unsigned, b); }
; __device__ __forceinline__ float bflo(unsigned u) { return __uint_as_float(u << 16); }
; __device__ __forceinline__ float bfhi(unsigned u) { return __uint_as_float(u & 0xffff0000u); }
;     __device__ __forceinline__ void operator()(const f32x4 (&acc)[2][2][4][2], const Unit& u, int wr, int wc, int fr, int fq) const {
;     ...
;                     const size_t off = (size_t)row * DM + col0 + bj * HALF;
;                     const u32x4 hh = *(const u32x4*)(HI + off), ll = *(const u32x4*)(LO + off);
;                     float hv[8] = {bflo(hh.x) + bflo(ll.x), bfhi(hh.x) + bfhi(ll.x), bflo(hh.y) + bflo(ll.y), bfhi(hh.y) + bfhi(ll.y),
;                                    bflo(hh.z) + bflo(ll.z), bfhi(hh.z) + bfhi(ll.z), bflo(hh.w) + bflo(ll.w), bfhi(hh.w) + bfhi(ll.w)};
;                     float av[8] = {acc[ai][bj][m][0][0], acc[ai][bj][m][0][1], acc[ai][bj][m][0][2], acc[ai][bj][m][0][3], acc[ai][bj][m][1][0], acc[ai][bj][m][1][1], acc[ai][bj][m][1][2], acc[ai][bj][m][1][3]};
;                     if (GATED) { const u32x4 pp = *(const u32x4*)(PP + off);
;                         const float pv[8] = {bflo(pp.x), bfhi(pp.x), bflo(pp.y), bfhi(pp.y), bflo(pp.z), bfhi(pp.z), bflo(pp.w), bfhi(pp.w)};
; #pragma unroll
;                         for (int e = 0; e < 8; ++e) av[e] = fast_sigmoid(av[e] * rs) * pv[e]; }
;                     else {
; #pragma unroll
;                         for (int e = 0; e < 8; ++e) av[e] *= alpha; }
;                     float lo[8];
; #pragma unroll
;                     for (int e = 0; e < 8; ++e) { hv[e] += av[e]; sq += hv[e] * hv[e]; }
;                     u32x4 wh; wh.x = pk2(hv[0], hv[1]); wh.y = pk2(hv[2], hv[3]); wh.z = pk2(hv[4], hv[5]); wh.w = pk2(hv[6], hv[7]);
;                     lo[0] = hv[0] - bflo(wh.x); lo[1] = hv[1] - bfhi(wh.x); lo[2] = hv[2] - bflo(wh.y); lo[3] = hv[3] - bfhi(wh.y);
;                     lo[4] = hv[4] - bflo(wh.z); lo[5] = hv[5] - bfhi(wh.z); lo[6] = hv[6] - bflo(wh.w); lo[7] = hv[7] - bfhi(wh.w);
;                     u32x4 wl; wl.x = pk2(lo[0], lo[1]); wl.y = pk2(lo[2], lo[3]); wl.z = pk2(lo[4], lo[5]); wl.w = pk2(lo[6], lo[7]);
;                     *(u32x4*)(HO + off) = wh; *(u32x4*)(LO + off) = wl;
	v_lshlrev_b32_e32 v156, 16, v140
	v_and_b32_e32 v157, 0xffff0000, v140
	v_lshlrev_b32_e32 v158, 16, v144
	v_and_b32_e32 v159, 0xffff0000, v144
	v_pk_add_f32 v[156:157], v[156:157], v[158:159]
	v_pk_fma_f32 v[156:157], v[30:31], 0.5, v[156:157] op_sel_hi:[1,0,1]
	v_cvt_pk_bf16_f32 v140, v156, v157
	v_pk_mul_f32 v[198:199], v[156:157], v[156:157]
	v_lshlrev_b32_e32 v158, 16, v140
	v_and_b32_e32 v159, 0xffff0000, v140
	v_pk_add_f32 v[196:197], v[156:157], v[158:159] neg_lo:[0,1] neg_hi:[0,1]
	v_cvt_pk_bf16_f32 v144, v196, v197
	v_lshlrev_b32_e32 v156, 16, v141
	v_and_b32_e32 v157, 0xffff0000, v141
	v_lshlrev_b32_e32 v158, 16, v145
	v_and_b32_e32 v159, 0xffff0000, v145
	v_pk_add_f32 v[156:157], v[156:157], v[158:159]
	v_pk_fma_f32 v[156:157], v[32:33], 0.5, v[156:157] op_sel_hi:[1,0,1]
	v_cvt_pk_bf16_f32 v141, v156, v157
	v_pk_fma_f32 v[198:199], v[156:157], v[156:157], v[198:199]
	v_lshlrev_b32_e32 v158, 16, v141
	v_and_b32_e32 v159, 0xffff0000, v141
	v_pk_add_f32 v[196:197], v[156:157], v[158:159] neg_lo:[0,1] neg_hi:[0,1]
	v_cvt_pk_bf16_f32 v145, v196, v197
	v_lshlrev_b32_e32 v156, 16, v142
	v_and_b32_e32 v157, 0xffff0000, v142
	v_lshlrev_b32_e32 v158, 16, v146
	v_and_b32_e32 v159, 0xffff0000, v146
	v_pk_add_f32 v[156:157], v[156:157], v[158:159]
	v_pk_fma_f32 v[156:157], v[26:27], 0.5, v[156:157] op_sel_hi:[1,0,1]
	v_cvt_pk_bf16_f32 v142, v156, v157
	v_pk_fma_f32 v[198:199], v[156:157], v[156:157], v[198:199]
	v_lshlrev_b32_e32 v158, 16, v142
	v_and_b32_e32 v159, 0xffff0000, v142
	v_pk_add_f32 v[196:197], v[156:157], v[158:159] neg_lo:[0,1] neg_hi:[0,1]
	v_cvt_pk_bf16_f32 v146, v196, v197
	v_lshlrev_b32_e32 v156, 16, v143
	v_and_b32_e32 v157, 0xffff0000, v143
	v_lshlrev_b32_e32 v158, 16, v147
	v_and_b32_e32 v159, 0xffff0000, v147
	v_pk_add_f32 v[156:157], v[156:157], v[158:159]
	v_pk_fma_f32 v[156:157], v[28:29], 0.5, v[156:157] op_sel_hi:[1,0,1]
	v_cvt_pk_bf16_f32 v143, v156, v157
	v_pk_fma_f32 v[198:199], v[156:157], v[156:157], v[198:199]
	v_lshlrev_b32_e32 v158, 16, v143
	v_and_b32_e32 v159, 0xffff0000, v143
	v_pk_add_f32 v[196:197], v[156:157], v[158:159] neg_lo:[0,1] neg_hi:[0,1]
	v_cvt_pk_bf16_f32 v147, v196, v197
	global_store_dwordx4 v210, v[140:143], s[10:11]
	global_store_dwordx4 v210, v[144:147], s[6:7]
	s_waitcnt vmcnt(14)
	v_lshlrev_b32_e32 v156, 16, v148
	v_and_b32_e32 v157, 0xffff0000, v148
	v_lshlrev_b32_e32 v158, 16, v152
	v_and_b32_e32 v159, 0xffff0000, v152
	v_pk_add_f32 v[156:157], v[156:157], v[158:159]
	v_pk_fma_f32 v[156:157], v[22:23], 0.5, v[156:157] op_sel_hi:[1,0,1]
	v_cvt_pk_bf16_f32 v148, v156, v157
	v_pk_fma_f32 v[198:199], v[156:157], v[156:157], v[198:199]
	v_lshlrev_b32_e32 v158, 16, v148
	v_and_b32_e32 v159, 0xffff0000, v148
	v_pk_add_f32 v[196:197], v[156:157], v[158:159] neg_lo:[0,1] neg_hi:[0,1]
	v_cvt_pk_bf16_f32 v152, v196, v197
	v_lshlrev_b32_e32 v156, 16, v149
	v_and_b32_e32 v157, 0xffff0000, v149
	v_lshlrev_b32_e32 v158, 16, v153
	v_and_b32_e32 v159, 0xffff0000, v153
	v_pk_add_f32 v[156:157], v[156:157], v[158:159]
	v_pk_fma_f32 v[156:157], v[24:25], 0.5, v[156:157] op_sel_hi:[1,0,1]
	v_cvt_pk_bf16_f32 v149, v156, v157
	v_pk_fma_f32 v[198:199], v[156:157], v[156:157], v[198:199]
	v_lshlrev_b32_e32 v158, 16, v149
	v_and_b32_e32 v159, 0xffff0000, v149
	v_pk_add_f32 v[196:197], v[156:157], v[158:159] neg_lo:[0,1] neg_hi:[0,1]
	v_cvt_pk_bf16_f32 v153, v196, v197
	v_lshlrev_b32_e32 v156, 16, v150
	v_and_b32_e32 v157, 0xffff0000, v150
	v_lshlrev_b32_e32 v158, 16, v154
	v_and_b32_e32 v159, 0xffff0000, v154
	v_pk_add_f32 v[156:157], v[156:157], v[158:159]
	v_pk_fma_f32 v[156:157], v[18:19], 0.5, v[156:157] op_sel_hi:[1,0,1]
	v_cvt_pk_bf16_f32 v150, v156, v157
	v_pk_fma_f32 v[198:199], v[156:157], v[156:157], v[198:199]
	v_lshlrev_b32_e32 v158, 16, v150
	v_and_b32_e32 v159, 0xffff0000, v150
	v_pk_add_f32 v[196:197], v[156:157], v[158:159] neg_lo:[0,1] neg_hi:[0,1]
	v_cvt_pk_bf16_f32 v154, v196, v197
	v_lshlrev_b32_e32 v156, 16, v151
	v_and_b32_e32 v157, 0xffff0000, v151
	v_lshlrev_b32_e32 v158, 16, v155
	v_and_b32_e32 v159, 0xffff0000, v155
	v_pk_add_f32 v[156:157], v[156:157], v[158:159]
	v_pk_fma_f32 v[156:157], v[20:21], 0.5, v[156:157] op_sel_hi:[1,0,1]
	v_cvt_pk_bf16_f32 v151, v156, v157
	v_pk_fma_f32 v[198:199], v[156:157], v[156:157], v[198:199]
	v_lshlrev_b32_e32 v158, 16, v151
	v_and_b32_e32 v159, 0xffff0000, v151
	v_pk_add_f32 v[196:197], v[156:157], v[158:159] neg_lo:[0,1] neg_hi:[0,1]
	v_cvt_pk_bf16_f32 v155, v196, v197
	global_store_dwordx4 v210, v[148:151], s[10:11] offset:256
	global_store_dwordx4 v210, v[152:155], s[6:7] offset:256
	v_add_f32_e32 v208, v198, v199
	s_waitcnt vmcnt(10)
; __device__ __forceinline__ unsigned pk2(float lo, float hi) { f32x2_t v = {lo, hi}; bf16x2_t b = __builtin_convertvector(v, bf16x2_t); return __builtin_bit_cast(unsigned, b); }
;     __device__ __forceinline__ void operator()(const f32x4 (&acc)[2][2][4][2], const Unit& u, int wr, int wc, int fr, int fq) const {
;     ...
;                     const size_t off = (size_t)row * DM + col0 + bj * HALF;
;                     const u32x4 hh = *(const u32x4*)(HI + off), ll = *(const u32x4*)(LO + off);
;                     float hv[8] = {bflo(hh.x) + bflo(ll.x), bfhi(hh.x) + bfhi(ll.x), bflo(hh.y) + bflo(ll.y), bfhi(hh.y) + bfhi(ll.y),
;                                    bflo(hh.z) + bflo(ll.z), bfhi(hh.z) + bfhi(ll.z), bflo(hh.w) + bflo(ll.w), bfhi(hh.w) + bfhi(ll.w)};
;                     float av[8] = {acc[ai][bj][m][0][0], acc[ai][bj][m][0][1], acc[ai][bj][m][0][2], acc[ai][bj][m][0][3], acc[ai][bj][m][1][0], acc[ai][bj][m][1][1], acc[ai][bj][m][1][2], acc[ai][bj][m][1][3]};
;                     if (GATED) { const u32x4 pp = *(const u32x4*)(PP + off);
;                         const float pv[8] = {bflo(pp.x), bfhi(pp.x), bflo(pp.y), bfhi(pp.y), bflo(pp.z), bfhi(pp.z), bflo(pp.w), bfhi(pp.w)};
; #pragma unroll
;                         for (int e = 0; e < 8; ++e) av[e] = fast_sigmoid(av[e] * rs) * pv[e]; }
;                     else {
; #pragma unroll
;                         for (int e = 0; e < 8; ++e) av[e] *= alpha; }
;                     float lo[8];
; #pragma unroll
;                     for (int e = 0; e < 8; ++e) { hv[e] += av[e]; sq += hv[e] * hv[e]; }
;                     u32x4 wh; wh.x = pk2(hv[0], hv[1]); wh.y = pk2(hv[2], hv[3]); wh.z = pk2(hv[4], hv[5]); wh.w = pk2(hv[6], hv[7]);
;                     lo[0] = hv[0] - bflo(wh.x); lo[1] = hv[1] - bfhi(wh.x); lo[2] = hv[2] - bflo(wh.y); lo[3] = hv[3] - bfhi(wh.y);
;                     lo[4] = hv[4] - bflo(wh.z); lo[5] = hv[5] - bfhi(wh.z); lo[6] = hv[6] - bflo(wh.w); lo[7] = hv[7] - bfhi(wh.w);
;                     u32x4 wl; wl.x = pk2(lo[0], lo[1]); wl.y = pk2(lo[2], lo[3]); wl.z = pk2(lo[4], lo[5]); wl.w = pk2(lo[6], lo[7]);
;                     *(u32x4*)(HO + off) = wh; *(u32x4*)(LO + off) = wl;
;                 }
;                 sq += __shfl_xor(sq, 16); sq += __shfl_xor(sq, 32);
;                 if (fq == 0) ssq_out[(size_t)row * 16 + 4 * u.pn + wc] = sq;
	v_lshlrev_b32_e32 v156, 16, v164
	v_and_b32_e32 v157, 0xffff0000, v164
	v_lshlrev_b32_e32 v158, 16, v168
	v_and_b32_e32 v159, 0xffff0000, v168
	v_pk_add_f32 v[156:157], v[156:157], v[158:159]
	v_pk_fma_f32 v[156:157], v[14:15], 0.5, v[156:157] op_sel_hi:[1,0,1]
	v_cvt_pk_bf16_f32 v164, v156, v157
	v_pk_mul_f32 v[198:199], v[156:157], v[156:157]
	v_lshlrev_b32_e32 v158, 16, v164
	v_and_b32_e32 v159, 0xffff0000, v164
	v_pk_add_f32 v[196:197], v[156:157], v[158:159] neg_lo:[0,1] neg_hi:[0,1]
	v_cvt_pk_bf16_f32 v168, v196, v197
	v_lshlrev_b32_e32 v156, 16, v165
	v_and_b32_e32 v157, 0xffff0000, v165
	v_lshlrev_b32_e32 v158, 16, v169
	v_and_b32_e32 v159, 0xffff0000, v169
	v_pk_add_f32 v[156:157], v[156:157], v[158:159]
	v_pk_fma_f32 v[156:157], v[16:17], 0.5, v[156:157] op_sel_hi:[1,0,1]
	v_cvt_pk_bf16_f32 v165, v156, v157
	v_pk_fma_f32 v[198:199], v[156:157], v[156:157], v[198:199]
	v_lshlrev_b32_e32 v158, 16, v165
	v_and_b32_e32 v159, 0xffff0000, v165
	v_pk_add_f32 v[196:197], v[156:157], v[158:159] neg_lo:[0,1] neg_hi:[0,1]
	v_cvt_pk_bf16_f32 v169, v196, v197
	v_lshlrev_b32_e32 v156, 16, v166
	v_and_b32_e32 v157, 0xffff0000, v166
	v_lshlrev_b32_e32 v158, 16, v170
	v_and_b32_e32 v159, 0xffff0000, v170
	v_pk_add_f32 v[156:157], v[156:157], v[158:159]
	v_pk_fma_f32 v[156:157], v[10:11], 0.5, v[156:157] op_sel_hi:[1,0,1]
	v_cvt_pk_bf16_f32 v166, v156, v157
	v_pk_fma_f32 v[198:199], v[156:157], v[156:157], v[198:199]
	v_lshlrev_b32_e32 v158, 16, v166
	v_and_b32_e32 v159, 0xffff0000, v166
	v_pk_add_f32 v[196:197], v[156:157], v[158:159] neg_lo:[0,1] neg_hi:[0,1]
	v_cvt_pk_bf16_f32 v170, v196, v197
	v_lshlrev_b32_e32 v156, 16, v167
	v_and_b32_e32 v157, 0xffff0000, v167
	v_lshlrev_b32_e32 v158, 16, v171
	v_and_b32_e32 v159, 0xffff0000, v171
	v_pk_add_f32 v[156:157], v[156:157], v[158:159]
	v_pk_fma_f32 v[156:157], v[12:13], 0.5, v[156:157] op_sel_hi:[1,0,1]
	v_cvt_pk_bf16_f32 v167, v156, v157
	v_pk_fma_f32 v[198:199], v[156:157], v[156:157], v[198:199]
	v_lshlrev_b32_e32 v158, 16, v167
	v_and_b32_e32 v159, 0xffff0000, v167
	v_pk_add_f32 v[196:197], v[156:157], v[158:159] neg_lo:[0,1] neg_hi:[0,1]
	v_cvt_pk_bf16_f32 v171, v196, v197
	global_store_dwordx4 v211, v[164:167], s[10:11]
	global_store_dwordx4 v211, v[168:171], s[6:7]
	s_waitcnt vmcnt(10)
	v_lshlrev_b32_e32 v156, 16, v172
	v_and_b32_e32 v157, 0xffff0000, v172
	v_lshlrev_b32_e32 v158, 16, v176
	v_and_b32_e32 v159, 0xffff0000, v176
	v_pk_add_f32 v[156:157], v[156:157], v[158:159]
	v_pk_fma_f32 v[156:157], v[6:7], 0.5, v[156:157] op_sel_hi:[1,0,1]
	v_cvt_pk_bf16_f32 v172, v156, v157
	v_pk_fma_f32 v[198:199], v[156:157], v[156:157], v[198:199]
	v_lshlrev_b32_e32 v158, 16, v172
	v_and_b32_e32 v159, 0xffff0000, v172
	v_pk_add_f32 v[196:197], v[156:157], v[158:159] neg_lo:[0,1] neg_hi:[0,1]
	v_cvt_pk_bf16_f32 v176, v196, v197
	v_lshlrev_b32_e32 v156, 16, v173
	v_and_b32_e32 v157, 0xffff0000, v173
	v_lshlrev_b32_e32 v158, 16, v177
	v_and_b32_e32 v159, 0xffff0000, v177
	v_pk_add_f32 v[156:157], v[156:157], v[158:159]
	v_pk_fma_f32 v[156:157], v[8:9], 0.5, v[156:157] op_sel_hi:[1,0,1]
	v_cvt_pk_bf16_f32 v173, v156, v157
	v_pk_fma_f32 v[198:199], v[156:157], v[156:157], v[198:199]
	v_lshlrev_b32_e32 v158, 16, v173
	v_and_b32_e32 v159, 0xffff0000, v173
	v_pk_add_f32 v[196:197], v[156:157], v[158:159] neg_lo:[0,1] neg_hi:[0,1]
	v_cvt_pk_bf16_f32 v177, v196, v197
	v_lshlrev_b32_e32 v156, 16, v174
	v_and_b32_e32 v157, 0xffff0000, v174
	v_lshlrev_b32_e32 v158, 16, v178
	v_and_b32_e32 v159, 0xffff0000, v178
	v_pk_add_f32 v[156:157], v[156:157], v[158:159]
	v_pk_fma_f32 v[156:157], v[2:3], 0.5, v[156:157] op_sel_hi:[1,0,1]
	v_cvt_pk_bf16_f32 v174, v156, v157
	v_pk_fma_f32 v[198:199], v[156:157], v[156:157], v[198:199]
	v_lshlrev_b32_e32 v158, 16, v174
	v_and_b32_e32 v159, 0xffff0000, v174
	v_pk_add_f32 v[196:197], v[156:157], v[158:159] neg_lo:[0,1] neg_hi:[0,1]
	v_cvt_pk_bf16_f32 v178, v196, v197
	v_lshlrev_b32_e32 v156, 16, v175
	v_and_b32_e32 v157, 0xffff0000, v175
	v_lshlrev_b32_e32 v158, 16, v179
	v_and_b32_e32 v159, 0xffff0000, v179
	v_pk_add_f32 v[156:157], v[156:157], v[158:159]
	v_pk_fma_f32 v[156:157], v[4:5], 0.5, v[156:157] op_sel_hi:[1,0,1]
	v_cvt_pk_bf16_f32 v175, v156, v157
	v_pk_fma_f32 v[198:199], v[156:157], v[156:157], v[198:199]
	v_lshlrev_b32_e32 v158, 16, v175
	v_and_b32_e32 v159, 0xffff0000, v175
	v_pk_add_f32 v[196:197], v[156:157], v[158:159] neg_lo:[0,1] neg_hi:[0,1]
	v_cvt_pk_bf16_f32 v179, v196, v197
	global_store_dwordx4 v211, v[172:175], s[10:11] offset:256
	global_store_dwordx4 v211, v[176:179], s[6:7] offset:256
	v_add_f32_e32 v209, v198, v199
	ds_bpermute_b32 v140, v214, v200
	ds_bpermute_b32 v141, v214, v201
	ds_bpermute_b32 v142, v214, v202
	ds_bpermute_b32 v143, v214, v203
	ds_bpermute_b32 v144, v214, v206
	ds_bpermute_b32 v145, v214, v207
	ds_bpermute_b32 v146, v214, v208
	ds_bpermute_b32 v147, v214, v209
	v_readlane_b32 s52, v250, 35
	v_readlane_b32 s53, v250, 36
	s_waitcnt lgkmcnt(0)
	v_add_f32_e32 v200, v200, v140
	v_add_f32_e32 v201, v201, v141
	v_add_f32_e32 v202, v202, v142
	v_add_f32_e32 v203, v203, v143
	v_add_f32_e32 v206, v206, v144
	v_add_f32_e32 v207, v207, v145
	v_add_f32_e32 v208, v208, v146
	v_add_f32_e32 v209, v209, v147
	ds_bpermute_b32 v140, v215, v200
	ds_bpermute_b32 v141, v215, v201
	ds_bpermute_b32 v142, v215, v202
	ds_bpermute_b32 v143, v215, v203
	ds_bpermute_b32 v144, v215, v206
	ds_bpermute_b32 v145, v215, v207
	ds_bpermute_b32 v146, v215, v208
	ds_bpermute_b32 v147, v215, v209
	s_waitcnt lgkmcnt(0)
	v_add_f32_e32 v200, v200, v140
	v_add_f32_e32 v201, v201, v141
	v_add_f32_e32 v202, v202, v142
	v_add_f32_e32 v203, v203, v143
	v_add_f32_e32 v206, v206, v144
	v_add_f32_e32 v207, v207, v145
	v_add_f32_e32 v208, v208, v146
	v_add_f32_e32 v209, v209, v147
	s_and_saveexec_b64 s[12:13], s[44:45]
	s_cbranch_execz .Lepir_f1d_skip
	global_store_dword v216, v200, s[52:53]
	global_store_dword v216, v201, s[52:53] offset:1024
	global_store_dword v216, v202, s[52:53] offset:2048
	global_store_dword v216, v203, s[52:53] offset:3072
	global_store_dword v217, v206, s[52:53]
	global_store_dword v217, v207, s[52:53] offset:1024
	global_store_dword v217, v208, s[52:53] offset:2048
	global_store_dword v217, v209, s[52:53] offset:3072

; __device__ __forceinline__ float bflo(unsigned u) { return __uint_as_float(u << 16); }
;     __device__ __forceinline__ void operator()(const f32x4 (&acc)[2][2][4][2], const Unit& u, int wr, int wc, int fr, int fq) const {
;         const int row0 = u.pm * BM + wr * 64 + fr, col0 = u.pn * BM + wc * 32 + 8 * fq;
; #pragma unroll
;         for (int ai = 0; ai < 2; ++ai)
; #pragma unroll
;             for (int m = 0; m < 4; ++m) {
;                 const int row = row0 + ai * HALF + m * 16;
;                 float rs = 0.f; if (GATED) rs = rsqrtf(row_ssq(ssq_in, 16, 4, row, fq) * (1.f / 1024.f) + EPS);
;                 float sq = 0.f;
; #pragma unroll
;                 for (int bj = 0; bj < 2; ++bj) {
;                     const size_t off = (size_t)row * DM + col0 + bj * HALF;
;                     const u32x4 hh = *(const u32x4*)(HI + off), ll = *(const u32x4*)(LO + off);
;                     float hv[8] = {bflo(hh.x) + bflo(ll.x), bfhi(hh.x) + bfhi(ll.x), bflo(hh.y) + bflo(ll.y), bfhi(hh.y) + bfhi(ll.y),
;                                    bflo(hh.z) + bflo(ll.z), bfhi(hh.z) + bfhi(ll.z), bflo(hh.w) + bflo(ll.w), bfhi(hh.w) + bfhi(ll.w)};
;                     float av[8] = {acc[ai][bj][m][0][0], acc[ai][bj][m][0][1], acc[ai][bj][m][0][2], acc[ai][bj][m][0][3], acc[ai][bj][m][1][0], acc[ai][bj][m][1][1], acc[ai][bj][m][1][2], acc[ai][bj][m][1][3]};
;                     if (GATED) { const u32x4 pp = *(const u32x4*)(PP + off);
;                         const float pv[8] = {bflo(pp.x), bfhi(pp.x), bflo(pp.y), bfhi(pp.y), bflo(pp.z), bfhi(pp.z), bflo(pp.w), bfhi(pp.w)};
; #pragma unroll
;                         for (int e = 0; e < 8; ++e) av[e] = fast_sigmoid(av[e] * rs) * pv[e]; }
;                     else {
; #pragma unroll
;                         for (int e = 0; e < 8; ++e) av[e] *= alpha; }
;                     float lo[8];
; #pragma unroll
;                     for (int e = 0; e < 8; ++e) { hv[e] += av[e]; sq += hv[e] * hv[e]; }
;                     u32x4 wh; wh.x = pk2(hv[0], hv[1]); wh.y = pk2(hv[2], hv[3]); wh.z = pk2(hv[4], hv[5]); wh.w = pk2(hv[6], hv[7]);
;                     lo[0] = hv[0] - bflo(wh.x); lo[1] = hv[1] - bfhi(wh.x); lo[2] = hv[2] - bflo(wh.y); lo[3] = hv[3] - bfhi(wh.y);
;                     lo[4] = hv[4] - bflo(wh.z); lo[5] = hv[5] - bfhi(wh.z); lo[6] = hv[6] - bflo(wh.w); lo[7] = hv[7] - bfhi(wh.w);
.LBB0_1071:
	v_and_b32_e32 v158, 64, v241
	v_xor_b32_e32 v214, 16, v241
	v_add_u32_e32 v158, 64, v158
	v_cmp_lt_i32_e32 vcc, v214, v158
	v_lshl_add_u32 v156, s40, 8, v160
	v_lshl_or_b32 v157, s4, 8, v162
	v_cndmask_b32_e32 v214, v241, v214, vcc
	v_lshlrev_b32_e32 v214, 2, v214
	v_xor_b32_e32 v215, 32, v241
	v_cmp_lt_i32_e32 vcc, v215, v158
	v_readlane_b32 s10, v254, 18
	v_readlane_b32 s11, v254, 19
	s_nop 1
	v_cndmask_b32_e32 v215, v241, v215, vcc
	v_lshlrev_b32_e32 v215, 2, v215
	v_lshl_add_u32 v213, v156, 10, v157
	v_lshlrev_b32_e32 v213, 1, v213
	s_lshl_b32 s40, s4, 4
	s_lshl_b32 s0, s48, 2
	s_add_i32 s40, s40, s0
	v_lshlrev_b32_e32 v216, 6, v156
	v_add_u32_e32 v216, s40, v216
	v_add_u32_e32 v217, 0x2000, v216
	v_readlane_b32 s30, v251, 4
	v_readlane_b32 s31, v251, 5
	s_nop 1
	v_mov_b32_e32 v210, v213
	global_load_dwordx4 v[140:143], v210, s[10:11]
	global_load_dwordx4 v[144:147], v210, s[14:15]
	global_load_dwordx4 v[148:151], v210, s[10:11] offset:256
	global_load_dwordx4 v[152:155], v210, s[14:15] offset:256
	v_add_u32_e32 v211, 0x8000, v213
	global_load_dwordx4 v[164:167], v211, s[10:11]
	global_load_dwordx4 v[168:171], v211, s[14:15]
	global_load_dwordx4 v[172:175], v211, s[10:11] offset:256
	global_load_dwordx4 v[176:179], v211, s[14:15] offset:256
	v_add_u32_e32 v212, 0x10000, v213
	global_load_dwordx4 v[180:183], v212, s[10:11]
	global_load_dwordx4 v[184:187], v212, s[14:15]
	global_load_dwordx4 v[188:191], v212, s[10:11] offset:256
	global_load_dwordx4 v[192:195], v212, s[14:15] offset:256
	s_waitcnt vmcnt(10)
	v_lshlrev_b32_e32 v156, 16, v140
	v_and_b32_e32 v157, 0xffff0000, v140
	v_lshlrev_b32_e32 v158, 16, v144
	v_and_b32_e32 v159, 0xffff0000, v144
	v_pk_add_f32 v[156:157], v[156:157], v[158:159]
	v_pk_add_f32 v[156:157], v[126:127], v[156:157]
	v_cvt_pk_bf16_f32 v140, v156, v157
	v_pk_mul_f32 v[198:199], v[156:157], v[156:157]
	v_lshlrev_b32_e32 v158, 16, v140
	v_and_b32_e32 v159, 0xffff0000, v140
	v_pk_add_f32 v[196:197], v[156:157], v[158:159] neg_lo:[0,1] neg_hi:[0,1]
	v_cvt_pk_bf16_f32 v144, v196, v197
	v_lshlrev_b32_e32 v156, 16, v141
	v_and_b32_e32 v157, 0xffff0000, v141
	v_lshlrev_b32_e32 v158, 16, v145
	v_and_b32_e32 v159, 0xffff0000, v145
	v_pk_add_f32 v[156:157], v[156:157], v[158:159]
	v_pk_add_f32 v[156:157], v[128:129], v[156:157]
	v_cvt_pk_bf16_f32 v141, v156, v157
	v_pk_fma_f32 v[198:199], v[156:157], v[156:157], v[198:199]
	v_lshlrev_b32_e32 v158, 16, v141
	v_and_b32_e32 v159, 0xffff0000, v141
	v_pk_add_f32 v[196:197], v[156:157], v[158:159] neg_lo:[0,1] neg_hi:[0,1]
	v_cvt_pk_bf16_f32 v145, v196, v197
	v_lshlrev_b32_e32 v156, 16, v142
	v_and_b32_e32 v157, 0xffff0000, v142
	v_lshlrev_b32_e32 v158, 16, v146
	v_and_b32_e32 v159, 0xffff0000, v146
	v_pk_add_f32 v[156:157], v[156:157], v[158:159]
	v_pk_add_f32 v[156:157], v[122:123], v[156:157]
	v_cvt_pk_bf16_f32 v142, v156, v157
	v_pk_fma_f32 v[198:199], v[156:157], v[156:157], v[198:199]
	v_lshlrev_b32_e32 v158, 16, v142
	v_and_b32_e32 v159, 0xffff0000, v142
	v_pk_add_f32 v[196:197], v[156:157], v[158:159] neg_lo:[0,1] neg_hi:[0,1]
	v_cvt_pk_bf16_f32 v146, v196, v197
	v_lshlrev_b32_e32 v156, 16, v143
	v_and_b32_e32 v157, 0xffff0000, v143
	v_lshlrev_b32_e32 v158, 16, v147
	v_and_b32_e32 v159, 0xffff0000, v147
	v_pk_add_f32 v[156:157], v[156:157], v[158:159]
	v_pk_add_f32 v[156:157], v[124:125], v[156:157]
	v_cvt_pk_bf16_f32 v143, v156, v157
	v_pk_fma_f32 v[198:199], v[156:157], v[156:157], v[198:199]
	v_lshlrev_b32_e32 v158, 16, v143
	v_and_b32_e32 v159, 0xffff0000, v143
	v_pk_add_f32 v[196:197], v[156:157], v[158:159] neg_lo:[0,1] neg_hi:[0,1]
	v_cvt_pk_bf16_f32 v147, v196, v197
	global_store_dwordx4 v210, v[140:143], s[10:11]
	global_store_dwordx4 v210, v[144:147], s[14:15]
	s_waitcnt vmcnt(10)
	v_lshlrev_b32_e32 v156, 16, v148
	v_and_b32_e32 v157, 0xffff0000, v148
	v_lshlrev_b32_e32 v158, 16, v152
	v_and_b32_e32 v159, 0xffff0000, v152
	v_pk_add_f32 v[156:157], v[156:157], v[158:159]
	v_pk_add_f32 v[156:157], v[118:119], v[156:157]
	v_cvt_pk_bf16_f32 v148, v156, v157
	v_pk_fma_f32 v[198:199], v[156:157], v[156:157], v[198:199]
	v_lshlrev_b32_e32 v158, 16, v148
	v_and_b32_e32 v159, 0xffff0000, v148
	v_pk_add_f32 v[196:197], v[156:157], v[158:159] neg_lo:[0,1] neg_hi:[0,1]
	v_cvt_pk_bf16_f32 v152, v196, v197
	v_lshlrev_b32_e32 v156, 16, v149
	v_and_b32_e32 v157, 0xffff0000, v149
	v_lshlrev_b32_e32 v158, 16, v153
	v_and_b32_e32 v159, 0xffff0000, v153
	v_pk_add_f32 v[156:157], v[156:157], v[158:159]
	v_pk_add_f32 v[156:157], v[120:121], v[156:157]
	v_cvt_pk_bf16_f32 v149, v156, v157
	v_pk_fma_f32 v[198:199], v[156:157], v[156:157], v[198:199]
	v_lshlrev_b32_e32 v158, 16, v149
	v_and_b32_e32 v159, 0xffff0000, v149
	v_pk_add_f32 v[196:197], v[156:157], v[158:159] neg_lo:[0,1] neg_hi:[0,1]
	v_cvt_pk_bf16_f32 v153, v196, v197
	v_lshlrev_b32_e32 v156, 16, v150
	v_and_b32_e32 v157, 0xffff0000, v150
	v_lshlrev_b32_e32 v158, 16, v154
	v_and_b32_e32 v159, 0xffff0000, v154
	v_pk_add_f32 v[156:157], v[156:157], v[158:159]
	v_pk_add_f32 v[156:157], v[114:115], v[156:157]
	v_cvt_pk_bf16_f32 v150, v156, v157
	v_pk_fma_f32 v[198:199], v[156:157], v[156:157], v[198:199]
	v_lshlrev_b32_e32 v158, 16, v150
	v_and_b32_e32 v159, 0xffff0000, v150
	v_pk_add_f32 v[196:197], v[156:157], v[158:159] neg_lo:[0,1] neg_hi:[0,1]
	v_cvt_pk_bf16_f32 v154, v196, v197
	v_lshlrev_b32_e32 v156, 16, v151
	v_and_b32_e32 v157, 0xffff0000, v151
	v_lshlrev_b32_e32 v158, 16, v155
	v_and_b32_e32 v159, 0xffff0000, v155
	v_pk_add_f32 v[156:157], v[156:157], v[158:159]
	v_pk_add_f32 v[156:157], v[116:117], v[156:157]
	v_cvt_pk_bf16_f32 v151, v156, v157
	v_pk_fma_f32 v[198:199], v[156:157], v[156:157], v[198:199]
	v_lshlrev_b32_e32 v158, 16, v151
	v_and_b32_e32 v159, 0xffff0000, v151
	v_pk_add_f32 v[196:197], v[156:157], v[158:159] neg_lo:[0,1] neg_hi:[0,1]
	v_cvt_pk_bf16_f32 v155, v196, v197
	global_store_dwordx4 v210, v[148:151], s[10:11] offset:256
	global_store_dwordx4 v210, v[152:155], s[14:15] offset:256
	v_add_f32_e32 v200, v198, v199
	s_nop 0
	v_add_u32_e32 v210, 0x18000, v213
	global_load_dwordx4 v[140:143], v210, s[10:11]
	global_load_dwordx4 v[144:147], v210, s[14:15]
	global_load_dwordx4 v[148:151], v210, s[10:11] offset:256
	global_load_dwordx4 v[152:155], v210, s[14:15] offset:256
	s_waitcnt vmcnt(14)
; __device__ __forceinline__ unsigned pk2(float lo, float hi) { f32x2_t v = {lo, hi}; bf16x2_t b = __builtin_convertvector(v, bf16x2_t); return __builtin_bit_cast(unsigned, b); }
; __device__ __forceinline__ float bflo(unsigned u) { return __uint_as_float(u << 16); }
; __device__ __forceinline__ float bfhi(unsigned u) { return __uint_as_float(u & 0xffff0000u); }
;     __device__ __forceinline__ void operator()(const f32x4 (&acc)[2][2][4][2], const Unit& u, int wr, int wc, int fr, int fq) const {
;     ...
;                     const size_t off = (size_t)row * DM + col0 + bj * HALF;
;                     const u32x4 hh = *(const u32x4*)(HI + off), ll = *(const u32x4*)(LO + off);
;                     float hv[8] = {bflo(hh.x) + bflo(ll.x), bfhi(hh.x) + bfhi(ll.x), bflo(hh.y) + bflo(ll.y), bfhi(hh.y) + bfhi(ll.y),
;                                    bflo(hh.z) + bflo(ll.z), bfhi(hh.z) + bfhi(ll.z), bflo(hh.w) + bflo(ll.w), bfhi(hh.w) + bfhi(ll.w)};
;                     float av[8] = {acc[ai][bj][m][0][0], acc[ai][bj][m][0][1], acc[ai][bj][m][0][2], acc[ai][bj][m][0][3], acc[ai][bj][m][1][0], acc[ai][bj][m][1][1], acc[ai][bj][m][1][2], acc[ai][bj][m][1][3]};
;                     if (GATED) { const u32x4 pp = *(const u32x4*)(PP + off);
;                         const float pv[8] = {bflo(pp.x), bfhi(pp.x), bflo(pp.y), bfhi(pp.y), bflo(pp.z), bfhi(pp.z), bflo(pp.w), bfhi(pp.w)};
; #pragma unroll
;                         for (int e = 0; e < 8; ++e) av[e] = fast_sigmoid(av[e] * rs) * pv[e]; }
;                     else {
; #pragma unroll
;                         for (int e = 0; e < 8; ++e) av[e] *= alpha; }
;                     float lo[8];
; #pragma unroll
;                     for (int e = 0; e < 8; ++e) { hv[e] += av[e]; sq += hv[e] * hv[e]; }
;                     u32x4 wh; wh.x = pk2(hv[0], hv[1]); wh.y = pk2(hv[2], hv[3]); wh.z = pk2(hv[4], hv[5]); wh.w = pk2(hv[6], hv[7]);
;                     lo[0] = hv[0] - bflo(wh.x); lo[1] = hv[1] - bfhi(wh.x); lo[2] = hv[2] - bflo(wh.y); lo[3] = hv[3] - bfhi(wh.y);
;                     lo[4] = hv[4] - bflo(wh.z); lo[5] = hv[5] - bfhi(wh.z); lo[6] = hv[6] - bflo(wh.w); lo[7] = hv[7] - bfhi(wh.w);
;                     u32x4 wl; wl.x = pk2(lo[0], lo[1]); wl.y = pk2(lo[2], lo[3]); wl.z = pk2(lo[4], lo[5]); wl.w = pk2(lo[6], lo[7]);
;                     *(u32x4*)(HO + off) = wh; *(u32x4*)(LO + off) = wl;
	v_lshlrev_b32_e32 v156, 16, v164
	v_and_b32_e32 v157, 0xffff0000, v164
	v_lshlrev_b32_e32 v158, 16, v168
	v_and_b32_e32 v159, 0xffff0000, v168
	v_pk_add_f32 v[156:157], v[156:157], v[158:159]
	v_pk_add_f32 v[156:157], v[110:111], v[156:157]
	v_cvt_pk_bf16_f32 v164, v156, v157
	v_pk_mul_f32 v[198:199], v[156:157], v[156:157]
	v_lshlrev_b32_e32 v158, 16, v164
	v_and_b32_e32 v159, 0xffff0000, v164
	v_pk_add_f32 v[196:197], v[156:157], v[158:159] neg_lo:[0,1] neg_hi:[0,1]
	v_cvt_pk_bf16_f32 v168, v196, v197
	v_lshlrev_b32_e32 v156, 16, v165
	v_and_b32_e32 v157, 0xffff0000, v165
	v_lshlrev_b32_e32 v158, 16, v169
	v_and_b32_e32 v159, 0xffff0000, v169
	v_pk_add_f32 v[156:157], v[156:157], v[158:159]
	v_pk_add_f32 v[156:157], v[112:113], v[156:157]
	v_cvt_pk_bf16_f32 v165, v156, v157
	v_pk_fma_f32 v[198:199], v[156:157], v[156:157], v[198:199]
	v_lshlrev_b32_e32 v158, 16, v165
	v_and_b32_e32 v159, 0xffff0000, v165
	v_pk_add_f32 v[196:197], v[156:157], v[158:159] neg_lo:[0,1] neg_hi:[0,1]
	v_cvt_pk_bf16_f32 v169, v196, v197
	v_lshlrev_b32_e32 v156, 16, v166
	v_and_b32_e32 v157, 0xffff0000, v166
	v_lshlrev_b32_e32 v158, 16, v170
	v_and_b32_e32 v159, 0xffff0000, v170
	v_pk_add_f32 v[156:157], v[156:157], v[158:159]
	v_pk_add_f32 v[156:157], v[106:107], v[156:157]
	v_cvt_pk_bf16_f32 v166, v156, v157
	v_pk_fma_f32 v[198:199], v[156:157], v[156:157], v[198:199]
	v_lshlrev_b32_e32 v158, 16, v166
	v_and_b32_e32 v159, 0xffff0000, v166
	v_pk_add_f32 v[196:197], v[156:157], v[158:159] neg_lo:[0,1] neg_hi:[0,1]
	v_cvt_pk_bf16_f32 v170, v196, v197
	v_lshlrev_b32_e32 v156, 16, v167
	v_and_b32_e32 v157, 0xffff0000, v167
	v_lshlrev_b32_e32 v158, 16, v171
	v_and_b32_e32 v159, 0xffff0000, v171
	v_pk_add_f32 v[156:157], v[156:157], v[158:159]
	v_pk_add_f32 v[156:157], v[108:109], v[156:157]
	v_cvt_pk_bf16_f32 v167, v156, v157
	v_pk_fma_f32 v[198:199], v[156:157], v[156:157], v[198:199]
	v_lshlrev_b32_e32 v158, 16, v167
	v_and_b32_e32 v159, 0xffff0000, v167
	v_pk_add_f32 v[196:197], v[156:157], v[158:159] neg_lo:[0,1] neg_hi:[0,1]
	v_cvt_pk_bf16_f32 v171, v196, v197
	global_store_dwordx4 v211, v[164:167], s[10:11]
	global_store_dwordx4 v211, v[168:171], s[14:15]
	s_waitcnt vmcnt(14)
	v_lshlrev_b32_e32 v156, 16, v172
	v_and_b32_e32 v157, 0xffff0000, v172
	v_lshlrev_b32_e32 v158, 16, v176
	v_and_b32_e32 v159, 0xffff0000, v176
	v_pk_add_f32 v[156:157], v[156:157], v[158:159]
	v_pk_add_f32 v[156:157], v[102:103], v[156:157]
	v_cvt_pk_bf16_f32 v172, v156, v157
	v_pk_fma_f32 v[198:199], v[156:157], v[156:157], v[198:199]
	v_lshlrev_b32_e32 v158, 16, v172
	v_and_b32_e32 v159, 0xffff0000, v172
	v_pk_add_f32 v[196:197], v[156:157], v[158:159] neg_lo:[0,1] neg_hi:[0,1]
	v_cvt_pk_bf16_f32 v176, v196, v197
	v_lshlrev_b32_e32 v156, 16, v173
	v_and_b32_e32 v157, 0xffff0000, v173
	v_lshlrev_b32_e32 v158, 16, v177
	v_and_b32_e32 v159, 0xffff0000, v177
	v_pk_add_f32 v[156:157], v[156:157], v[158:159]
	v_pk_add_f32 v[156:157], v[104:105], v[156:157]
	v_cvt_pk_bf16_f32 v173, v156, v157
	v_pk_fma_f32 v[198:199], v[156:157], v[156:157], v[198:199]
	v_lshlrev_b32_e32 v158, 16, v173
	v_and_b32_e32 v159, 0xffff0000, v173
	v_pk_add_f32 v[196:197], v[156:157], v[158:159] neg_lo:[0,1] neg_hi:[0,1]
	v_cvt_pk_bf16_f32 v177, v196, v197
	v_lshlrev_b32_e32 v156, 16, v174
	v_and_b32_e32 v157, 0xffff0000, v174
	v_lshlrev_b32_e32 v158, 16, v178
	v_and_b32_e32 v159, 0xffff0000, v178
	v_pk_add_f32 v[156:157], v[156:157], v[158:159]
	v_pk_add_f32 v[156:157], v[98:99], v[156:157]
	v_cvt_pk_bf16_f32 v174, v156, v157
	v_pk_fma_f32 v[198:199], v[156:157], v[156:157], v[198:199]
	v_lshlrev_b32_e32 v158, 16, v174
	v_and_b32_e32 v159, 0xffff0000, v174
	v_pk_add_f32 v[196:197], v[156:157], v[158:159] neg_lo:[0,1] neg_hi:[0,1]
	v_cvt_pk_bf16_f32 v178, v196, v197
	v_lshlrev_b32_e32 v156, 16, v175
	v_and_b32_e32 v157, 0xffff0000, v175
	v_lshlrev_b32_e32 v158, 16, v179
	v_and_b32_e32 v159, 0xffff0000, v179
	v_pk_add_f32 v[156:157], v[156:157], v[158:159]
	v_pk_add_f32 v[156:157], v[100:101], v[156:157]
	v_cvt_pk_bf16_f32 v175, v156, v157
	v_pk_fma_f32 v[198:199], v[156:157], v[156:157], v[198:199]
	v_lshlrev_b32_e32 v158, 16, v175
	v_and_b32_e32 v159, 0xffff0000, v175
	v_pk_add_f32 v[196:197], v[156:157], v[158:159] neg_lo:[0,1] neg_hi:[0,1]
	v_cvt_pk_bf16_f32 v179, v196, v197
	global_store_dwordx4 v211, v[172:175], s[10:11] offset:256
	global_store_dwordx4 v211, v[176:179], s[14:15] offset:256
	v_add_f32_e32 v201, v198, v199
	s_nop 0
	v_add_u32_e32 v211, 0x40000, v213
	global_load_dwordx4 v[164:167], v211, s[10:11]
	global_load_dwordx4 v[168:171], v211, s[14:15]
	global_load_dwordx4 v[172:175], v211, s[10:11] offset:256
	global_load_dwordx4 v[176:179], v211, s[14:15] offset:256
	s_waitcnt vmcnt(18)
; __device__ __forceinline__ unsigned pk2(float lo, float hi) { f32x2_t v = {lo, hi}; bf16x2_t b = __builtin_convertvector(v, bf16x2_t); return __builtin_bit_cast(unsigned, b); }
; __device__ __forceinline__ float bflo(unsigned u) { return __uint_as_float(u << 16); }
; __device__ __forceinline__ float bfhi(unsigned u) { return __uint_as_float(u & 0xffff0000u); }
;     __device__ __forceinline__ void operator()(const f32x4 (&acc)[2][2][4][2], const Unit& u, int wr, int wc, int fr, int fq) const {
;     ...
;                     const size_t off = (size_t)row * DM + col0 + bj * HALF;
;                     const u32x4 hh = *(const u32x4*)(HI + off), ll = *(const u32x4*)(LO + off);
;                     float hv[8] = {bflo(hh.x) + bflo(ll.x), bfhi(hh.x) + bfhi(ll.x), bflo(hh.y) + bflo(ll.y), bfhi(hh.y) + bfhi(ll.y),
;                                    bflo(hh.z) + bflo(ll.z), bfhi(hh.z) + bfhi(ll.z), bflo(hh.w) + bflo(ll.w), bfhi(hh.w) + bfhi(ll.w)};
;                     float av[8] = {acc[ai][bj][m][0][0], acc[ai][bj][m][0][1], acc[ai][bj][m][0][2], acc[ai][bj][m][0][3], acc[ai][bj][m][1][0], acc[ai][bj][m][1][1], acc[ai][bj][m][1][2], acc[ai][bj][m][1][3]};
;                     if (GATED) { const u32x4 pp = *(const u32x4*)(PP + off);
;                         const float pv[8] = {bflo(pp.x), bfhi(pp.x), bflo(pp.y), bfhi(pp.y), bflo(pp.z), bfhi(pp.z), bflo(pp.w), bfhi(pp.w)};
; #pragma unroll
;                         for (int e = 0; e < 8; ++e) av[e] = fast_sigmoid(av[e] * rs) * pv[e]; }
;                     else {
; #pragma unroll
;                         for (int e = 0; e < 8; ++e) av[e] *= alpha; }
;                     float lo[8];
; #pragma unroll
;                     for (int e = 0; e < 8; ++e) { hv[e] += av[e]; sq += hv[e] * hv[e]; }
;                     u32x4 wh; wh.x = pk2(hv[0], hv[1]); wh.y = pk2(hv[2], hv[3]); wh.z = pk2(hv[4], hv[5]); wh.w = pk2(hv[6], hv[7]);
;                     lo[0] = hv[0] - bflo(wh.x); lo[1] = hv[1] - bfhi(wh.x); lo[2] = hv[2] - bflo(wh.y); lo[3] = hv[3] - bfhi(wh.y);
;                     lo[4] = hv[4] - bflo(wh.z); lo[5] = hv[5] - bfhi(wh.z); lo[6] = hv[6] - bflo(wh.w); lo[7] = hv[7] - bfhi(wh.w);
;                     u32x4 wl; wl.x = pk2(lo[0], lo[1]); wl.y = pk2(lo[2], lo[3]); wl.z = pk2(lo[4], lo[5]); wl.w = pk2(lo[6], lo[7]);
;                     *(u32x4*)(HO + off) = wh; *(u32x4*)(LO + off) = wl;
	v_lshlrev_b32_e32 v156, 16, v180
	v_and_b32_e32 v157, 0xffff0000, v180
	v_lshlrev_b32_e32 v158, 16, v184
	v_and_b32_e32 v159, 0xffff0000, v184
	v_pk_add_f32 v[156:157], v[156:157], v[158:159]
	v_pk_add_f32 v[156:157], v[94:95], v[156:157]
	v_cvt_pk_bf16_f32 v180, v156, v157
	v_pk_mul_f32 v[198:199], v[156:157], v[156:157]
	v_lshlrev_b32_e32 v158, 16, v180
	v_and_b32_e32 v159, 0xffff0000, v180
	v_pk_add_f32 v[196:197], v[156:157], v[158:159] neg_lo:[0,1] neg_hi:[0,1]
	v_cvt_pk_bf16_f32 v184, v196, v197
	v_lshlrev_b32_e32 v156, 16, v181
	v_and_b32_e32 v157, 0xffff0000, v181
	v_lshlrev_b32_e32 v158, 16, v185
	v_and_b32_e32 v159, 0xffff0000, v185
	v_pk_add_f32 v[156:157], v[156:157], v[158:159]
	v_pk_add_f32 v[156:157], v[96:97], v[156:157]
	v_cvt_pk_bf16_f32 v181, v156, v157
	v_pk_fma_f32 v[198:199], v[156:157], v[156:157], v[198:199]
	v_lshlrev_b32_e32 v158, 16, v181
	v_and_b32_e32 v159, 0xffff0000, v181
	v_pk_add_f32 v[196:197], v[156:157], v[158:159] neg_lo:[0,1] neg_hi:[0,1]
	v_cvt_pk_bf16_f32 v185, v196, v197
	v_lshlrev_b32_e32 v156, 16, v182
	v_and_b32_e32 v157, 0xffff0000, v182
	v_lshlrev_b32_e32 v158, 16, v186
	v_and_b32_e32 v159, 0xffff0000, v186
	v_pk_add_f32 v[156:157], v[156:157], v[158:159]
	v_pk_add_f32 v[156:157], v[90:91], v[156:157]
	v_cvt_pk_bf16_f32 v182, v156, v157
	v_pk_fma_f32 v[198:199], v[156:157], v[156:157], v[198:199]
	v_lshlrev_b32_e32 v158, 16, v182
	v_and_b32_e32 v159, 0xffff0000, v182
	v_pk_add_f32 v[196:197], v[156:157], v[158:159] neg_lo:[0,1] neg_hi:[0,1]
	v_cvt_pk_bf16_f32 v186, v196, v197
	v_lshlrev_b32_e32 v156, 16, v183
	v_and_b32_e32 v157, 0xffff0000, v183
	v_lshlrev_b32_e32 v158, 16, v187
	v_and_b32_e32 v159, 0xffff0000, v187
	v_pk_add_f32 v[156:157], v[156:157], v[158:159]
	v_pk_add_f32 v[156:157], v[92:93], v[156:157]
	v_cvt_pk_bf16_f32 v183, v156, v157
	v_pk_fma_f32 v[198:199], v[156:157], v[156:157], v[198:199]
	v_lshlrev_b32_e32 v158, 16, v183
	v_and_b32_e32 v159, 0xffff0000, v183
	v_pk_add_f32 v[196:197], v[156:157], v[158:159] neg_lo:[0,1] neg_hi:[0,1]
	v_cvt_pk_bf16_f32 v187, v196, v197
	global_store_dwordx4 v212, v[180:183], s[10:11]
	global_store_dwordx4 v212, v[184:187], s[14:15]
	s_waitcnt vmcnt(18)
	v_lshlrev_b32_e32 v156, 16, v188
	v_and_b32_e32 v157, 0xffff0000, v188
	v_lshlrev_b32_e32 v158, 16, v192
	v_and_b32_e32 v159, 0xffff0000, v192
	v_pk_add_f32 v[156:157], v[156:157], v[158:159]
	v_pk_add_f32 v[156:157], v[86:87], v[156:157]
	v_cvt_pk_bf16_f32 v188, v156, v157
	v_pk_fma_f32 v[198:199], v[156:157], v[156:157], v[198:199]
	v_lshlrev_b32_e32 v158, 16, v188
	v_and_b32_e32 v159, 0xffff0000, v188
	v_pk_add_f32 v[196:197], v[156:157], v[158:159] neg_lo:[0,1] neg_hi:[0,1]
	v_cvt_pk_bf16_f32 v192, v196, v197
	v_lshlrev_b32_e32 v156, 16, v189
	v_and_b32_e32 v157, 0xffff0000, v189
	v_lshlrev_b32_e32 v158, 16, v193
	v_and_b32_e32 v159, 0xffff0000, v193
	v_pk_add_f32 v[156:157], v[156:157], v[158:159]
	v_pk_add_f32 v[156:157], v[88:89], v[156:157]
	v_cvt_pk_bf16_f32 v189, v156, v157
	v_pk_fma_f32 v[198:199], v[156:157], v[156:157], v[198:199]
	v_lshlrev_b32_e32 v158, 16, v189
	v_and_b32_e32 v159, 0xffff0000, v189
	v_pk_add_f32 v[196:197], v[156:157], v[158:159] neg_lo:[0,1] neg_hi:[0,1]
	v_cvt_pk_bf16_f32 v193, v196, v197
	v_lshlrev_b32_e32 v156, 16, v190
	v_and_b32_e32 v157, 0xffff0000, v190
	v_lshlrev_b32_e32 v158, 16, v194
	v_and_b32_e32 v159, 0xffff0000, v194
	v_pk_add_f32 v[156:157], v[156:157], v[158:159]
	v_pk_add_f32 v[156:157], v[82:83], v[156:157]
	v_cvt_pk_bf16_f32 v190, v156, v157
	v_pk_fma_f32 v[198:199], v[156:157], v[156:157], v[198:199]
	v_lshlrev_b32_e32 v158, 16, v190
	v_and_b32_e32 v159, 0xffff0000, v190
	v_pk_add_f32 v[196:197], v[156:157], v[158:159] neg_lo:[0,1] neg_hi:[0,1]
	v_cvt_pk_bf16_f32 v194, v196, v197
	v_lshlrev_b32_e32 v156, 16, v191
	v_and_b32_e32 v157, 0xffff0000, v191
	v_lshlrev_b32_e32 v158, 16, v195
	v_and_b32_e32 v159, 0xffff0000, v195
	v_pk_add_f32 v[156:157], v[156:157], v[158:159]
	v_pk_add_f32 v[156:157], v[84:85], v[156:157]
	v_cvt_pk_bf16_f32 v191, v156, v157
	v_pk_fma_f32 v[198:199], v[156:157], v[156:157], v[198:199]
	v_lshlrev_b32_e32 v158, 16, v191
	v_and_b32_e32 v159, 0xffff0000, v191
	v_pk_add_f32 v[196:197], v[156:157], v[158:159] neg_lo:[0,1] neg_hi:[0,1]
	v_cvt_pk_bf16_f32 v195, v196, v197
	global_store_dwordx4 v212, v[188:191], s[10:11] offset:256
	global_store_dwordx4 v212, v[192:195], s[14:15] offset:256
	v_add_f32_e32 v202, v198, v199
	s_nop 0
	v_add_u32_e32 v212, 0x48000, v213
	global_load_dwordx4 v[180:183], v212, s[10:11]
	global_load_dwordx4 v[184:187], v212, s[14:15]
	global_load_dwordx4 v[188:191], v212, s[10:11] offset:256
	global_load_dwordx4 v[192:195], v212, s[14:15] offset:256
	s_waitcnt vmcnt(18)
; __device__ __forceinline__ unsigned pk2(float lo, float hi) { f32x2_t v = {lo, hi}; bf16x2_t b = __builtin_convertvector(v, bf16x2_t); return __builtin_bit_cast(unsigned, b); }
; __device__ __forceinline__ float bflo(unsigned u) { return __uint_as_float(u << 16); }
; __device__ __forceinline__ float bfhi(unsigned u) { return __uint_as_float(u & 0xffff0000u); }
;     __device__ __forceinline__ void operator()(const f32x4 (&acc)[2][2][4][2], const Unit& u, int wr, int wc, int fr, int fq) const {
;     ...
;                     const size_t off = (size_t)row * DM + col0 + bj * HALF;
;                     const u32x4 hh = *(const u32x4*)(HI + off), ll = *(const u32x4*)(LO + off);
;                     float hv[8] = {bflo(hh.x) + bflo(ll.x), bfhi(hh.x) + bfhi(ll.x), bflo(hh.y) + bflo(ll.y), bfhi(hh.y) + bfhi(ll.y),
;                                    bflo(hh.z) + bflo(ll.z), bfhi(hh.z) + bfhi(ll.z), bflo(hh.w) + bflo(ll.w), bfhi(hh.w) + bfhi(ll.w)};
;                     float av[8] = {acc[ai][bj][m][0][0], acc[ai][bj][m][0][1], acc[ai][bj][m][0][2], acc[ai][bj][m][0][3], acc[ai][bj][m][1][0], acc[ai][bj][m][1][1], acc[ai][bj][m][1][2], acc[ai][bj][m][1][3]};
;                     if (GATED) { const u32x4 pp = *(const u32x4*)(PP + off);
;                         const float pv[8] = {bflo(pp.x), bfhi(pp.x), bflo(pp.y), bfhi(pp.y), bflo(pp.z), bfhi(pp.z), bflo(pp.w), bfhi(pp.w)};
; #pragma unroll
;                         for (int e = 0; e < 8; ++e) av[e] = fast_sigmoid(av[e] * rs) * pv[e]; }
;                     else {
; #pragma unroll
;                         for (int e = 0; e < 8; ++e) av[e] *= alpha; }
;                     float lo[8];
; #pragma unroll
;                     for (int e = 0; e < 8; ++e) { hv[e] += av[e]; sq += hv[e] * hv[e]; }
;                     u32x4 wh; wh.x = pk2(hv[0], hv[1]); wh.y = pk2(hv[2], hv[3]); wh.z = pk2(hv[4], hv[5]); wh.w = pk2(hv[6], hv[7]);
;                     lo[0] = hv[0] - bflo(wh.x); lo[1] = hv[1] - bfhi(wh.x); lo[2] = hv[2] - bflo(wh.y); lo[3] = hv[3] - bfhi(wh.y);
;                     lo[4] = hv[4] - bflo(wh.z); lo[5] = hv[5] - bfhi(wh.z); lo[6] = hv[6] - bflo(wh.w); lo[7] = hv[7] - bfhi(wh.w);
;                     u32x4 wl; wl.x = pk2(lo[0], lo[1]); wl.y = pk2(lo[2], lo[3]); wl.z = pk2(lo[4], lo[5]); wl.w = pk2(lo[6], lo[7]);
;                     *(u32x4*)(HO + off) = wh; *(u32x4*)(LO + off) = wl;
	v_lshlrev_b32_e32 v156, 16, v140
	v_and_b32_e32 v157, 0xffff0000, v140
	v_lshlrev_b32_e32 v158, 16, v144
	v_and_b32_e32 v159, 0xffff0000, v144
	v_pk_add_f32 v[156:157], v[156:157], v[158:159]
	v_pk_add_f32 v[156:157], v[78:79], v[156:157]
	v_cvt_pk_bf16_f32 v140, v156, v157
	v_pk_mul_f32 v[198:199], v[156:157], v[156:157]
	v_lshlrev_b32_e32 v158, 16, v140
	v_and_b32_e32 v159, 0xffff0000, v140
	v_pk_add_f32 v[196:197], v[156:157], v[158:159] neg_lo:[0,1] neg_hi:[0,1]
	v_cvt_pk_bf16_f32 v144, v196, v197
	v_lshlrev_b32_e32 v156, 16, v141
	v_and_b32_e32 v157, 0xffff0000, v141
	v_lshlrev_b32_e32 v158, 16, v145
	v_and_b32_e32 v159, 0xffff0000, v145
	v_pk_add_f32 v[156:157], v[156:157], v[158:159]
	v_pk_add_f32 v[156:157], v[80:81], v[156:157]
	v_cvt_pk_bf16_f32 v141, v156, v157
	v_pk_fma_f32 v[198:199], v[156:157], v[156:157], v[198:199]
	v_lshlrev_b32_e32 v158, 16, v141
	v_and_b32_e32 v159, 0xffff0000, v141
	v_pk_add_f32 v[196:197], v[156:157], v[158:159] neg_lo:[0,1] neg_hi:[0,1]
	v_cvt_pk_bf16_f32 v145, v196, v197
	v_lshlrev_b32_e32 v156, 16, v142
	v_and_b32_e32 v157, 0xffff0000, v142
	v_lshlrev_b32_e32 v158, 16, v146
	v_and_b32_e32 v159, 0xffff0000, v146
	v_pk_add_f32 v[156:157], v[156:157], v[158:159]
	v_pk_add_f32 v[156:157], v[74:75], v[156:157]
	v_cvt_pk_bf16_f32 v142, v156, v157
	v_pk_fma_f32 v[198:199], v[156:157], v[156:157], v[198:199]
	v_lshlrev_b32_e32 v158, 16, v142
	v_and_b32_e32 v159, 0xffff0000, v142
	v_pk_add_f32 v[196:197], v[156:157], v[158:159] neg_lo:[0,1] neg_hi:[0,1]
	v_cvt_pk_bf16_f32 v146, v196, v197
	v_lshlrev_b32_e32 v156, 16, v143
	v_and_b32_e32 v157, 0xffff0000, v143
	v_lshlrev_b32_e32 v158, 16, v147
	v_and_b32_e32 v159, 0xffff0000, v147
	v_pk_add_f32 v[156:157], v[156:157], v[158:159]
	v_pk_add_f32 v[156:157], v[76:77], v[156:157]
	v_cvt_pk_bf16_f32 v143, v156, v157
	v_pk_fma_f32 v[198:199], v[156:157], v[156:157], v[198:199]
	v_lshlrev_b32_e32 v158, 16, v143
	v_and_b32_e32 v159, 0xffff0000, v143
	v_pk_add_f32 v[196:197], v[156:157], v[158:159] neg_lo:[0,1] neg_hi:[0,1]
	v_cvt_pk_bf16_f32 v147, v196, v197
	global_store_dwordx4 v210, v[140:143], s[10:11]
	global_store_dwordx4 v210, v[144:147], s[14:15]
	s_waitcnt vmcnt(18)
	v_lshlrev_b32_e32 v156, 16, v148
	v_and_b32_e32 v157, 0xffff0000, v148
	v_lshlrev_b32_e32 v158, 16, v152
	v_and_b32_e32 v159, 0xffff0000, v152
	v_pk_add_f32 v[156:157], v[156:157], v[158:159]
	v_pk_add_f32 v[156:157], v[70:71], v[156:157]
	v_cvt_pk_bf16_f32 v148, v156, v157
	v_pk_fma_f32 v[198:199], v[156:157], v[156:157], v[198:199]
	v_lshlrev_b32_e32 v158, 16, v148
	v_and_b32_e32 v159, 0xffff0000, v148
	v_pk_add_f32 v[196:197], v[156:157], v[158:159] neg_lo:[0,1] neg_hi:[0,1]
	v_cvt_pk_bf16_f32 v152, v196, v197
	v_lshlrev_b32_e32 v156, 16, v149
	v_and_b32_e32 v157, 0xffff0000, v149
	v_lshlrev_b32_e32 v158, 16, v153
	v_and_b32_e32 v159, 0xffff0000, v153
	v_pk_add_f32 v[156:157], v[156:157], v[158:159]
	v_pk_add_f32 v[156:157], v[72:73], v[156:157]
	v_cvt_pk_bf16_f32 v149, v156, v157
	v_pk_fma_f32 v[198:199], v[156:157], v[156:157], v[198:199]
	v_lshlrev_b32_e32 v158, 16, v149
	v_and_b32_e32 v159, 0xffff0000, v149
	v_pk_add_f32 v[196:197], v[156:157], v[158:159] neg_lo:[0,1] neg_hi:[0,1]
	v_cvt_pk_bf16_f32 v153, v196, v197
	v_lshlrev_b32_e32 v156, 16, v150
	v_and_b32_e32 v157, 0xffff0000, v150
	v_lshlrev_b32_e32 v158, 16, v154
	v_and_b32_e32 v159, 0xffff0000, v154
	v_pk_add_f32 v[156:157], v[156:157], v[158:159]
	v_pk_add_f32 v[156:157], v[66:67], v[156:157]
	v_cvt_pk_bf16_f32 v150, v156, v157
	v_pk_fma_f32 v[198:199], v[156:157], v[156:157], v[198:199]
	v_lshlrev_b32_e32 v158, 16, v150
	v_and_b32_e32 v159, 0xffff0000, v150
	v_pk_add_f32 v[196:197], v[156:157], v[158:159] neg_lo:[0,1] neg_hi:[0,1]
	v_cvt_pk_bf16_f32 v154, v196, v197
	v_lshlrev_b32_e32 v156, 16, v151
	v_and_b32_e32 v157, 0xffff0000, v151
	v_lshlrev_b32_e32 v158, 16, v155
	v_and_b32_e32 v159, 0xffff0000, v155
	v_pk_add_f32 v[156:157], v[156:157], v[158:159]
	v_pk_add_f32 v[156:157], v[68:69], v[156:157]
	v_cvt_pk_bf16_f32 v151, v156, v157
	v_pk_fma_f32 v[198:199], v[156:157], v[156:157], v[198:199]
	v_lshlrev_b32_e32 v158, 16, v151
	v_and_b32_e32 v159, 0xffff0000, v151
	v_pk_add_f32 v[196:197], v[156:157], v[158:159] neg_lo:[0,1] neg_hi:[0,1]
	v_cvt_pk_bf16_f32 v155, v196, v197
	global_store_dwordx4 v210, v[148:151], s[10:11] offset:256
	global_store_dwordx4 v210, v[152:155], s[14:15] offset:256
	v_add_f32_e32 v203, v198, v199
	s_nop 0
	v_add_u32_e32 v210, 0x50000, v213
	global_load_dwordx4 v[140:143], v210, s[10:11]
	global_load_dwordx4 v[144:147], v210, s[14:15]
	global_load_dwordx4 v[148:151], v210, s[10:11] offset:256
	global_load_dwordx4 v[152:155], v210, s[14:15] offset:256
	s_waitcnt vmcnt(18)
; __device__ __forceinline__ unsigned pk2(float lo, float hi) { f32x2_t v = {lo, hi}; bf16x2_t b = __builtin_convertvector(v, bf16x2_t); return __builtin_bit_cast(unsigned, b); }
; __device__ __forceinline__ float bflo(unsigned u) { return __uint_as_float(u << 16); }
; __device__ __forceinline__ float bfhi(unsigned u) { return __uint_as_float(u & 0xffff0000u); }
;     __device__ __forceinline__ void operator()(const f32x4 (&acc)[2][2][4][2], const Unit& u, int wr, int wc, int fr, int fq) const {
;     ...
;                     const size_t off = (size_t)row * DM + col0 + bj * HALF;
;                     const u32x4 hh = *(const u32x4*)(HI + off), ll = *(const u32x4*)(LO + off);
;                     float hv[8] = {bflo(hh.x) + bflo(ll.x), bfhi(hh.x) + bfhi(ll.x), bflo(hh.y) + bflo(ll.y), bfhi(hh.y) + bfhi(ll.y),
;                                    bflo(hh.z) + bflo(ll.z), bfhi(hh.z) + bfhi(ll.z), bflo(hh.w) + bflo(ll.w), bfhi(hh.w) + bfhi(ll.w)};
;                     float av[8] = {acc[ai][bj][m][0][0], acc[ai][bj][m][0][1], acc[ai][bj][m][0][2], acc[ai][bj][m][0][3], acc[ai][bj][m][1][0], acc[ai][bj][m][1][1], acc[ai][bj][m][1][2], acc[ai][bj][m][1][3]};
;                     if (GATED) { const u32x4 pp = *(const u32x4*)(PP + off);
;                         const float pv[8] = {bflo(pp.x), bfhi(pp.x), bflo(pp.y), bfhi(pp.y), bflo(pp.z), bfhi(pp.z), bflo(pp.w), bfhi(pp.w)};
; #pragma unroll
;                         for (int e = 0; e < 8; ++e) av[e] = fast_sigmoid(av[e] * rs) * pv[e]; }
;                     else {
; #pragma unroll
;                         for (int e = 0; e < 8; ++e) av[e] *= alpha; }
;                     float lo[8];
; #pragma unroll
;                     for (int e = 0; e < 8; ++e) { hv[e] += av[e]; sq += hv[e] * hv[e]; }
;                     u32x4 wh; wh.x = pk2(hv[0], hv[1]); wh.y = pk2(hv[2], hv[3]); wh.z = pk2(hv[4], hv[5]); wh.w = pk2(hv[6], hv[7]);
;                     lo[0] = hv[0] - bflo(wh.x); lo[1] = hv[1] - bfhi(wh.x); lo[2] = hv[2] - bflo(wh.y); lo[3] = hv[3] - bfhi(wh.y);
;                     lo[4] = hv[4] - bflo(wh.z); lo[5] = hv[5] - bfhi(wh.z); lo[6] = hv[6] - bflo(wh.w); lo[7] = hv[7] - bfhi(wh.w);
;                     u32x4 wl; wl.x = pk2(lo[0], lo[1]); wl.y = pk2(lo[2], lo[3]); wl.z = pk2(lo[4], lo[5]); wl.w = pk2(lo[6], lo[7]);
;                     *(u32x4*)(HO + off) = wh; *(u32x4*)(LO + off) = wl;
	v_lshlrev_b32_e32 v156, 16, v164
	v_and_b32_e32 v157, 0xffff0000, v164
	v_lshlrev_b32_e32 v158, 16, v168
	v_and_b32_e32 v159, 0xffff0000, v168
	v_pk_add_f32 v[156:157], v[156:157], v[158:159]
	v_pk_add_f32 v[156:157], v[62:63], v[156:157]
	v_cvt_pk_bf16_f32 v164, v156, v157
	v_pk_mul_f32 v[198:199], v[156:157], v[156:157]
	v_lshlrev_b32_e32 v158, 16, v164
	v_and_b32_e32 v159, 0xffff0000, v164
	v_pk_add_f32 v[196:197], v[156:157], v[158:159] neg_lo:[0,1] neg_hi:[0,1]
	v_cvt_pk_bf16_f32 v168, v196, v197
	v_lshlrev_b32_e32 v156, 16, v165
	v_and_b32_e32 v157, 0xffff0000, v165
	v_lshlrev_b32_e32 v158, 16, v169
	v_and_b32_e32 v159, 0xffff0000, v169
	v_pk_add_f32 v[156:157], v[156:157], v[158:159]
	v_pk_add_f32 v[156:157], v[64:65], v[156:157]
	v_cvt_pk_bf16_f32 v165, v156, v157
	v_pk_fma_f32 v[198:199], v[156:157], v[156:157], v[198:199]
	v_lshlrev_b32_e32 v158, 16, v165
	v_and_b32_e32 v159, 0xffff0000, v165
	v_pk_add_f32 v[196:197], v[156:157], v[158:159] neg_lo:[0,1] neg_hi:[0,1]
	v_cvt_pk_bf16_f32 v169, v196, v197
	v_lshlrev_b32_e32 v156, 16, v166
	v_and_b32_e32 v157, 0xffff0000, v166
	v_lshlrev_b32_e32 v158, 16, v170
	v_and_b32_e32 v159, 0xffff0000, v170
	v_pk_add_f32 v[156:157], v[156:157], v[158:159]
	v_pk_add_f32 v[156:157], v[58:59], v[156:157]
	v_cvt_pk_bf16_f32 v166, v156, v157
	v_pk_fma_f32 v[198:199], v[156:157], v[156:157], v[198:199]
	v_lshlrev_b32_e32 v158, 16, v166
	v_and_b32_e32 v159, 0xffff0000, v166
	v_pk_add_f32 v[196:197], v[156:157], v[158:159] neg_lo:[0,1] neg_hi:[0,1]
	v_cvt_pk_bf16_f32 v170, v196, v197
	v_lshlrev_b32_e32 v156, 16, v167
	v_and_b32_e32 v157, 0xffff0000, v167
	v_lshlrev_b32_e32 v158, 16, v171
	v_and_b32_e32 v159, 0xffff0000, v171
	v_pk_add_f32 v[156:157], v[156:157], v[158:159]
	v_pk_add_f32 v[156:157], v[60:61], v[156:157]
	v_cvt_pk_bf16_f32 v167, v156, v157
	v_pk_fma_f32 v[198:199], v[156:157], v[156:157], v[198:199]
	v_lshlrev_b32_e32 v158, 16, v167
	v_and_b32_e32 v159, 0xffff0000, v167
	v_pk_add_f32 v[196:197], v[156:157], v[158:159] neg_lo:[0,1] neg_hi:[0,1]
	v_cvt_pk_bf16_f32 v171, v196, v197
	global_store_dwordx4 v211, v[164:167], s[10:11]
	global_store_dwordx4 v211, v[168:171], s[14:15]
	s_waitcnt vmcnt(18)
	v_lshlrev_b32_e32 v156, 16, v172
	v_and_b32_e32 v157, 0xffff0000, v172
	v_lshlrev_b32_e32 v158, 16, v176
	v_and_b32_e32 v159, 0xffff0000, v176
	v_pk_add_f32 v[156:157], v[156:157], v[158:159]
	v_pk_add_f32 v[156:157], v[54:55], v[156:157]
	v_cvt_pk_bf16_f32 v172, v156, v157
	v_pk_fma_f32 v[198:199], v[156:157], v[156:157], v[198:199]
	v_lshlrev_b32_e32 v158, 16, v172
	v_and_b32_e32 v159, 0xffff0000, v172
	v_pk_add_f32 v[196:197], v[156:157], v[158:159] neg_lo:[0,1] neg_hi:[0,1]
	v_cvt_pk_bf16_f32 v176, v196, v197
	v_lshlrev_b32_e32 v156, 16, v173
	v_and_b32_e32 v157, 0xffff0000, v173
	v_lshlrev_b32_e32 v158, 16, v177
	v_and_b32_e32 v159, 0xffff0000, v177
	v_pk_add_f32 v[156:157], v[156:157], v[158:159]
	v_pk_add_f32 v[156:157], v[56:57], v[156:157]
	v_cvt_pk_bf16_f32 v173, v156, v157
	v_pk_fma_f32 v[198:199], v[156:157], v[156:157], v[198:199]
	v_lshlrev_b32_e32 v158, 16, v173
	v_and_b32_e32 v159, 0xffff0000, v173
	v_pk_add_f32 v[196:197], v[156:157], v[158:159] neg_lo:[0,1] neg_hi:[0,1]
	v_cvt_pk_bf16_f32 v177, v196, v197
	v_lshlrev_b32_e32 v156, 16, v174
	v_and_b32_e32 v157, 0xffff0000, v174
	v_lshlrev_b32_e32 v158, 16, v178
	v_and_b32_e32 v159, 0xffff0000, v178
	v_pk_add_f32 v[156:157], v[156:157], v[158:159]
	v_pk_add_f32 v[156:157], v[50:51], v[156:157]
	v_cvt_pk_bf16_f32 v174, v156, v157
	v_pk_fma_f32 v[198:199], v[156:157], v[156:157], v[198:199]
	v_lshlrev_b32_e32 v158, 16, v174
	v_and_b32_e32 v159, 0xffff0000, v174
	v_pk_add_f32 v[196:197], v[156:157], v[158:159] neg_lo:[0,1] neg_hi:[0,1]
	v_cvt_pk_bf16_f32 v178, v196, v197
	v_lshlrev_b32_e32 v156, 16, v175
	v_and_b32_e32 v157, 0xffff0000, v175
	v_lshlrev_b32_e32 v158, 16, v179
	v_and_b32_e32 v159, 0xffff0000, v179
	v_pk_add_f32 v[156:157], v[156:157], v[158:159]
	v_pk_add_f32 v[156:157], v[52:53], v[156:157]
	v_cvt_pk_bf16_f32 v175, v156, v157
	v_pk_fma_f32 v[198:199], v[156:157], v[156:157], v[198:199]
	v_lshlrev_b32_e32 v158, 16, v175
	v_and_b32_e32 v159, 0xffff0000, v175
	v_pk_add_f32 v[196:197], v[156:157], v[158:159] neg_lo:[0,1] neg_hi:[0,1]
	v_cvt_pk_bf16_f32 v179, v196, v197
	global_store_dwordx4 v211, v[172:175], s[10:11] offset:256
	global_store_dwordx4 v211, v[176:179], s[14:15] offset:256
	v_add_f32_e32 v206, v198, v199
	s_nop 0
	v_add_u32_e32 v211, 0x58000, v213
	global_load_dwordx4 v[164:167], v211, s[10:11]
	global_load_dwordx4 v[168:171], v211, s[14:15]
	global_load_dwordx4 v[172:175], v211, s[10:11] offset:256
	global_load_dwordx4 v[176:179], v211, s[14:15] offset:256
	s_waitcnt vmcnt(18)
; __device__ __forceinline__ unsigned pk2(float lo, float hi) { f32x2_t v = {lo, hi}; bf16x2_t b = __builtin_convertvector(v, bf16x2_t); return __builtin_bit_cast(unsigned, b); }
; __device__ __forceinline__ float bflo(unsigned u) { return __uint_as_float(u << 16); }
; __device__ __forceinline__ float bfhi(unsigned u) { return __uint_as_float(u & 0xffff0000u); }
;     __device__ __forceinline__ void operator()(const f32x4 (&acc)[2][2][4][2], const Unit& u, int wr, int wc, int fr, int fq) const {
;     ...
;                     const size_t off = (size_t)row * DM + col0 + bj * HALF;
;                     const u32x4 hh = *(const u32x4*)(HI + off), ll = *(const u32x4*)(LO + off);
;                     float hv[8] = {bflo(hh.x) + bflo(ll.x), bfhi(hh.x) + bfhi(ll.x), bflo(hh.y) + bflo(ll.y), bfhi(hh.y) + bfhi(ll.y),
;                                    bflo(hh.z) + bflo(ll.z), bfhi(hh.z) + bfhi(ll.z), bflo(hh.w) + bflo(ll.w), bfhi(hh.w) + bfhi(ll.w)};
;                     float av[8] = {acc[ai][bj][m][0][0], acc[ai][bj][m][0][1], acc[ai][bj][m][0][2], acc[ai][bj][m][0][3], acc[ai][bj][m][1][0], acc[ai][bj][m][1][1], acc[ai][bj][m][1][2], acc[ai][bj][m][1][3]};
;                     if (GATED) { const u32x4 pp = *(const u32x4*)(PP + off);
;                         const float pv[8] = {bflo(pp.x), bfhi(pp.x), bflo(pp.y), bfhi(pp.y), bflo(pp.z), bfhi(pp.z), bflo(pp.w), bfhi(pp.w)};
; #pragma unroll
;                         for (int e = 0; e < 8; ++e) av[e] = fast_sigmoid(av[e] * rs) * pv[e]; }
;                     else {
; #pragma unroll
;                         for (int e = 0; e < 8; ++e) av[e] *= alpha; }
;                     float lo[8];
; #pragma unroll
;                     for (int e = 0; e < 8; ++e) { hv[e] += av[e]; sq += hv[e] * hv[e]; }
;                     u32x4 wh; wh.x = pk2(hv[0], hv[1]); wh.y = pk2(hv[2], hv[3]); wh.z = pk2(hv[4], hv[5]); wh.w = pk2(hv[6], hv[7]);
;                     lo[0] = hv[0] - bflo(wh.x); lo[1] = hv[1] - bfhi(wh.x); lo[2] = hv[2] - bflo(wh.y); lo[3] = hv[3] - bfhi(wh.y);
;                     lo[4] = hv[4] - bflo(wh.z); lo[5] = hv[5] - bfhi(wh.z); lo[6] = hv[6] - bflo(wh.w); lo[7] = hv[7] - bfhi(wh.w);
;                     u32x4 wl; wl.x = pk2(lo[0], lo[1]); wl.y = pk2(lo[2], lo[3]); wl.z = pk2(lo[4], lo[5]); wl.w = pk2(lo[6], lo[7]);
;                     *(u32x4*)(HO + off) = wh; *(u32x4*)(LO + off) = wl;
	v_lshlrev_b32_e32 v156, 16, v180
	v_and_b32_e32 v157, 0xffff0000, v180
	v_lshlrev_b32_e32 v158, 16, v184
	v_and_b32_e32 v159, 0xffff0000, v184
	v_pk_add_f32 v[156:157], v[156:157], v[158:159]
	v_pk_add_f32 v[156:157], v[46:47], v[156:157]
	v_cvt_pk_bf16_f32 v180, v156, v157
	v_pk_mul_f32 v[198:199], v[156:157], v[156:157]
	v_lshlrev_b32_e32 v158, 16, v180
	v_and_b32_e32 v159, 0xffff0000, v180
	v_pk_add_f32 v[196:197], v[156:157], v[158:159] neg_lo:[0,1] neg_hi:[0,1]
	v_cvt_pk_bf16_f32 v184, v196, v197
	v_lshlrev_b32_e32 v156, 16, v181
	v_and_b32_e32 v157, 0xffff0000, v181
	v_lshlrev_b32_e32 v158, 16, v185
	v_and_b32_e32 v159, 0xffff0000, v185
	v_pk_add_f32 v[156:157], v[156:157], v[158:159]
	v_pk_add_f32 v[156:157], v[48:49], v[156:157]
	v_cvt_pk_bf16_f32 v181, v156, v157
	v_pk_fma_f32 v[198:199], v[156:157], v[156:157], v[198:199]
	v_lshlrev_b32_e32 v158, 16, v181
	v_and_b32_e32 v159, 0xffff0000, v181
	v_pk_add_f32 v[196:197], v[156:157], v[158:159] neg_lo:[0,1] neg_hi:[0,1]
	v_cvt_pk_bf16_f32 v185, v196, v197
	v_lshlrev_b32_e32 v156, 16, v182
	v_and_b32_e32 v157, 0xffff0000, v182
	v_lshlrev_b32_e32 v158, 16, v186
	v_and_b32_e32 v159, 0xffff0000, v186
	v_pk_add_f32 v[156:157], v[156:157], v[158:159]
	v_pk_add_f32 v[156:157], v[42:43], v[156:157]
	v_cvt_pk_bf16_f32 v182, v156, v157
	v_pk_fma_f32 v[198:199], v[156:157], v[156:157], v[198:199]
	v_lshlrev_b32_e32 v158, 16, v182
	v_and_b32_e32 v159, 0xffff0000, v182
	v_pk_add_f32 v[196:197], v[156:157], v[158:159] neg_lo:[0,1] neg_hi:[0,1]
	v_cvt_pk_bf16_f32 v186, v196, v197
	v_lshlrev_b32_e32 v156, 16, v183
	v_and_b32_e32 v157, 0xffff0000, v183
	v_lshlrev_b32_e32 v158, 16, v187
	v_and_b32_e32 v159, 0xffff0000, v187
	v_pk_add_f32 v[156:157], v[156:157], v[158:159]
	v_pk_add_f32 v[156:157], v[44:45], v[156:157]
	v_cvt_pk_bf16_f32 v183, v156, v157
	v_pk_fma_f32 v[198:199], v[156:157], v[156:157], v[198:199]
	v_lshlrev_b32_e32 v158, 16, v183
	v_and_b32_e32 v159, 0xffff0000, v183
	v_pk_add_f32 v[196:197], v[156:157], v[158:159] neg_lo:[0,1] neg_hi:[0,1]
	v_cvt_pk_bf16_f32 v187, v196, v197
	global_store_dwordx4 v212, v[180:183], s[10:11]
	global_store_dwordx4 v212, v[184:187], s[14:15]
	s_waitcnt vmcnt(18)
	v_lshlrev_b32_e32 v156, 16, v188
	v_and_b32_e32 v157, 0xffff0000, v188
	v_lshlrev_b32_e32 v158, 16, v192
	v_and_b32_e32 v159, 0xffff0000, v192
	v_pk_add_f32 v[156:157], v[156:157], v[158:159]
	v_pk_add_f32 v[156:157], v[38:39], v[156:157]
	v_cvt_pk_bf16_f32 v188, v156, v157
	v_pk_fma_f32 v[198:199], v[156:157], v[156:157], v[198:199]
	v_lshlrev_b32_e32 v158, 16, v188
	v_and_b32_e32 v159, 0xffff0000, v188
	v_pk_add_f32 v[196:197], v[156:157], v[158:159] neg_lo:[0,1] neg_hi:[0,1]
	v_cvt_pk_bf16_f32 v192, v196, v197
	v_lshlrev_b32_e32 v156, 16, v189
	v_and_b32_e32 v157, 0xffff0000, v189
	v_lshlrev_b32_e32 v158, 16, v193
	v_and_b32_e32 v159, 0xffff0000, v193
	v_pk_add_f32 v[156:157], v[156:157], v[158:159]
	v_pk_add_f32 v[156:157], v[40:41], v[156:157]
	v_cvt_pk_bf16_f32 v189, v156, v157
	v_pk_fma_f32 v[198:199], v[156:157], v[156:157], v[198:199]
	v_lshlrev_b32_e32 v158, 16, v189
	v_and_b32_e32 v159, 0xffff0000, v189
	v_pk_add_f32 v[196:197], v[156:157], v[158:159] neg_lo:[0,1] neg_hi:[0,1]
	v_cvt_pk_bf16_f32 v193, v196, v197
	v_lshlrev_b32_e32 v156, 16, v190
	v_and_b32_e32 v157, 0xffff0000, v190
	v_lshlrev_b32_e32 v158, 16, v194
	v_and_b32_e32 v159, 0xffff0000, v194
	v_pk_add_f32 v[156:157], v[156:157], v[158:159]
	v_pk_add_f32 v[156:157], v[34:35], v[156:157]
	v_cvt_pk_bf16_f32 v190, v156, v157
	v_pk_fma_f32 v[198:199], v[156:157], v[156:157], v[198:199]
	v_lshlrev_b32_e32 v158, 16, v190
	v_and_b32_e32 v159, 0xffff0000, v190
	v_pk_add_f32 v[196:197], v[156:157], v[158:159] neg_lo:[0,1] neg_hi:[0,1]
	v_cvt_pk_bf16_f32 v194, v196, v197
	v_lshlrev_b32_e32 v156, 16, v191
	v_and_b32_e32 v157, 0xffff0000, v191
	v_lshlrev_b32_e32 v158, 16, v195
	v_and_b32_e32 v159, 0xffff0000, v195
	v_pk_add_f32 v[156:157], v[156:157], v[158:159]
	v_pk_add_f32 v[156:157], v[36:37], v[156:157]
	v_cvt_pk_bf16_f32 v191, v156, v157
	v_pk_fma_f32 v[198:199], v[156:157], v[156:157], v[198:199]
	v_lshlrev_b32_e32 v158, 16, v191
	v_and_b32_e32 v159, 0xffff0000, v191
	v_pk_add_f32 v[196:197], v[156:157], v[158:159] neg_lo:[0,1] neg_hi:[0,1]
	v_cvt_pk_bf16_f32 v195, v196, v197
	global_store_dwordx4 v212, v[188:191], s[10:11] offset:256
	global_store_dwordx4 v212, v[192:195], s[14:15] offset:256
	v_add_f32_e32 v207, v198, v199
	s_waitcnt vmcnt(14)
	v_lshlrev_b32_e32 v156, 16, v140
	v_and_b32_e32 v157, 0xffff0000, v140
	v_lshlrev_b32_e32 v158, 16, v144
	v_and_b32_e32 v159, 0xffff0000, v144
	v_pk_add_f32 v[156:157], v[156:157], v[158:159]
	v_pk_add_f32 v[156:157], v[30:31], v[156:157]
	v_cvt_pk_bf16_f32 v140, v156, v157
	v_pk_mul_f32 v[198:199], v[156:157], v[156:157]
	v_lshlrev_b32_e32 v158, 16, v140
	v_and_b32_e32 v159, 0xffff0000, v140
	v_pk_add_f32 v[196:197], v[156:157], v[158:159] neg_lo:[0,1] neg_hi:[0,1]
	v_cvt_pk_bf16_f32 v144, v196, v197
	v_lshlrev_b32_e32 v156, 16, v141
	v_and_b32_e32 v157, 0xffff0000, v141
	v_lshlrev_b32_e32 v158, 16, v145
	v_and_b32_e32 v159, 0xffff0000, v145
	v_pk_add_f32 v[156:157], v[156:157], v[158:159]
	v_pk_add_f32 v[156:157], v[32:33], v[156:157]
	v_cvt_pk_bf16_f32 v141, v156, v157
	v_pk_fma_f32 v[198:199], v[156:157], v[156:157], v[198:199]
	v_lshlrev_b32_e32 v158, 16, v141
	v_and_b32_e32 v159, 0xffff0000, v141
	v_pk_add_f32 v[196:197], v[156:157], v[158:159] neg_lo:[0,1] neg_hi:[0,1]
	v_cvt_pk_bf16_f32 v145, v196, v197
	v_lshlrev_b32_e32 v156, 16, v142
	v_and_b32_e32 v157, 0xffff0000, v142
	v_lshlrev_b32_e32 v158, 16, v146
	v_and_b32_e32 v159, 0xffff0000, v146
	v_pk_add_f32 v[156:157], v[156:157], v[158:159]
	v_pk_add_f32 v[156:157], v[26:27], v[156:157]
	v_cvt_pk_bf16_f32 v142, v156, v157
	v_pk_fma_f32 v[198:199], v[156:157], v[156:157], v[198:199]
	v_lshlrev_b32_e32 v158, 16, v142
	v_and_b32_e32 v159, 0xffff0000, v142
	v_pk_add_f32 v[196:197], v[156:157], v[158:159] neg_lo:[0,1] neg_hi:[0,1]
	v_cvt_pk_bf16_f32 v146, v196, v197
	v_lshlrev_b32_e32 v156, 16, v143
	v_and_b32_e32 v157, 0xffff0000, v143
	v_lshlrev_b32_e32 v158, 16, v147
	v_and_b32_e32 v159, 0xffff0000, v147
	v_pk_add_f32 v[156:157], v[156:157], v[158:159]
	v_pk_add_f32 v[156:157], v[28:29], v[156:157]
	v_cvt_pk_bf16_f32 v143, v156, v157
	v_pk_fma_f32 v[198:199], v[156:157], v[156:157], v[198:199]
	v_lshlrev_b32_e32 v158, 16, v143
	v_and_b32_e32 v159, 0xffff0000, v143
	v_pk_add_f32 v[196:197], v[156:157], v[158:159] neg_lo:[0,1] neg_hi:[0,1]
	v_cvt_pk_bf16_f32 v147, v196, v197
	global_store_dwordx4 v210, v[140:143], s[10:11]
	global_store_dwordx4 v210, v[144:147], s[14:15]
	s_waitcnt vmcnt(14)
; __device__ __forceinline__ unsigned pk2(float lo, float hi) { f32x2_t v = {lo, hi}; bf16x2_t b = __builtin_convertvector(v, bf16x2_t); return __builtin_bit_cast(unsigned, b); }
; __device__ __forceinline__ float bflo(unsigned u) { return __uint_as_float(u << 16); }
; __device__ __forceinline__ float bfhi(unsigned u) { return __uint_as_float(u & 0xffff0000u); }
;     __device__ __forceinline__ void operator()(const f32x4 (&acc)[2][2][4][2], const Unit& u, int wr, int wc, int fr, int fq) const {
;     ...
;                     const size_t off = (size_t)row * DM + col0 + bj * HALF;
;                     const u32x4 hh = *(const u32x4*)(HI + off), ll = *(const u32x4*)(LO + off);
;                     float hv[8] = {bflo(hh.x) + bflo(ll.x), bfhi(hh.x) + bfhi(ll.x), bflo(hh.y) + bflo(ll.y), bfhi(hh.y) + bfhi(ll.y),
;                                    bflo(hh.z) + bflo(ll.z), bfhi(hh.z) + bfhi(ll.z), bflo(hh.w) + bflo(ll.w), bfhi(hh.w) + bfhi(ll.w)};
;                     float av[8] = {acc[ai][bj][m][0][0], acc[ai][bj][m][0][1], acc[ai][bj][m][0][2], acc[ai][bj][m][0][3], acc[ai][bj][m][1][0], acc[ai][bj][m][1][1], acc[ai][bj][m][1][2], acc[ai][bj][m][1][3]};
;                     if (GATED) { const u32x4 pp = *(const u32x4*)(PP + off);
;                         const float pv[8] = {bflo(pp.x), bfhi(pp.x), bflo(pp.y), bfhi(pp.y), bflo(pp.z), bfhi(pp.z), bflo(pp.w), bfhi(pp.w)};
; #pragma unroll
;                         for (int e = 0; e < 8; ++e) av[e] = fast_sigmoid(av[e] * rs) * pv[e]; }
;                     else {
; #pragma unroll
;                         for (int e = 0; e < 8; ++e) av[e] *= alpha; }
;                     float lo[8];
; #pragma unroll
;                     for (int e = 0; e < 8; ++e) { hv[e] += av[e]; sq += hv[e] * hv[e]; }
;                     u32x4 wh; wh.x = pk2(hv[0], hv[1]); wh.y = pk2(hv[2], hv[3]); wh.z = pk2(hv[4], hv[5]); wh.w = pk2(hv[6], hv[7]);
;                     lo[0] = hv[0] - bflo(wh.x); lo[1] = hv[1] - bfhi(wh.x); lo[2] = hv[2] - bflo(wh.y); lo[3] = hv[3] - bfhi(wh.y);
;                     lo[4] = hv[4] - bflo(wh.z); lo[5] = hv[5] - bfhi(wh.z); lo[6] = hv[6] - bflo(wh.w); lo[7] = hv[7] - bfhi(wh.w);
;                     u32x4 wl; wl.x = pk2(lo[0], lo[1]); wl.y = pk2(lo[2], lo[3]); wl.z = pk2(lo[4], lo[5]); wl.w = pk2(lo[6], lo[7]);
;                     *(u32x4*)(HO + off) = wh; *(u32x4*)(LO + off) = wl;
	v_lshlrev_b32_e32 v156, 16, v148
	v_and_b32_e32 v157, 0xffff0000, v148
	v_lshlrev_b32_e32 v158, 16, v152
	v_and_b32_e32 v159, 0xffff0000, v152
	v_pk_add_f32 v[156:157], v[156:157], v[158:159]
	v_pk_add_f32 v[156:157], v[22:23], v[156:157]
	v_cvt_pk_bf16_f32 v148, v156, v157
	v_pk_fma_f32 v[198:199], v[156:157], v[156:157], v[198:199]
	v_lshlrev_b32_e32 v158, 16, v148
	v_and_b32_e32 v159, 0xffff0000, v148
	v_pk_add_f32 v[196:197], v[156:157], v[158:159] neg_lo:[0,1] neg_hi:[0,1]
	v_cvt_pk_bf16_f32 v152, v196, v197
	v_lshlrev_b32_e32 v156, 16, v149
	v_and_b32_e32 v157, 0xffff0000, v149
	v_lshlrev_b32_e32 v158, 16, v153
	v_and_b32_e32 v159, 0xffff0000, v153
	v_pk_add_f32 v[156:157], v[156:157], v[158:159]
	v_pk_add_f32 v[156:157], v[24:25], v[156:157]
	v_cvt_pk_bf16_f32 v149, v156, v157
	v_pk_fma_f32 v[198:199], v[156:157], v[156:157], v[198:199]
	v_lshlrev_b32_e32 v158, 16, v149
	v_and_b32_e32 v159, 0xffff0000, v149
	v_pk_add_f32 v[196:197], v[156:157], v[158:159] neg_lo:[0,1] neg_hi:[0,1]
	v_cvt_pk_bf16_f32 v153, v196, v197
	v_lshlrev_b32_e32 v156, 16, v150
	v_and_b32_e32 v157, 0xffff0000, v150
	v_lshlrev_b32_e32 v158, 16, v154
	v_and_b32_e32 v159, 0xffff0000, v154
	v_pk_add_f32 v[156:157], v[156:157], v[158:159]
	v_pk_add_f32 v[156:157], v[18:19], v[156:157]
	v_cvt_pk_bf16_f32 v150, v156, v157
	v_pk_fma_f32 v[198:199], v[156:157], v[156:157], v[198:199]
	v_lshlrev_b32_e32 v158, 16, v150
	v_and_b32_e32 v159, 0xffff0000, v150
	v_pk_add_f32 v[196:197], v[156:157], v[158:159] neg_lo:[0,1] neg_hi:[0,1]
	v_cvt_pk_bf16_f32 v154, v196, v197
	v_lshlrev_b32_e32 v156, 16, v151
	v_and_b32_e32 v157, 0xffff0000, v151
	v_lshlrev_b32_e32 v158, 16, v155
	v_and_b32_e32 v159, 0xffff0000, v155
	v_pk_add_f32 v[156:157], v[156:157], v[158:159]
	v_pk_add_f32 v[156:157], v[20:21], v[156:157]
	v_cvt_pk_bf16_f32 v151, v156, v157
	v_pk_fma_f32 v[198:199], v[156:157], v[156:157], v[198:199]
	v_lshlrev_b32_e32 v158, 16, v151
	v_and_b32_e32 v159, 0xffff0000, v151
	v_pk_add_f32 v[196:197], v[156:157], v[158:159] neg_lo:[0,1] neg_hi:[0,1]
	v_cvt_pk_bf16_f32 v155, v196, v197
	global_store_dwordx4 v210, v[148:151], s[10:11] offset:256
	global_store_dwordx4 v210, v[152:155], s[14:15] offset:256
	v_add_f32_e32 v208, v198, v199
	s_waitcnt vmcnt(10)
	v_lshlrev_b32_e32 v156, 16, v164
	v_and_b32_e32 v157, 0xffff0000, v164
	v_lshlrev_b32_e32 v158, 16, v168
	v_and_b32_e32 v159, 0xffff0000, v168
	v_pk_add_f32 v[156:157], v[156:157], v[158:159]
	v_pk_add_f32 v[156:157], v[14:15], v[156:157]
	v_cvt_pk_bf16_f32 v164, v156, v157
	v_pk_mul_f32 v[198:199], v[156:157], v[156:157]
	v_lshlrev_b32_e32 v158, 16, v164
	v_and_b32_e32 v159, 0xffff0000, v164
	v_pk_add_f32 v[196:197], v[156:157], v[158:159] neg_lo:[0,1] neg_hi:[0,1]
	v_cvt_pk_bf16_f32 v168, v196, v197
	v_lshlrev_b32_e32 v156, 16, v165
	v_and_b32_e32 v157, 0xffff0000, v165
	v_lshlrev_b32_e32 v158, 16, v169
	v_and_b32_e32 v159, 0xffff0000, v169
	v_pk_add_f32 v[156:157], v[156:157], v[158:159]
	v_pk_add_f32 v[156:157], v[16:17], v[156:157]
	v_cvt_pk_bf16_f32 v165, v156, v157
	v_pk_fma_f32 v[198:199], v[156:157], v[156:157], v[198:199]
	v_lshlrev_b32_e32 v158, 16, v165
	v_and_b32_e32 v159, 0xffff0000, v165
	v_pk_add_f32 v[196:197], v[156:157], v[158:159] neg_lo:[0,1] neg_hi:[0,1]
	v_cvt_pk_bf16_f32 v169, v196, v197
	v_lshlrev_b32_e32 v156, 16, v166
	v_and_b32_e32 v157, 0xffff0000, v166
	v_lshlrev_b32_e32 v158, 16, v170
	v_and_b32_e32 v159, 0xffff0000, v170
	v_pk_add_f32 v[156:157], v[156:157], v[158:159]
	v_pk_add_f32 v[156:157], v[10:11], v[156:157]
	v_cvt_pk_bf16_f32 v166, v156, v157
	v_pk_fma_f32 v[198:199], v[156:157], v[156:157], v[198:199]
	v_lshlrev_b32_e32 v158, 16, v166
	v_and_b32_e32 v159, 0xffff0000, v166
	v_pk_add_f32 v[196:197], v[156:157], v[158:159] neg_lo:[0,1] neg_hi:[0,1]
	v_cvt_pk_bf16_f32 v170, v196, v197
	v_lshlrev_b32_e32 v156, 16, v167
	v_and_b32_e32 v157, 0xffff0000, v167
	v_lshlrev_b32_e32 v158, 16, v171
	v_and_b32_e32 v159, 0xffff0000, v171
	v_pk_add_f32 v[156:157], v[156:157], v[158:159]
	v_pk_add_f32 v[156:157], v[12:13], v[156:157]
	v_cvt_pk_bf16_f32 v167, v156, v157
	v_pk_fma_f32 v[198:199], v[156:157], v[156:157], v[198:199]
	v_lshlrev_b32_e32 v158, 16, v167
	v_and_b32_e32 v159, 0xffff0000, v167
	v_pk_add_f32 v[196:197], v[156:157], v[158:159] neg_lo:[0,1] neg_hi:[0,1]
	v_cvt_pk_bf16_f32 v171, v196, v197
	global_store_dwordx4 v211, v[164:167], s[10:11]
	global_store_dwordx4 v211, v[168:171], s[14:15]
	s_waitcnt vmcnt(10)
; __device__ __forceinline__ unsigned pk2(float lo, float hi) { f32x2_t v = {lo, hi}; bf16x2_t b = __builtin_convertvector(v, bf16x2_t); return __builtin_bit_cast(unsigned, b); }
;     __device__ __forceinline__ void operator()(const f32x4 (&acc)[2][2][4][2], const Unit& u, int wr, int wc, int fr, int fq) const {
;     ...
;                     const size_t off = (size_t)row * DM + col0 + bj * HALF;
;                     const u32x4 hh = *(const u32x4*)(HI + off), ll = *(const u32x4*)(LO + off);
;                     float hv[8] = {bflo(hh.x) + bflo(ll.x), bfhi(hh.x) + bfhi(ll.x), bflo(hh.y) + bflo(ll.y), bfhi(hh.y) + bfhi(ll.y),
;                                    bflo(hh.z) + bflo(ll.z), bfhi(hh.z) + bfhi(ll.z), bflo(hh.w) + bflo(ll.w), bfhi(hh.w) + bfhi(ll.w)};
;                     float av[8] = {acc[ai][bj][m][0][0], acc[ai][bj][m][0][1], acc[ai][bj][m][0][2], acc[ai][bj][m][0][3], acc[ai][bj][m][1][0], acc[ai][bj][m][1][1], acc[ai][bj][m][1][2], acc[ai][bj][m][1][3]};
;                     if (GATED) { const u32x4 pp = *(const u32x4*)(PP + off);
;                         const float pv[8] = {bflo(pp.x), bfhi(pp.x), bflo(pp.y), bfhi(pp.y), bflo(pp.z), bfhi(pp.z), bflo(pp.w), bfhi(pp.w)};
; #pragma unroll
;                         for (int e = 0; e < 8; ++e) av[e] = fast_sigmoid(av[e] * rs) * pv[e]; }
;                     else {
; #pragma unroll
;                         for (int e = 0; e < 8; ++e) av[e] *= alpha; }
;                     float lo[8];
; #pragma unroll
;                     for (int e = 0; e < 8; ++e) { hv[e] += av[e]; sq += hv[e] * hv[e]; }
;                     u32x4 wh; wh.x = pk2(hv[0], hv[1]); wh.y = pk2(hv[2], hv[3]); wh.z = pk2(hv[4], hv[5]); wh.w = pk2(hv[6], hv[7]);
;                     lo[0] = hv[0] - bflo(wh.x); lo[1] = hv[1] - bfhi(wh.x); lo[2] = hv[2] - bflo(wh.y); lo[3] = hv[3] - bfhi(wh.y);
;                     lo[4] = hv[4] - bflo(wh.z); lo[5] = hv[5] - bfhi(wh.z); lo[6] = hv[6] - bflo(wh.w); lo[7] = hv[7] - bfhi(wh.w);
;                     u32x4 wl; wl.x = pk2(lo[0], lo[1]); wl.y = pk2(lo[2], lo[3]); wl.z = pk2(lo[4], lo[5]); wl.w = pk2(lo[6], lo[7]);
;                     *(u32x4*)(HO + off) = wh; *(u32x4*)(LO + off) = wl;
;                 }
;                 sq += __shfl_xor(sq, 16); sq += __shfl_xor(sq, 32);
;                 if (fq == 0) ssq_out[(size_t)row * 16 + 4 * u.pn + wc] = sq;
	v_lshlrev_b32_e32 v156, 16, v172
	v_and_b32_e32 v157, 0xffff0000, v172
	v_lshlrev_b32_e32 v158, 16, v176
	v_and_b32_e32 v159, 0xffff0000, v176
	v_pk_add_f32 v[156:157], v[156:157], v[158:159]
	v_pk_add_f32 v[156:157], v[6:7], v[156:157]
	v_cvt_pk_bf16_f32 v172, v156, v157
	v_pk_fma_f32 v[198:199], v[156:157], v[156:157], v[198:199]
	v_lshlrev_b32_e32 v158, 16, v172
	v_and_b32_e32 v159, 0xffff0000, v172
	v_pk_add_f32 v[196:197], v[156:157], v[158:159] neg_lo:[0,1] neg_hi:[0,1]
	v_cvt_pk_bf16_f32 v176, v196, v197
	v_lshlrev_b32_e32 v156, 16, v173
	v_and_b32_e32 v157, 0xffff0000, v173
	v_lshlrev_b32_e32 v158, 16, v177
	v_and_b32_e32 v159, 0xffff0000, v177
	v_pk_add_f32 v[156:157], v[156:157], v[158:159]
	v_pk_add_f32 v[156:157], v[8:9], v[156:157]
	v_cvt_pk_bf16_f32 v173, v156, v157
	v_pk_fma_f32 v[198:199], v[156:157], v[156:157], v[198:199]
	v_lshlrev_b32_e32 v158, 16, v173
	v_and_b32_e32 v159, 0xffff0000, v173
	v_pk_add_f32 v[196:197], v[156:157], v[158:159] neg_lo:[0,1] neg_hi:[0,1]
	v_cvt_pk_bf16_f32 v177, v196, v197
	v_lshlrev_b32_e32 v156, 16, v174
	v_and_b32_e32 v157, 0xffff0000, v174
	v_lshlrev_b32_e32 v158, 16, v178
	v_and_b32_e32 v159, 0xffff0000, v178
	v_pk_add_f32 v[156:157], v[156:157], v[158:159]
	v_pk_add_f32 v[156:157], v[2:3], v[156:157]
	v_cvt_pk_bf16_f32 v174, v156, v157
	v_pk_fma_f32 v[198:199], v[156:157], v[156:157], v[198:199]
	v_lshlrev_b32_e32 v158, 16, v174
	v_and_b32_e32 v159, 0xffff0000, v174
	v_pk_add_f32 v[196:197], v[156:157], v[158:159] neg_lo:[0,1] neg_hi:[0,1]
	v_cvt_pk_bf16_f32 v178, v196, v197
	v_lshlrev_b32_e32 v156, 16, v175
	v_and_b32_e32 v157, 0xffff0000, v175
	v_lshlrev_b32_e32 v158, 16, v179
	v_and_b32_e32 v159, 0xffff0000, v179
	v_pk_add_f32 v[156:157], v[156:157], v[158:159]
	v_pk_add_f32 v[156:157], v[4:5], v[156:157]
	v_cvt_pk_bf16_f32 v175, v156, v157
	v_pk_fma_f32 v[198:199], v[156:157], v[156:157], v[198:199]
	v_lshlrev_b32_e32 v158, 16, v175
	v_and_b32_e32 v159, 0xffff0000, v175
	v_pk_add_f32 v[196:197], v[156:157], v[158:159] neg_lo:[0,1] neg_hi:[0,1]
	v_cvt_pk_bf16_f32 v179, v196, v197
	global_store_dwordx4 v211, v[172:175], s[10:11] offset:256
	global_store_dwordx4 v211, v[176:179], s[14:15] offset:256
	v_add_f32_e32 v209, v198, v199
	ds_bpermute_b32 v140, v214, v200
	ds_bpermute_b32 v141, v214, v201
	ds_bpermute_b32 v142, v214, v202
	ds_bpermute_b32 v143, v214, v203
	ds_bpermute_b32 v144, v214, v206
	ds_bpermute_b32 v145, v214, v207
	ds_bpermute_b32 v146, v214, v208
	ds_bpermute_b32 v147, v214, v209
	s_waitcnt lgkmcnt(0)
	v_add_f32_e32 v200, v200, v140
	v_add_f32_e32 v201, v201, v141
	v_add_f32_e32 v202, v202, v142
	v_add_f32_e32 v203, v203, v143
	v_add_f32_e32 v206, v206, v144
	v_add_f32_e32 v207, v207, v145
	v_add_f32_e32 v208, v208, v146
	v_add_f32_e32 v209, v209, v147
	ds_bpermute_b32 v140, v215, v200
	ds_bpermute_b32 v141, v215, v201
	ds_bpermute_b32 v142, v215, v202
	ds_bpermute_b32 v143, v215, v203
	ds_bpermute_b32 v144, v215, v206
	ds_bpermute_b32 v145, v215, v207
	ds_bpermute_b32 v146, v215, v208
	ds_bpermute_b32 v147, v215, v209
	s_waitcnt lgkmcnt(0)
	v_add_f32_e32 v200, v200, v140
	v_add_f32_e32 v201, v201, v141
	v_add_f32_e32 v202, v202, v142
	v_add_f32_e32 v203, v203, v143
	v_add_f32_e32 v206, v206, v144
	v_add_f32_e32 v207, v207, v145
	v_add_f32_e32 v208, v208, v146
	v_add_f32_e32 v209, v209, v147
	s_and_saveexec_b64 s[26:27], s[44:45]
	s_cbranch_execz .Lepir_wout_skip
	global_store_dword v216, v200, s[16:17]
	global_store_dword v216, v201, s[16:17] offset:1024
	global_store_dword v216, v202, s[16:17] offset:2048
	global_store_dword v216, v203, s[16:17] offset:3072
	global_store_dword v217, v206, s[16:17]
	global_store_dword v217, v207, s[16:17] offset:1024
	global_store_dword v217, v208, s[16:17] offset:2048
	global_store_dword v217, v209, s[16:17] offset:3072

; __device__ __forceinline__ float bflo(unsigned u) { return __uint_as_float(u << 16); }
;     __device__ __forceinline__ void operator()(const f32x4 (&acc)[2][2][4][2], const Unit& u, int wr, int wc, int fr, int fq) const {
;         const int row0 = u.pm * BM + wr * 64 + fr, col0 = u.pn * BM + wc * 32 + 8 * fq;
; #pragma unroll
;         for (int ai = 0; ai < 2; ++ai)
; #pragma unroll
;             for (int m = 0; m < 4; ++m) {
;                 const int row = row0 + ai * HALF + m * 16;
;                 float rs = 0.f; if (GATED) rs = rsqrtf(row_ssq(ssq_in, 16, 4, row, fq) * (1.f / 1024.f) + EPS);
;                 float sq = 0.f;
; #pragma unroll
;                 for (int bj = 0; bj < 2; ++bj) {
;                     const size_t off = (size_t)row * DM + col0 + bj * HALF;
;                     const u32x4 hh = *(const u32x4*)(HI + off), ll = *(const u32x4*)(LO + off);
;                     float hv[8] = {bflo(hh.x) + bflo(ll.x), bfhi(hh.x) + bfhi(ll.x), bflo(hh.y) + bflo(ll.y), bfhi(hh.y) + bfhi(ll.y),
;                                    bflo(hh.z) + bflo(ll.z), bfhi(hh.z) + bfhi(ll.z), bflo(hh.w) + bflo(ll.w), bfhi(hh.w) + bfhi(ll.w)};
;                     float av[8] = {acc[ai][bj][m][0][0], acc[ai][bj][m][0][1], acc[ai][bj][m][0][2], acc[ai][bj][m][0][3], acc[ai][bj][m][1][0], acc[ai][bj][m][1][1], acc[ai][bj][m][1][2], acc[ai][bj][m][1][3]};
;                     if (GATED) { const u32x4 pp = *(const u32x4*)(PP + off);
;                         const float pv[8] = {bflo(pp.x), bfhi(pp.x), bflo(pp.y), bfhi(pp.y), bflo(pp.z), bfhi(pp.z), bflo(pp.w), bfhi(pp.w)};
; #pragma unroll
;                         for (int e = 0; e < 8; ++e) av[e] = fast_sigmoid(av[e] * rs) * pv[e]; }
;                     else {
; #pragma unroll
;                         for (int e = 0; e < 8; ++e) av[e] *= alpha; }
;                     float lo[8];
; #pragma unroll
;                     for (int e = 0; e < 8; ++e) { hv[e] += av[e]; sq += hv[e] * hv[e]; }
;                     u32x4 wh; wh.x = pk2(hv[0], hv[1]); wh.y = pk2(hv[2], hv[3]); wh.z = pk2(hv[4], hv[5]); wh.w = pk2(hv[6], hv[7]);
;                     lo[0] = hv[0] - bflo(wh.x); lo[1] = hv[1] - bfhi(wh.x); lo[2] = hv[2] - bflo(wh.y); lo[3] = hv[3] - bfhi(wh.y);
;                     lo[4] = hv[4] - bflo(wh.z); lo[5] = hv[5] - bfhi(wh.z); lo[6] = hv[6] - bflo(wh.w); lo[7] = hv[7] - bfhi(wh.w);
.LBB0_1250:
	v_and_b32_e32 v158, 64, v241
	v_xor_b32_e32 v214, 16, v241
	v_add_u32_e32 v158, 64, v158
	v_cmp_lt_i32_e32 vcc, v214, v158
	v_lshl_add_u32 v156, s31, 8, v160
	v_lshl_or_b32 v157, s4, 8, v162
	v_cndmask_b32_e32 v214, v241, v214, vcc
	v_lshlrev_b32_e32 v214, 2, v214
	v_xor_b32_e32 v215, 32, v241
	v_cmp_lt_i32_e32 vcc, v215, v158
	v_readlane_b32 s10, v253, 35
	v_readlane_b32 s11, v253, 36
	v_readlane_b32 s6, v250, 49
	v_readlane_b32 s7, v250, 50
	s_nop 1
	v_cndmask_b32_e32 v215, v241, v215, vcc
	v_lshlrev_b32_e32 v215, 2, v215
	v_lshl_add_u32 v213, v156, 10, v157
	v_lshlrev_b32_e32 v213, 1, v213
	s_lshl_b32 s40, s4, 4
	s_lshl_b32 s50, s25, 2
	s_add_i32 s40, s40, s50
	v_lshlrev_b32_e32 v216, 6, v156
	v_add_u32_e32 v216, s40, v216
	v_add_u32_e32 v217, 0x2000, v216
	s_nop 1
	v_mov_b32_e32 v210, v213
	global_load_dwordx4 v[140:143], v210, s[10:11]
	global_load_dwordx4 v[144:147], v210, s[6:7]
	global_load_dwordx4 v[148:151], v210, s[10:11] offset:256
	global_load_dwordx4 v[152:155], v210, s[6:7] offset:256
	v_add_u32_e32 v211, 0x8000, v213
	global_load_dwordx4 v[164:167], v211, s[10:11]
	global_load_dwordx4 v[168:171], v211, s[6:7]
	global_load_dwordx4 v[172:175], v211, s[10:11] offset:256
	global_load_dwordx4 v[176:179], v211, s[6:7] offset:256
	v_add_u32_e32 v212, 0x10000, v213
	global_load_dwordx4 v[180:183], v212, s[10:11]
	global_load_dwordx4 v[184:187], v212, s[6:7]
	global_load_dwordx4 v[188:191], v212, s[10:11] offset:256
	global_load_dwordx4 v[192:195], v212, s[6:7] offset:256
	s_waitcnt vmcnt(10)
	v_lshlrev_b32_e32 v156, 16, v140
	v_and_b32_e32 v157, 0xffff0000, v140
	v_lshlrev_b32_e32 v158, 16, v144
	v_and_b32_e32 v159, 0xffff0000, v144
	v_pk_add_f32 v[156:157], v[156:157], v[158:159]
	v_pk_fma_f32 v[156:157], v[126:127], 0.5, v[156:157] op_sel_hi:[1,0,1]
	v_cvt_pk_bf16_f32 v140, v156, v157
	v_pk_mul_f32 v[198:199], v[156:157], v[156:157]
	v_lshlrev_b32_e32 v158, 16, v140
	v_and_b32_e32 v159, 0xffff0000, v140
	v_pk_add_f32 v[196:197], v[156:157], v[158:159] neg_lo:[0,1] neg_hi:[0,1]
	v_cvt_pk_bf16_f32 v144, v196, v197
	v_lshlrev_b32_e32 v156, 16, v141
	v_and_b32_e32 v157, 0xffff0000, v141
	v_lshlrev_b32_e32 v158, 16, v145
	v_and_b32_e32 v159, 0xffff0000, v145
	v_pk_add_f32 v[156:157], v[156:157], v[158:159]
	v_pk_fma_f32 v[156:157], v[128:129], 0.5, v[156:157] op_sel_hi:[1,0,1]
	v_cvt_pk_bf16_f32 v141, v156, v157
	v_pk_fma_f32 v[198:199], v[156:157], v[156:157], v[198:199]
	v_lshlrev_b32_e32 v158, 16, v141
	v_and_b32_e32 v159, 0xffff0000, v141
	v_pk_add_f32 v[196:197], v[156:157], v[158:159] neg_lo:[0,1] neg_hi:[0,1]
	v_cvt_pk_bf16_f32 v145, v196, v197
	v_lshlrev_b32_e32 v156, 16, v142
	v_and_b32_e32 v157, 0xffff0000, v142
	v_lshlrev_b32_e32 v158, 16, v146
	v_and_b32_e32 v159, 0xffff0000, v146
	v_pk_add_f32 v[156:157], v[156:157], v[158:159]
	v_pk_fma_f32 v[156:157], v[122:123], 0.5, v[156:157] op_sel_hi:[1,0,1]
	v_cvt_pk_bf16_f32 v142, v156, v157
	v_pk_fma_f32 v[198:199], v[156:157], v[156:157], v[198:199]
	v_lshlrev_b32_e32 v158, 16, v142
	v_and_b32_e32 v159, 0xffff0000, v142
	v_pk_add_f32 v[196:197], v[156:157], v[158:159] neg_lo:[0,1] neg_hi:[0,1]
	v_cvt_pk_bf16_f32 v146, v196, v197
	v_lshlrev_b32_e32 v156, 16, v143
	v_and_b32_e32 v157, 0xffff0000, v143
	v_lshlrev_b32_e32 v158, 16, v147
	v_and_b32_e32 v159, 0xffff0000, v147
	v_pk_add_f32 v[156:157], v[156:157], v[158:159]
	v_pk_fma_f32 v[156:157], v[124:125], 0.5, v[156:157] op_sel_hi:[1,0,1]
	v_cvt_pk_bf16_f32 v143, v156, v157
	v_pk_fma_f32 v[198:199], v[156:157], v[156:157], v[198:199]
	v_lshlrev_b32_e32 v158, 16, v143
	v_and_b32_e32 v159, 0xffff0000, v143
	v_pk_add_f32 v[196:197], v[156:157], v[158:159] neg_lo:[0,1] neg_hi:[0,1]
	v_cvt_pk_bf16_f32 v147, v196, v197
	global_store_dwordx4 v210, v[140:143], s[10:11]
	global_store_dwordx4 v210, v[144:147], s[6:7]
	s_waitcnt vmcnt(10)
	v_lshlrev_b32_e32 v156, 16, v148
	v_and_b32_e32 v157, 0xffff0000, v148
	v_lshlrev_b32_e32 v158, 16, v152
	v_and_b32_e32 v159, 0xffff0000, v152
	v_pk_add_f32 v[156:157], v[156:157], v[158:159]
	v_pk_fma_f32 v[156:157], v[118:119], 0.5, v[156:157] op_sel_hi:[1,0,1]
	v_cvt_pk_bf16_f32 v148, v156, v157
	v_pk_fma_f32 v[198:199], v[156:157], v[156:157], v[198:199]
	v_lshlrev_b32_e32 v158, 16, v148
	v_and_b32_e32 v159, 0xffff0000, v148
	v_pk_add_f32 v[196:197], v[156:157], v[158:159] neg_lo:[0,1] neg_hi:[0,1]
	v_cvt_pk_bf16_f32 v152, v196, v197
	v_lshlrev_b32_e32 v156, 16, v149
	v_and_b32_e32 v157, 0xffff0000, v149
	v_lshlrev_b32_e32 v158, 16, v153
	v_and_b32_e32 v159, 0xffff0000, v153
	v_pk_add_f32 v[156:157], v[156:157], v[158:159]
	v_pk_fma_f32 v[156:157], v[120:121], 0.5, v[156:157] op_sel_hi:[1,0,1]
	v_cvt_pk_bf16_f32 v149, v156, v157
	v_pk_fma_f32 v[198:199], v[156:157], v[156:157], v[198:199]
	v_lshlrev_b32_e32 v158, 16, v149
	v_and_b32_e32 v159, 0xffff0000, v149
	v_pk_add_f32 v[196:197], v[156:157], v[158:159] neg_lo:[0,1] neg_hi:[0,1]
	v_cvt_pk_bf16_f32 v153, v196, v197
	v_lshlrev_b32_e32 v156, 16, v150
	v_and_b32_e32 v157, 0xffff0000, v150
	v_lshlrev_b32_e32 v158, 16, v154
	v_and_b32_e32 v159, 0xffff0000, v154
	v_pk_add_f32 v[156:157], v[156:157], v[158:159]
	v_pk_fma_f32 v[156:157], v[114:115], 0.5, v[156:157] op_sel_hi:[1,0,1]
	v_cvt_pk_bf16_f32 v150, v156, v157
	v_pk_fma_f32 v[198:199], v[156:157], v[156:157], v[198:199]
	v_lshlrev_b32_e32 v158, 16, v150
	v_and_b32_e32 v159, 0xffff0000, v150
	v_pk_add_f32 v[196:197], v[156:157], v[158:159] neg_lo:[0,1] neg_hi:[0,1]
	v_cvt_pk_bf16_f32 v154, v196, v197
	v_lshlrev_b32_e32 v156, 16, v151
	v_and_b32_e32 v157, 0xffff0000, v151
	v_lshlrev_b32_e32 v158, 16, v155
	v_and_b32_e32 v159, 0xffff0000, v155
	v_pk_add_f32 v[156:157], v[156:157], v[158:159]
	v_pk_fma_f32 v[156:157], v[116:117], 0.5, v[156:157] op_sel_hi:[1,0,1]
	v_cvt_pk_bf16_f32 v151, v156, v157
	v_pk_fma_f32 v[198:199], v[156:157], v[156:157], v[198:199]
	v_lshlrev_b32_e32 v158, 16, v151
	v_and_b32_e32 v159, 0xffff0000, v151
	v_pk_add_f32 v[196:197], v[156:157], v[158:159] neg_lo:[0,1] neg_hi:[0,1]
	v_cvt_pk_bf16_f32 v155, v196, v197
	global_store_dwordx4 v210, v[148:151], s[10:11] offset:256
	global_store_dwordx4 v210, v[152:155], s[6:7] offset:256
	v_add_f32_e32 v200, v198, v199
	s_nop 0
	v_add_u32_e32 v210, 0x18000, v213
	global_load_dwordx4 v[140:143], v210, s[10:11]
	global_load_dwordx4 v[144:147], v210, s[6:7]
	global_load_dwordx4 v[148:151], v210, s[10:11] offset:256
	global_load_dwordx4 v[152:155], v210, s[6:7] offset:256
	s_waitcnt vmcnt(14)
; __device__ __forceinline__ unsigned pk2(float lo, float hi) { f32x2_t v = {lo, hi}; bf16x2_t b = __builtin_convertvector(v, bf16x2_t); return __builtin_bit_cast(unsigned, b); }
; __device__ __forceinline__ float bflo(unsigned u) { return __uint_as_float(u << 16); }
; __device__ __forceinline__ float bfhi(unsigned u) { return __uint_as_float(u & 0xffff0000u); }
;     __device__ __forceinline__ void operator()(const f32x4 (&acc)[2][2][4][2], const Unit& u, int wr, int wc, int fr, int fq) const {
;     ...
;                     const size_t off = (size_t)row * DM + col0 + bj * HALF;
;                     const u32x4 hh = *(const u32x4*)(HI + off), ll = *(const u32x4*)(LO + off);
;                     float hv[8] = {bflo(hh.x) + bflo(ll.x), bfhi(hh.x) + bfhi(ll.x), bflo(hh.y) + bflo(ll.y), bfhi(hh.y) + bfhi(ll.y),
;                                    bflo(hh.z) + bflo(ll.z), bfhi(hh.z) + bfhi(ll.z), bflo(hh.w) + bflo(ll.w), bfhi(hh.w) + bfhi(ll.w)};
;                     float av[8] = {acc[ai][bj][m][0][0], acc[ai][bj][m][0][1], acc[ai][bj][m][0][2], acc[ai][bj][m][0][3], acc[ai][bj][m][1][0], acc[ai][bj][m][1][1], acc[ai][bj][m][1][2], acc[ai][bj][m][1][3]};
;                     if (GATED) { const u32x4 pp = *(const u32x4*)(PP + off);
;                         const float pv[8] = {bflo(pp.x), bfhi(pp.x), bflo(pp.y), bfhi(pp.y), bflo(pp.z), bfhi(pp.z), bflo(pp.w), bfhi(pp.w)};
; #pragma unroll
;                         for (int e = 0; e < 8; ++e) av[e] = fast_sigmoid(av[e] * rs) * pv[e]; }
;                     else {
; #pragma unroll
;                         for (int e = 0; e < 8; ++e) av[e] *= alpha; }
;                     float lo[8];
; #pragma unroll
;                     for (int e = 0; e < 8; ++e) { hv[e] += av[e]; sq += hv[e] * hv[e]; }
;                     u32x4 wh; wh.x = pk2(hv[0], hv[1]); wh.y = pk2(hv[2], hv[3]); wh.z = pk2(hv[4], hv[5]); wh.w = pk2(hv[6], hv[7]);
;                     lo[0] = hv[0] - bflo(wh.x); lo[1] = hv[1] - bfhi(wh.x); lo[2] = hv[2] - bflo(wh.y); lo[3] = hv[3] - bfhi(wh.y);
;                     lo[4] = hv[4] - bflo(wh.z); lo[5] = hv[5] - bfhi(wh.z); lo[6] = hv[6] - bflo(wh.w); lo[7] = hv[7] - bfhi(wh.w);
;                     u32x4 wl; wl.x = pk2(lo[0], lo[1]); wl.y = pk2(lo[2], lo[3]); wl.z = pk2(lo[4], lo[5]); wl.w = pk2(lo[6], lo[7]);
;                     *(u32x4*)(HO + off) = wh; *(u32x4*)(LO + off) = wl;
	v_lshlrev_b32_e32 v156, 16, v164
	v_and_b32_e32 v157, 0xffff0000, v164
	v_lshlrev_b32_e32 v158, 16, v168
	v_and_b32_e32 v159, 0xffff0000, v168
	v_pk_add_f32 v[156:157], v[156:157], v[158:159]
	v_pk_fma_f32 v[156:157], v[110:111], 0.5, v[156:157] op_sel_hi:[1,0,1]
	v_cvt_pk_bf16_f32 v164, v156, v157
	v_pk_mul_f32 v[198:199], v[156:157], v[156:157]
	v_lshlrev_b32_e32 v158, 16, v164
	v_and_b32_e32 v159, 0xffff0000, v164
	v_pk_add_f32 v[196:197], v[156:157], v[158:159] neg_lo:[0,1] neg_hi:[0,1]
	v_cvt_pk_bf16_f32 v168, v196, v197
	v_lshlrev_b32_e32 v156, 16, v165
	v_and_b32_e32 v157, 0xffff0000, v165
	v_lshlrev_b32_e32 v158, 16, v169
	v_and_b32_e32 v159, 0xffff0000, v169
	v_pk_add_f32 v[156:157], v[156:157], v[158:159]
	v_pk_fma_f32 v[156:157], v[112:113], 0.5, v[156:157] op_sel_hi:[1,0,1]
	v_cvt_pk_bf16_f32 v165, v156, v157
	v_pk_fma_f32 v[198:199], v[156:157], v[156:157], v[198:199]
	v_lshlrev_b32_e32 v158, 16, v165
	v_and_b32_e32 v159, 0xffff0000, v165
	v_pk_add_f32 v[196:197], v[156:157], v[158:159] neg_lo:[0,1] neg_hi:[0,1]
	v_cvt_pk_bf16_f32 v169, v196, v197
	v_lshlrev_b32_e32 v156, 16, v166
	v_and_b32_e32 v157, 0xffff0000, v166
	v_lshlrev_b32_e32 v158, 16, v170
	v_and_b32_e32 v159, 0xffff0000, v170
	v_pk_add_f32 v[156:157], v[156:157], v[158:159]
	v_pk_fma_f32 v[156:157], v[106:107], 0.5, v[156:157] op_sel_hi:[1,0,1]
	v_cvt_pk_bf16_f32 v166, v156, v157
	v_pk_fma_f32 v[198:199], v[156:157], v[156:157], v[198:199]
	v_lshlrev_b32_e32 v158, 16, v166
	v_and_b32_e32 v159, 0xffff0000, v166
	v_pk_add_f32 v[196:197], v[156:157], v[158:159] neg_lo:[0,1] neg_hi:[0,1]
	v_cvt_pk_bf16_f32 v170, v196, v197
	v_lshlrev_b32_e32 v156, 16, v167
	v_and_b32_e32 v157, 0xffff0000, v167
	v_lshlrev_b32_e32 v158, 16, v171
	v_and_b32_e32 v159, 0xffff0000, v171
	v_pk_add_f32 v[156:157], v[156:157], v[158:159]
	v_pk_fma_f32 v[156:157], v[108:109], 0.5, v[156:157] op_sel_hi:[1,0,1]
	v_cvt_pk_bf16_f32 v167, v156, v157
	v_pk_fma_f32 v[198:199], v[156:157], v[156:157], v[198:199]
	v_lshlrev_b32_e32 v158, 16, v167
	v_and_b32_e32 v159, 0xffff0000, v167
	v_pk_add_f32 v[196:197], v[156:157], v[158:159] neg_lo:[0,1] neg_hi:[0,1]
	v_cvt_pk_bf16_f32 v171, v196, v197
	global_store_dwordx4 v211, v[164:167], s[10:11]
	global_store_dwordx4 v211, v[168:171], s[6:7]
	s_waitcnt vmcnt(14)
	v_lshlrev_b32_e32 v156, 16, v172
	v_and_b32_e32 v157, 0xffff0000, v172
	v_lshlrev_b32_e32 v158, 16, v176
	v_and_b32_e32 v159, 0xffff0000, v176
	v_pk_add_f32 v[156:157], v[156:157], v[158:159]
	v_pk_fma_f32 v[156:157], v[102:103], 0.5, v[156:157] op_sel_hi:[1,0,1]
	v_cvt_pk_bf16_f32 v172, v156, v157
	v_pk_fma_f32 v[198:199], v[156:157], v[156:157], v[198:199]
	v_lshlrev_b32_e32 v158, 16, v172
	v_and_b32_e32 v159, 0xffff0000, v172
	v_pk_add_f32 v[196:197], v[156:157], v[158:159] neg_lo:[0,1] neg_hi:[0,1]
	v_cvt_pk_bf16_f32 v176, v196, v197
	v_lshlrev_b32_e32 v156, 16, v173
	v_and_b32_e32 v157, 0xffff0000, v173
	v_lshlrev_b32_e32 v158, 16, v177
	v_and_b32_e32 v159, 0xffff0000, v177
	v_pk_add_f32 v[156:157], v[156:157], v[158:159]
	v_pk_fma_f32 v[156:157], v[104:105], 0.5, v[156:157] op_sel_hi:[1,0,1]
	v_cvt_pk_bf16_f32 v173, v156, v157
	v_pk_fma_f32 v[198:199], v[156:157], v[156:157], v[198:199]
	v_lshlrev_b32_e32 v158, 16, v173
	v_and_b32_e32 v159, 0xffff0000, v173
	v_pk_add_f32 v[196:197], v[156:157], v[158:159] neg_lo:[0,1] neg_hi:[0,1]
	v_cvt_pk_bf16_f32 v177, v196, v197
	v_lshlrev_b32_e32 v156, 16, v174
	v_and_b32_e32 v157, 0xffff0000, v174
	v_lshlrev_b32_e32 v158, 16, v178
	v_and_b32_e32 v159, 0xffff0000, v178
	v_pk_add_f32 v[156:157], v[156:157], v[158:159]
	v_pk_fma_f32 v[156:157], v[98:99], 0.5, v[156:157] op_sel_hi:[1,0,1]
	v_cvt_pk_bf16_f32 v174, v156, v157
	v_pk_fma_f32 v[198:199], v[156:157], v[156:157], v[198:199]
	v_lshlrev_b32_e32 v158, 16, v174
	v_and_b32_e32 v159, 0xffff0000, v174
	v_pk_add_f32 v[196:197], v[156:157], v[158:159] neg_lo:[0,1] neg_hi:[0,1]
	v_cvt_pk_bf16_f32 v178, v196, v197
	v_lshlrev_b32_e32 v156, 16, v175
	v_and_b32_e32 v157, 0xffff0000, v175
	v_lshlrev_b32_e32 v158, 16, v179
	v_and_b32_e32 v159, 0xffff0000, v179
	v_pk_add_f32 v[156:157], v[156:157], v[158:159]
	v_pk_fma_f32 v[156:157], v[100:101], 0.5, v[156:157] op_sel_hi:[1,0,1]
	v_cvt_pk_bf16_f32 v175, v156, v157
	v_pk_fma_f32 v[198:199], v[156:157], v[156:157], v[198:199]
	v_lshlrev_b32_e32 v158, 16, v175
	v_and_b32_e32 v159, 0xffff0000, v175
	v_pk_add_f32 v[196:197], v[156:157], v[158:159] neg_lo:[0,1] neg_hi:[0,1]
	v_cvt_pk_bf16_f32 v179, v196, v197
	global_store_dwordx4 v211, v[172:175], s[10:11] offset:256
	global_store_dwordx4 v211, v[176:179], s[6:7] offset:256
	v_add_f32_e32 v201, v198, v199
	s_nop 0
	v_add_u32_e32 v211, 0x40000, v213
	global_load_dwordx4 v[164:167], v211, s[10:11]
	global_load_dwordx4 v[168:171], v211, s[6:7]
	global_load_dwordx4 v[172:175], v211, s[10:11] offset:256
	global_load_dwordx4 v[176:179], v211, s[6:7] offset:256
	s_waitcnt vmcnt(18)
; __device__ __forceinline__ unsigned pk2(float lo, float hi) { f32x2_t v = {lo, hi}; bf16x2_t b = __builtin_convertvector(v, bf16x2_t); return __builtin_bit_cast(unsigned, b); }
; __device__ __forceinline__ float bflo(unsigned u) { return __uint_as_float(u << 16); }
; __device__ __forceinline__ float bfhi(unsigned u) { return __uint_as_float(u & 0xffff0000u); }
;     __device__ __forceinline__ void operator()(const f32x4 (&acc)[2][2][4][2], const Unit& u, int wr, int wc, int fr, int fq) const {
;     ...
;                     const size_t off = (size_t)row * DM + col0 + bj * HALF;
;                     const u32x4 hh = *(const u32x4*)(HI + off), ll = *(const u32x4*)(LO + off);
;                     float hv[8] = {bflo(hh.x) + bflo(ll.x), bfhi(hh.x) + bfhi(ll.x), bflo(hh.y) + bflo(ll.y), bfhi(hh.y) + bfhi(ll.y),
;                                    bflo(hh.z) + bflo(ll.z), bfhi(hh.z) + bfhi(ll.z), bflo(hh.w) + bflo(ll.w), bfhi(hh.w) + bfhi(ll.w)};
;                     float av[8] = {acc[ai][bj][m][0][0], acc[ai][bj][m][0][1], acc[ai][bj][m][0][2], acc[ai][bj][m][0][3], acc[ai][bj][m][1][0], acc[ai][bj][m][1][1], acc[ai][bj][m][1][2], acc[ai][bj][m][1][3]};
;                     if (GATED) { const u32x4 pp = *(const u32x4*)(PP + off);
;                         const float pv[8] = {bflo(pp.x), bfhi(pp.x), bflo(pp.y), bfhi(pp.y), bflo(pp.z), bfhi(pp.z), bflo(pp.w), bfhi(pp.w)};
; #pragma unroll
;                         for (int e = 0; e < 8; ++e) av[e] = fast_sigmoid(av[e] * rs) * pv[e]; }
;                     else {
; #pragma unroll
;                         for (int e = 0; e < 8; ++e) av[e] *= alpha; }
;                     float lo[8];
; #pragma unroll
;                     for (int e = 0; e < 8; ++e) { hv[e] += av[e]; sq += hv[e] * hv[e]; }
;                     u32x4 wh; wh.x = pk2(hv[0], hv[1]); wh.y = pk2(hv[2], hv[3]); wh.z = pk2(hv[4], hv[5]); wh.w = pk2(hv[6], hv[7]);
;                     lo[0] = hv[0] - bflo(wh.x); lo[1] = hv[1] - bfhi(wh.x); lo[2] = hv[2] - bflo(wh.y); lo[3] = hv[3] - bfhi(wh.y);
;                     lo[4] = hv[4] - bflo(wh.z); lo[5] = hv[5] - bfhi(wh.z); lo[6] = hv[6] - bflo(wh.w); lo[7] = hv[7] - bfhi(wh.w);
;                     u32x4 wl; wl.x = pk2(lo[0], lo[1]); wl.y = pk2(lo[2], lo[3]); wl.z = pk2(lo[4], lo[5]); wl.w = pk2(lo[6], lo[7]);
;                     *(u32x4*)(HO + off) = wh; *(u32x4*)(LO + off) = wl;
	v_lshlrev_b32_e32 v156, 16, v180
	v_and_b32_e32 v157, 0xffff0000, v180
	v_lshlrev_b32_e32 v158, 16, v184
	v_and_b32_e32 v159, 0xffff0000, v184
	v_pk_add_f32 v[156:157], v[156:157], v[158:159]
	v_pk_fma_f32 v[156:157], v[94:95], 0.5, v[156:157] op_sel_hi:[1,0,1]
	v_cvt_pk_bf16_f32 v180, v156, v157
	v_pk_mul_f32 v[198:199], v[156:157], v[156:157]
	v_lshlrev_b32_e32 v158, 16, v180
	v_and_b32_e32 v159, 0xffff0000, v180
	v_pk_add_f32 v[196:197], v[156:157], v[158:159] neg_lo:[0,1] neg_hi:[0,1]
	v_cvt_pk_bf16_f32 v184, v196, v197
	v_lshlrev_b32_e32 v156, 16, v181
	v_and_b32_e32 v157, 0xffff0000, v181
	v_lshlrev_b32_e32 v158, 16, v185
	v_and_b32_e32 v159, 0xffff0000, v185
	v_pk_add_f32 v[156:157], v[156:157], v[158:159]
	v_pk_fma_f32 v[156:157], v[96:97], 0.5, v[156:157] op_sel_hi:[1,0,1]
	v_cvt_pk_bf16_f32 v181, v156, v157
	v_pk_fma_f32 v[198:199], v[156:157], v[156:157], v[198:199]
	v_lshlrev_b32_e32 v158, 16, v181
	v_and_b32_e32 v159, 0xffff0000, v181
	v_pk_add_f32 v[196:197], v[156:157], v[158:159] neg_lo:[0,1] neg_hi:[0,1]
	v_cvt_pk_bf16_f32 v185, v196, v197
	v_lshlrev_b32_e32 v156, 16, v182
	v_and_b32_e32 v157, 0xffff0000, v182
	v_lshlrev_b32_e32 v158, 16, v186
	v_and_b32_e32 v159, 0xffff0000, v186
	v_pk_add_f32 v[156:157], v[156:157], v[158:159]
	v_pk_fma_f32 v[156:157], v[90:91], 0.5, v[156:157] op_sel_hi:[1,0,1]
	v_cvt_pk_bf16_f32 v182, v156, v157
	v_pk_fma_f32 v[198:199], v[156:157], v[156:157], v[198:199]
	v_lshlrev_b32_e32 v158, 16, v182
	v_and_b32_e32 v159, 0xffff0000, v182
	v_pk_add_f32 v[196:197], v[156:157], v[158:159] neg_lo:[0,1] neg_hi:[0,1]
	v_cvt_pk_bf16_f32 v186, v196, v197
	v_lshlrev_b32_e32 v156, 16, v183
	v_and_b32_e32 v157, 0xffff0000, v183
	v_lshlrev_b32_e32 v158, 16, v187
	v_and_b32_e32 v159, 0xffff0000, v187
	v_pk_add_f32 v[156:157], v[156:157], v[158:159]
	v_pk_fma_f32 v[156:157], v[92:93], 0.5, v[156:157] op_sel_hi:[1,0,1]
	v_cvt_pk_bf16_f32 v183, v156, v157
	v_pk_fma_f32 v[198:199], v[156:157], v[156:157], v[198:199]
	v_lshlrev_b32_e32 v158, 16, v183
	v_and_b32_e32 v159, 0xffff0000, v183
	v_pk_add_f32 v[196:197], v[156:157], v[158:159] neg_lo:[0,1] neg_hi:[0,1]
	v_cvt_pk_bf16_f32 v187, v196, v197
	global_store_dwordx4 v212, v[180:183], s[10:11]
	global_store_dwordx4 v212, v[184:187], s[6:7]
	s_waitcnt vmcnt(18)
	v_lshlrev_b32_e32 v156, 16, v188
	v_and_b32_e32 v157, 0xffff0000, v188
	v_lshlrev_b32_e32 v158, 16, v192
	v_and_b32_e32 v159, 0xffff0000, v192
	v_pk_add_f32 v[156:157], v[156:157], v[158:159]
	v_pk_fma_f32 v[156:157], v[86:87], 0.5, v[156:157] op_sel_hi:[1,0,1]
	v_cvt_pk_bf16_f32 v188, v156, v157
	v_pk_fma_f32 v[198:199], v[156:157], v[156:157], v[198:199]
	v_lshlrev_b32_e32 v158, 16, v188
	v_and_b32_e32 v159, 0xffff0000, v188
	v_pk_add_f32 v[196:197], v[156:157], v[158:159] neg_lo:[0,1] neg_hi:[0,1]
	v_cvt_pk_bf16_f32 v192, v196, v197
	v_lshlrev_b32_e32 v156, 16, v189
	v_and_b32_e32 v157, 0xffff0000, v189
	v_lshlrev_b32_e32 v158, 16, v193
	v_and_b32_e32 v159, 0xffff0000, v193
	v_pk_add_f32 v[156:157], v[156:157], v[158:159]
	v_pk_fma_f32 v[156:157], v[88:89], 0.5, v[156:157] op_sel_hi:[1,0,1]
	v_cvt_pk_bf16_f32 v189, v156, v157
	v_pk_fma_f32 v[198:199], v[156:157], v[156:157], v[198:199]
	v_lshlrev_b32_e32 v158, 16, v189
	v_and_b32_e32 v159, 0xffff0000, v189
	v_pk_add_f32 v[196:197], v[156:157], v[158:159] neg_lo:[0,1] neg_hi:[0,1]
	v_cvt_pk_bf16_f32 v193, v196, v197
	v_lshlrev_b32_e32 v156, 16, v190
	v_and_b32_e32 v157, 0xffff0000, v190
	v_lshlrev_b32_e32 v158, 16, v194
	v_and_b32_e32 v159, 0xffff0000, v194
	v_pk_add_f32 v[156:157], v[156:157], v[158:159]
	v_pk_fma_f32 v[156:157], v[82:83], 0.5, v[156:157] op_sel_hi:[1,0,1]
	v_cvt_pk_bf16_f32 v190, v156, v157
	v_pk_fma_f32 v[198:199], v[156:157], v[156:157], v[198:199]
	v_lshlrev_b32_e32 v158, 16, v190
	v_and_b32_e32 v159, 0xffff0000, v190
	v_pk_add_f32 v[196:197], v[156:157], v[158:159] neg_lo:[0,1] neg_hi:[0,1]
	v_cvt_pk_bf16_f32 v194, v196, v197
	v_lshlrev_b32_e32 v156, 16, v191
	v_and_b32_e32 v157, 0xffff0000, v191
	v_lshlrev_b32_e32 v158, 16, v195
	v_and_b32_e32 v159, 0xffff0000, v195
	v_pk_add_f32 v[156:157], v[156:157], v[158:159]
	v_pk_fma_f32 v[156:157], v[84:85], 0.5, v[156:157] op_sel_hi:[1,0,1]
	v_cvt_pk_bf16_f32 v191, v156, v157
	v_pk_fma_f32 v[198:199], v[156:157], v[156:157], v[198:199]
	v_lshlrev_b32_e32 v158, 16, v191
	v_and_b32_e32 v159, 0xffff0000, v191
	v_pk_add_f32 v[196:197], v[156:157], v[158:159] neg_lo:[0,1] neg_hi:[0,1]
	v_cvt_pk_bf16_f32 v195, v196, v197
	global_store_dwordx4 v212, v[188:191], s[10:11] offset:256
	global_store_dwordx4 v212, v[192:195], s[6:7] offset:256
	v_add_f32_e32 v202, v198, v199
	s_nop 0
	v_add_u32_e32 v212, 0x48000, v213
	global_load_dwordx4 v[180:183], v212, s[10:11]
	global_load_dwordx4 v[184:187], v212, s[6:7]
	global_load_dwordx4 v[188:191], v212, s[10:11] offset:256
	global_load_dwordx4 v[192:195], v212, s[6:7] offset:256
	s_waitcnt vmcnt(18)
; __device__ __forceinline__ unsigned pk2(float lo, float hi) { f32x2_t v = {lo, hi}; bf16x2_t b = __builtin_convertvector(v, bf16x2_t); return __builtin_bit_cast(unsigned, b); }
; __device__ __forceinline__ float bflo(unsigned u) { return __uint_as_float(u << 16); }
; __device__ __forceinline__ float bfhi(unsigned u) { return __uint_as_float(u & 0xffff0000u); }
;     __device__ __forceinline__ void operator()(const f32x4 (&acc)[2][2][4][2], const Unit& u, int wr, int wc, int fr, int fq) const {
;     ...
;                     const size_t off = (size_t)row * DM + col0 + bj * HALF;
;                     const u32x4 hh = *(const u32x4*)(HI + off), ll = *(const u32x4*)(LO + off);
;                     float hv[8] = {bflo(hh.x) + bflo(ll.x), bfhi(hh.x) + bfhi(ll.x), bflo(hh.y) + bflo(ll.y), bfhi(hh.y) + bfhi(ll.y),
;                                    bflo(hh.z) + bflo(ll.z), bfhi(hh.z) + bfhi(ll.z), bflo(hh.w) + bflo(ll.w), bfhi(hh.w) + bfhi(ll.w)};
;                     float av[8] = {acc[ai][bj][m][0][0], acc[ai][bj][m][0][1], acc[ai][bj][m][0][2], acc[ai][bj][m][0][3], acc[ai][bj][m][1][0], acc[ai][bj][m][1][1], acc[ai][bj][m][1][2], acc[ai][bj][m][1][3]};
;                     if (GATED) { const u32x4 pp = *(const u32x4*)(PP + off);
;                         const float pv[8] = {bflo(pp.x), bfhi(pp.x), bflo(pp.y), bfhi(pp.y), bflo(pp.z), bfhi(pp.z), bflo(pp.w), bfhi(pp.w)};
; #pragma unroll
;                         for (int e = 0; e < 8; ++e) av[e] = fast_sigmoid(av[e] * rs) * pv[e]; }
;                     else {
; #pragma unroll
;                         for (int e = 0; e < 8; ++e) av[e] *= alpha; }
;                     float lo[8];
; #pragma unroll
;                     for (int e = 0; e < 8; ++e) { hv[e] += av[e]; sq += hv[e] * hv[e]; }
;                     u32x4 wh; wh.x = pk2(hv[0], hv[1]); wh.y = pk2(hv[2], hv[3]); wh.z = pk2(hv[4], hv[5]); wh.w = pk2(hv[6], hv[7]);
;                     lo[0] = hv[0] - bflo(wh.x); lo[1] = hv[1] - bfhi(wh.x); lo[2] = hv[2] - bflo(wh.y); lo[3] = hv[3] - bfhi(wh.y);
;                     lo[4] = hv[4] - bflo(wh.z); lo[5] = hv[5] - bfhi(wh.z); lo[6] = hv[6] - bflo(wh.w); lo[7] = hv[7] - bfhi(wh.w);
;                     u32x4 wl; wl.x = pk2(lo[0], lo[1]); wl.y = pk2(lo[2], lo[3]); wl.z = pk2(lo[4], lo[5]); wl.w = pk2(lo[6], lo[7]);
;                     *(u32x4*)(HO + off) = wh; *(u32x4*)(LO + off) = wl;
	v_lshlrev_b32_e32 v156, 16, v140
	v_and_b32_e32 v157, 0xffff0000, v140
	v_lshlrev_b32_e32 v158, 16, v144
	v_and_b32_e32 v159, 0xffff0000, v144
	v_pk_add_f32 v[156:157], v[156:157], v[158:159]
	v_pk_fma_f32 v[156:157], v[78:79], 0.5, v[156:157] op_sel_hi:[1,0,1]
	v_cvt_pk_bf16_f32 v140, v156, v157
	v_pk_mul_f32 v[198:199], v[156:157], v[156:157]
	v_lshlrev_b32_e32 v158, 16, v140
	v_and_b32_e32 v159, 0xffff0000, v140
	v_pk_add_f32 v[196:197], v[156:157], v[158:159] neg_lo:[0,1] neg_hi:[0,1]
	v_cvt_pk_bf16_f32 v144, v196, v197
	v_lshlrev_b32_e32 v156, 16, v141
	v_and_b32_e32 v157, 0xffff0000, v141
	v_lshlrev_b32_e32 v158, 16, v145
	v_and_b32_e32 v159, 0xffff0000, v145
	v_pk_add_f32 v[156:157], v[156:157], v[158:159]
	v_pk_fma_f32 v[156:157], v[80:81], 0.5, v[156:157] op_sel_hi:[1,0,1]
	v_cvt_pk_bf16_f32 v141, v156, v157
	v_pk_fma_f32 v[198:199], v[156:157], v[156:157], v[198:199]
	v_lshlrev_b32_e32 v158, 16, v141
	v_and_b32_e32 v159, 0xffff0000, v141
	v_pk_add_f32 v[196:197], v[156:157], v[158:159] neg_lo:[0,1] neg_hi:[0,1]
	v_cvt_pk_bf16_f32 v145, v196, v197
	v_lshlrev_b32_e32 v156, 16, v142
	v_and_b32_e32 v157, 0xffff0000, v142
	v_lshlrev_b32_e32 v158, 16, v146
	v_and_b32_e32 v159, 0xffff0000, v146
	v_pk_add_f32 v[156:157], v[156:157], v[158:159]
	v_pk_fma_f32 v[156:157], v[74:75], 0.5, v[156:157] op_sel_hi:[1,0,1]
	v_cvt_pk_bf16_f32 v142, v156, v157
	v_pk_fma_f32 v[198:199], v[156:157], v[156:157], v[198:199]
	v_lshlrev_b32_e32 v158, 16, v142
	v_and_b32_e32 v159, 0xffff0000, v142
	v_pk_add_f32 v[196:197], v[156:157], v[158:159] neg_lo:[0,1] neg_hi:[0,1]
	v_cvt_pk_bf16_f32 v146, v196, v197
	v_lshlrev_b32_e32 v156, 16, v143
	v_and_b32_e32 v157, 0xffff0000, v143
	v_lshlrev_b32_e32 v158, 16, v147
	v_and_b32_e32 v159, 0xffff0000, v147
	v_pk_add_f32 v[156:157], v[156:157], v[158:159]
	v_pk_fma_f32 v[156:157], v[76:77], 0.5, v[156:157] op_sel_hi:[1,0,1]
	v_cvt_pk_bf16_f32 v143, v156, v157
	v_pk_fma_f32 v[198:199], v[156:157], v[156:157], v[198:199]
	v_lshlrev_b32_e32 v158, 16, v143
	v_and_b32_e32 v159, 0xffff0000, v143
	v_pk_add_f32 v[196:197], v[156:157], v[158:159] neg_lo:[0,1] neg_hi:[0,1]
	v_cvt_pk_bf16_f32 v147, v196, v197
	global_store_dwordx4 v210, v[140:143], s[10:11]
	global_store_dwordx4 v210, v[144:147], s[6:7]
	s_waitcnt vmcnt(18)
	v_lshlrev_b32_e32 v156, 16, v148
	v_and_b32_e32 v157, 0xffff0000, v148
	v_lshlrev_b32_e32 v158, 16, v152
	v_and_b32_e32 v159, 0xffff0000, v152
	v_pk_add_f32 v[156:157], v[156:157], v[158:159]
	v_pk_fma_f32 v[156:157], v[70:71], 0.5, v[156:157] op_sel_hi:[1,0,1]
	v_cvt_pk_bf16_f32 v148, v156, v157
	v_pk_fma_f32 v[198:199], v[156:157], v[156:157], v[198:199]
	v_lshlrev_b32_e32 v158, 16, v148
	v_and_b32_e32 v159, 0xffff0000, v148
	v_pk_add_f32 v[196:197], v[156:157], v[158:159] neg_lo:[0,1] neg_hi:[0,1]
	v_cvt_pk_bf16_f32 v152, v196, v197
	v_lshlrev_b32_e32 v156, 16, v149
	v_and_b32_e32 v157, 0xffff0000, v149
	v_lshlrev_b32_e32 v158, 16, v153
	v_and_b32_e32 v159, 0xffff0000, v153
	v_pk_add_f32 v[156:157], v[156:157], v[158:159]
	v_pk_fma_f32 v[156:157], v[72:73], 0.5, v[156:157] op_sel_hi:[1,0,1]
	v_cvt_pk_bf16_f32 v149, v156, v157
	v_pk_fma_f32 v[198:199], v[156:157], v[156:157], v[198:199]
	v_lshlrev_b32_e32 v158, 16, v149
	v_and_b32_e32 v159, 0xffff0000, v149
	v_pk_add_f32 v[196:197], v[156:157], v[158:159] neg_lo:[0,1] neg_hi:[0,1]
	v_cvt_pk_bf16_f32 v153, v196, v197
	v_lshlrev_b32_e32 v156, 16, v150
	v_and_b32_e32 v157, 0xffff0000, v150
	v_lshlrev_b32_e32 v158, 16, v154
	v_and_b32_e32 v159, 0xffff0000, v154
	v_pk_add_f32 v[156:157], v[156:157], v[158:159]
	v_pk_fma_f32 v[156:157], v[66:67], 0.5, v[156:157] op_sel_hi:[1,0,1]
	v_cvt_pk_bf16_f32 v150, v156, v157
	v_pk_fma_f32 v[198:199], v[156:157], v[156:157], v[198:199]
	v_lshlrev_b32_e32 v158, 16, v150
	v_and_b32_e32 v159, 0xffff0000, v150
	v_pk_add_f32 v[196:197], v[156:157], v[158:159] neg_lo:[0,1] neg_hi:[0,1]
	v_cvt_pk_bf16_f32 v154, v196, v197
	v_lshlrev_b32_e32 v156, 16, v151
	v_and_b32_e32 v157, 0xffff0000, v151
	v_lshlrev_b32_e32 v158, 16, v155
	v_and_b32_e32 v159, 0xffff0000, v155
	v_pk_add_f32 v[156:157], v[156:157], v[158:159]
	v_pk_fma_f32 v[156:157], v[68:69], 0.5, v[156:157] op_sel_hi:[1,0,1]
	v_cvt_pk_bf16_f32 v151, v156, v157
	v_pk_fma_f32 v[198:199], v[156:157], v[156:157], v[198:199]
	v_lshlrev_b32_e32 v158, 16, v151
	v_and_b32_e32 v159, 0xffff0000, v151
	v_pk_add_f32 v[196:197], v[156:157], v[158:159] neg_lo:[0,1] neg_hi:[0,1]
	v_cvt_pk_bf16_f32 v155, v196, v197
	global_store_dwordx4 v210, v[148:151], s[10:11] offset:256
	global_store_dwordx4 v210, v[152:155], s[6:7] offset:256
	v_add_f32_e32 v203, v198, v199
	s_nop 0
	v_add_u32_e32 v210, 0x50000, v213
	global_load_dwordx4 v[140:143], v210, s[10:11]
	global_load_dwordx4 v[144:147], v210, s[6:7]
	global_load_dwordx4 v[148:151], v210, s[10:11] offset:256
	global_load_dwordx4 v[152:155], v210, s[6:7] offset:256
	s_waitcnt vmcnt(18)
; __device__ __forceinline__ unsigned pk2(float lo, float hi) { f32x2_t v = {lo, hi}; bf16x2_t b = __builtin_convertvector(v, bf16x2_t); return __builtin_bit_cast(unsigned, b); }
; __device__ __forceinline__ float bflo(unsigned u) { return __uint_as_float(u << 16); }
; __device__ __forceinline__ float bfhi(unsigned u) { return __uint_as_float(u & 0xffff0000u); }
;     __device__ __forceinline__ void operator()(const f32x4 (&acc)[2][2][4][2], const Unit& u, int wr, int wc, int fr, int fq) const {
;     ...
;                     const size_t off = (size_t)row * DM + col0 + bj * HALF;
;                     const u32x4 hh = *(const u32x4*)(HI + off), ll = *(const u32x4*)(LO + off);
;                     float hv[8] = {bflo(hh.x) + bflo(ll.x), bfhi(hh.x) + bfhi(ll.x), bflo(hh.y) + bflo(ll.y), bfhi(hh.y) + bfhi(ll.y),
;                                    bflo(hh.z) + bflo(ll.z), bfhi(hh.z) + bfhi(ll.z), bflo(hh.w) + bflo(ll.w), bfhi(hh.w) + bfhi(ll.w)};
;                     float av[8] = {acc[ai][bj][m][0][0], acc[ai][bj][m][0][1], acc[ai][bj][m][0][2], acc[ai][bj][m][0][3], acc[ai][bj][m][1][0], acc[ai][bj][m][1][1], acc[ai][bj][m][1][2], acc[ai][bj][m][1][3]};
;                     if (GATED) { const u32x4 pp = *(const u32x4*)(PP + off);
;                         const float pv[8] = {bflo(pp.x), bfhi(pp.x), bflo(pp.y), bfhi(pp.y), bflo(pp.z), bfhi(pp.z), bflo(pp.w), bfhi(pp.w)};
; #pragma unroll
;                         for (int e = 0; e < 8; ++e) av[e] = fast_sigmoid(av[e] * rs) * pv[e]; }
;                     else {
; #pragma unroll
;                         for (int e = 0; e < 8; ++e) av[e] *= alpha; }
;                     float lo[8];
; #pragma unroll
;                     for (int e = 0; e < 8; ++e) { hv[e] += av[e]; sq += hv[e] * hv[e]; }
;                     u32x4 wh; wh.x = pk2(hv[0], hv[1]); wh.y = pk2(hv[2], hv[3]); wh.z = pk2(hv[4], hv[5]); wh.w = pk2(hv[6], hv[7]);
;                     lo[0] = hv[0] - bflo(wh.x); lo[1] = hv[1] - bfhi(wh.x); lo[2] = hv[2] - bflo(wh.y); lo[3] = hv[3] - bfhi(wh.y);
;                     lo[4] = hv[4] - bflo(wh.z); lo[5] = hv[5] - bfhi(wh.z); lo[6] = hv[6] - bflo(wh.w); lo[7] = hv[7] - bfhi(wh.w);
;                     u32x4 wl; wl.x = pk2(lo[0], lo[1]); wl.y = pk2(lo[2], lo[3]); wl.z = pk2(lo[4], lo[5]); wl.w = pk2(lo[6], lo[7]);
;                     *(u32x4*)(HO + off) = wh; *(u32x4*)(LO + off) = wl;
	v_lshlrev_b32_e32 v156, 16, v164
	v_and_b32_e32 v157, 0xffff0000, v164
	v_lshlrev_b32_e32 v158, 16, v168
	v_and_b32_e32 v159, 0xffff0000, v168
	v_pk_add_f32 v[156:157], v[156:157], v[158:159]
	v_pk_fma_f32 v[156:157], v[62:63], 0.5, v[156:157] op_sel_hi:[1,0,1]
	v_cvt_pk_bf16_f32 v164, v156, v157
	v_pk_mul_f32 v[198:199], v[156:157], v[156:157]
	v_lshlrev_b32_e32 v158, 16, v164
	v_and_b32_e32 v159, 0xffff0000, v164
	v_pk_add_f32 v[196:197], v[156:157], v[158:159] neg_lo:[0,1] neg_hi:[0,1]
	v_cvt_pk_bf16_f32 v168, v196, v197
	v_lshlrev_b32_e32 v156, 16, v165
	v_and_b32_e32 v157, 0xffff0000, v165
	v_lshlrev_b32_e32 v158, 16, v169
	v_and_b32_e32 v159, 0xffff0000, v169
	v_pk_add_f32 v[156:157], v[156:157], v[158:159]
	v_pk_fma_f32 v[156:157], v[64:65], 0.5, v[156:157] op_sel_hi:[1,0,1]
	v_cvt_pk_bf16_f32 v165, v156, v157
	v_pk_fma_f32 v[198:199], v[156:157], v[156:157], v[198:199]
	v_lshlrev_b32_e32 v158, 16, v165
	v_and_b32_e32 v159, 0xffff0000, v165
	v_pk_add_f32 v[196:197], v[156:157], v[158:159] neg_lo:[0,1] neg_hi:[0,1]
	v_cvt_pk_bf16_f32 v169, v196, v197
	v_lshlrev_b32_e32 v156, 16, v166
	v_and_b32_e32 v157, 0xffff0000, v166
	v_lshlrev_b32_e32 v158, 16, v170
	v_and_b32_e32 v159, 0xffff0000, v170
	v_pk_add_f32 v[156:157], v[156:157], v[158:159]
	v_pk_fma_f32 v[156:157], v[58:59], 0.5, v[156:157] op_sel_hi:[1,0,1]
	v_cvt_pk_bf16_f32 v166, v156, v157
	v_pk_fma_f32 v[198:199], v[156:157], v[156:157], v[198:199]
	v_lshlrev_b32_e32 v158, 16, v166
	v_and_b32_e32 v159, 0xffff0000, v166
	v_pk_add_f32 v[196:197], v[156:157], v[158:159] neg_lo:[0,1] neg_hi:[0,1]
	v_cvt_pk_bf16_f32 v170, v196, v197
	v_lshlrev_b32_e32 v156, 16, v167
	v_and_b32_e32 v157, 0xffff0000, v167
	v_lshlrev_b32_e32 v158, 16, v171
	v_and_b32_e32 v159, 0xffff0000, v171
	v_pk_add_f32 v[156:157], v[156:157], v[158:159]
	v_pk_fma_f32 v[156:157], v[60:61], 0.5, v[156:157] op_sel_hi:[1,0,1]
	v_cvt_pk_bf16_f32 v167, v156, v157
	v_pk_fma_f32 v[198:199], v[156:157], v[156:157], v[198:199]
	v_lshlrev_b32_e32 v158, 16, v167
	v_and_b32_e32 v159, 0xffff0000, v167
	v_pk_add_f32 v[196:197], v[156:157], v[158:159] neg_lo:[0,1] neg_hi:[0,1]
	v_cvt_pk_bf16_f32 v171, v196, v197
	global_store_dwordx4 v211, v[164:167], s[10:11]
	global_store_dwordx4 v211, v[168:171], s[6:7]
	s_waitcnt vmcnt(18)
	v_lshlrev_b32_e32 v156, 16, v172
	v_and_b32_e32 v157, 0xffff0000, v172
	v_lshlrev_b32_e32 v158, 16, v176
	v_and_b32_e32 v159, 0xffff0000, v176
	v_pk_add_f32 v[156:157], v[156:157], v[158:159]
	v_pk_fma_f32 v[156:157], v[54:55], 0.5, v[156:157] op_sel_hi:[1,0,1]
	v_cvt_pk_bf16_f32 v172, v156, v157
	v_pk_fma_f32 v[198:199], v[156:157], v[156:157], v[198:199]
	v_lshlrev_b32_e32 v158, 16, v172
	v_and_b32_e32 v159, 0xffff0000, v172
	v_pk_add_f32 v[196:197], v[156:157], v[158:159] neg_lo:[0,1] neg_hi:[0,1]
	v_cvt_pk_bf16_f32 v176, v196, v197
	v_lshlrev_b32_e32 v156, 16, v173
	v_and_b32_e32 v157, 0xffff0000, v173
	v_lshlrev_b32_e32 v158, 16, v177
	v_and_b32_e32 v159, 0xffff0000, v177
	v_pk_add_f32 v[156:157], v[156:157], v[158:159]
	v_pk_fma_f32 v[156:157], v[56:57], 0.5, v[156:157] op_sel_hi:[1,0,1]
	v_cvt_pk_bf16_f32 v173, v156, v157
	v_pk_fma_f32 v[198:199], v[156:157], v[156:157], v[198:199]
	v_lshlrev_b32_e32 v158, 16, v173
	v_and_b32_e32 v159, 0xffff0000, v173
	v_pk_add_f32 v[196:197], v[156:157], v[158:159] neg_lo:[0,1] neg_hi:[0,1]
	v_cvt_pk_bf16_f32 v177, v196, v197
	v_lshlrev_b32_e32 v156, 16, v174
	v_and_b32_e32 v157, 0xffff0000, v174
	v_lshlrev_b32_e32 v158, 16, v178
	v_and_b32_e32 v159, 0xffff0000, v178
	v_pk_add_f32 v[156:157], v[156:157], v[158:159]
	v_pk_fma_f32 v[156:157], v[50:51], 0.5, v[156:157] op_sel_hi:[1,0,1]
	v_cvt_pk_bf16_f32 v174, v156, v157
	v_pk_fma_f32 v[198:199], v[156:157], v[156:157], v[198:199]
	v_lshlrev_b32_e32 v158, 16, v174
	v_and_b32_e32 v159, 0xffff0000, v174
	v_pk_add_f32 v[196:197], v[156:157], v[158:159] neg_lo:[0,1] neg_hi:[0,1]
	v_cvt_pk_bf16_f32 v178, v196, v197
	v_lshlrev_b32_e32 v156, 16, v175
	v_and_b32_e32 v157, 0xffff0000, v175
	v_lshlrev_b32_e32 v158, 16, v179
	v_and_b32_e32 v159, 0xffff0000, v179
	v_pk_add_f32 v[156:157], v[156:157], v[158:159]
	v_pk_fma_f32 v[156:157], v[52:53], 0.5, v[156:157] op_sel_hi:[1,0,1]
	v_cvt_pk_bf16_f32 v175, v156, v157
	v_pk_fma_f32 v[198:199], v[156:157], v[156:157], v[198:199]
	v_lshlrev_b32_e32 v158, 16, v175
	v_and_b32_e32 v159, 0xffff0000, v175
	v_pk_add_f32 v[196:197], v[156:157], v[158:159] neg_lo:[0,1] neg_hi:[0,1]
	v_cvt_pk_bf16_f32 v179, v196, v197
	global_store_dwordx4 v211, v[172:175], s[10:11] offset:256
	global_store_dwordx4 v211, v[176:179], s[6:7] offset:256
	v_add_f32_e32 v206, v198, v199
	s_nop 0
	v_add_u32_e32 v211, 0x58000, v213
	global_load_dwordx4 v[164:167], v211, s[10:11]
	global_load_dwordx4 v[168:171], v211, s[6:7]
	global_load_dwordx4 v[172:175], v211, s[10:11] offset:256
	global_load_dwordx4 v[176:179], v211, s[6:7] offset:256
	s_waitcnt vmcnt(18)
; __device__ __forceinline__ unsigned pk2(float lo, float hi) { f32x2_t v = {lo, hi}; bf16x2_t b = __builtin_convertvector(v, bf16x2_t); return __builtin_bit_cast(unsigned, b); }
; __device__ __forceinline__ float bflo(unsigned u) { return __uint_as_float(u << 16); }
;     __device__ __forceinline__ void operator()(const f32x4 (&acc)[2][2][4][2], const Unit& u, int wr, int wc, int fr, int fq) const {
;     ...
;                 for (int bj = 0; bj < 2; ++bj) {
;                     const size_t off = (size_t)row * DM + col0 + bj * HALF;
;                     const u32x4 hh = *(const u32x4*)(HI + off), ll = *(const u32x4*)(LO + off);
;                     float hv[8] = {bflo(hh.x) + bflo(ll.x), bfhi(hh.x) + bfhi(ll.x), bflo(hh.y) + bflo(ll.y), bfhi(hh.y) + bfhi(ll.y),
;                                    bflo(hh.z) + bflo(ll.z), bfhi(hh.z) + bfhi(ll.z), bflo(hh.w) + bflo(ll.w), bfhi(hh.w) + bfhi(ll.w)};
;                     float av[8] = {acc[ai][bj][m][0][0], acc[ai][bj][m][0][1], acc[ai][bj][m][0][2], acc[ai][bj][m][0][3], acc[ai][bj][m][1][0], acc[ai][bj][m][1][1], acc[ai][bj][m][1][2], acc[ai][bj][m][1][3]};
;                     if (GATED) { const u32x4 pp = *(const u32x4*)(PP + off);
;                         const float pv[8] = {bflo(pp.x), bfhi(pp.x), bflo(pp.y), bfhi(pp.y), bflo(pp.z), bfhi(pp.z), bflo(pp.w), bfhi(pp.w)};
; #pragma unroll
;                         for (int e = 0; e < 8; ++e) av[e] = fast_sigmoid(av[e] * rs) * pv[e]; }
;                     else {
; #pragma unroll
;                         for (int e = 0; e < 8; ++e) av[e] *= alpha; }
;                     float lo[8];
; #pragma unroll
;                     for (int e = 0; e < 8; ++e) { hv[e] += av[e]; sq += hv[e] * hv[e]; }
;                     u32x4 wh; wh.x = pk2(hv[0], hv[1]); wh.y = pk2(hv[2], hv[3]); wh.z = pk2(hv[4], hv[5]); wh.w = pk2(hv[6], hv[7]);
;                     lo[0] = hv[0] - bflo(wh.x); lo[1] = hv[1] - bfhi(wh.x); lo[2] = hv[2] - bflo(wh.y); lo[3] = hv[3] - bfhi(wh.y);
;                     lo[4] = hv[4] - bflo(wh.z); lo[5] = hv[5] - bfhi(wh.z); lo[6] = hv[6] - bflo(wh.w); lo[7] = hv[7] - bfhi(wh.w);
;                     u32x4 wl; wl.x = pk2(lo[0], lo[1]); wl.y = pk2(lo[2], lo[3]); wl.z = pk2(lo[4], lo[5]); wl.w = pk2(lo[6], lo[7]);
;                     *(u32x4*)(HO + off) = wh; *(u32x4*)(LO + off) = wl;
	v_lshlrev_b32_e32 v156, 16, v180
	v_and_b32_e32 v157, 0xffff0000, v180
	v_lshlrev_b32_e32 v158, 16, v184
	v_and_b32_e32 v159, 0xffff0000, v184
	v_pk_add_f32 v[156:157], v[156:157], v[158:159]
	v_pk_fma_f32 v[156:157], v[46:47], 0.5, v[156:157] op_sel_hi:[1,0,1]
	v_cvt_pk_bf16_f32 v180, v156, v157
	v_pk_mul_f32 v[198:199], v[156:157], v[156:157]
	v_lshlrev_b32_e32 v158, 16, v180
	v_and_b32_e32 v159, 0xffff0000, v180
	v_pk_add_f32 v[196:197], v[156:157], v[158:159] neg_lo:[0,1] neg_hi:[0,1]
	v_cvt_pk_bf16_f32 v184, v196, v197
	v_lshlrev_b32_e32 v156, 16, v181
	v_and_b32_e32 v157, 0xffff0000, v181
	v_lshlrev_b32_e32 v158, 16, v185
	v_and_b32_e32 v159, 0xffff0000, v185
	v_pk_add_f32 v[156:157], v[156:157], v[158:159]
	v_pk_fma_f32 v[156:157], v[48:49], 0.5, v[156:157] op_sel_hi:[1,0,1]
	v_cvt_pk_bf16_f32 v181, v156, v157
	v_pk_fma_f32 v[198:199], v[156:157], v[156:157], v[198:199]
	v_lshlrev_b32_e32 v158, 16, v181
	v_and_b32_e32 v159, 0xffff0000, v181
	v_pk_add_f32 v[196:197], v[156:157], v[158:159] neg_lo:[0,1] neg_hi:[0,1]
	v_cvt_pk_bf16_f32 v185, v196, v197
	v_lshlrev_b32_e32 v156, 16, v182
	v_and_b32_e32 v157, 0xffff0000, v182
	v_lshlrev_b32_e32 v158, 16, v186
	v_and_b32_e32 v159, 0xffff0000, v186
	v_pk_add_f32 v[156:157], v[156:157], v[158:159]
	v_pk_fma_f32 v[156:157], v[42:43], 0.5, v[156:157] op_sel_hi:[1,0,1]
	v_cvt_pk_bf16_f32 v182, v156, v157
	v_pk_fma_f32 v[198:199], v[156:157], v[156:157], v[198:199]
	v_lshlrev_b32_e32 v158, 16, v182
	v_and_b32_e32 v159, 0xffff0000, v182
	v_pk_add_f32 v[196:197], v[156:157], v[158:159] neg_lo:[0,1] neg_hi:[0,1]
	v_cvt_pk_bf16_f32 v186, v196, v197
	v_lshlrev_b32_e32 v156, 16, v183
	v_and_b32_e32 v157, 0xffff0000, v183
	v_lshlrev_b32_e32 v158, 16, v187
	v_and_b32_e32 v159, 0xffff0000, v187
	v_pk_add_f32 v[156:157], v[156:157], v[158:159]
	v_pk_fma_f32 v[156:157], v[44:45], 0.5, v[156:157] op_sel_hi:[1,0,1]
	v_cvt_pk_bf16_f32 v183, v156, v157
	v_pk_fma_f32 v[198:199], v[156:157], v[156:157], v[198:199]
	v_lshlrev_b32_e32 v158, 16, v183
	v_and_b32_e32 v159, 0xffff0000, v183
	v_pk_add_f32 v[196:197], v[156:157], v[158:159] neg_lo:[0,1] neg_hi:[0,1]
	v_cvt_pk_bf16_f32 v187, v196, v197
	global_store_dwordx4 v212, v[180:183], s[10:11]
	global_store_dwordx4 v212, v[184:187], s[6:7]
	s_waitcnt vmcnt(18)
	v_lshlrev_b32_e32 v156, 16, v188
	v_and_b32_e32 v157, 0xffff0000, v188
	v_lshlrev_b32_e32 v158, 16, v192
	v_and_b32_e32 v159, 0xffff0000, v192
	v_pk_add_f32 v[156:157], v[156:157], v[158:159]
	v_pk_fma_f32 v[156:157], v[38:39], 0.5, v[156:157] op_sel_hi:[1,0,1]
	v_cvt_pk_bf16_f32 v188, v156, v157
	v_pk_fma_f32 v[198:199], v[156:157], v[156:157], v[198:199]
	v_lshlrev_b32_e32 v158, 16, v188
	v_and_b32_e32 v159, 0xffff0000, v188
	v_pk_add_f32 v[196:197], v[156:157], v[158:159] neg_lo:[0,1] neg_hi:[0,1]
	v_cvt_pk_bf16_f32 v192, v196, v197
	v_lshlrev_b32_e32 v156, 16, v189
	v_and_b32_e32 v157, 0xffff0000, v189
	v_lshlrev_b32_e32 v158, 16, v193
	v_and_b32_e32 v159, 0xffff0000, v193
	v_pk_add_f32 v[156:157], v[156:157], v[158:159]
	v_pk_fma_f32 v[156:157], v[40:41], 0.5, v[156:157] op_sel_hi:[1,0,1]
	v_cvt_pk_bf16_f32 v189, v156, v157
	v_pk_fma_f32 v[198:199], v[156:157], v[156:157], v[198:199]
	v_lshlrev_b32_e32 v158, 16, v189
	v_and_b32_e32 v159, 0xffff0000, v189
	v_pk_add_f32 v[196:197], v[156:157], v[158:159] neg_lo:[0,1] neg_hi:[0,1]
	v_cvt_pk_bf16_f32 v193, v196, v197
	v_lshlrev_b32_e32 v156, 16, v190
	v_and_b32_e32 v157, 0xffff0000, v190
	v_lshlrev_b32_e32 v158, 16, v194
	v_and_b32_e32 v159, 0xffff0000, v194
	v_pk_add_f32 v[156:157], v[156:157], v[158:159]
	v_pk_fma_f32 v[156:157], v[34:35], 0.5, v[156:157] op_sel_hi:[1,0,1]
	v_cvt_pk_bf16_f32 v190, v156, v157
	v_pk_fma_f32 v[198:199], v[156:157], v[156:157], v[198:199]
	v_lshlrev_b32_e32 v158, 16, v190
	v_and_b32_e32 v159, 0xffff0000, v190
	v_pk_add_f32 v[196:197], v[156:157], v[158:159] neg_lo:[0,1] neg_hi:[0,1]
	v_cvt_pk_bf16_f32 v194, v196, v197
	v_lshlrev_b32_e32 v156, 16, v191
	v_and_b32_e32 v157, 0xffff0000, v191
	v_lshlrev_b32_e32 v158, 16, v195
	v_and_b32_e32 v159, 0xffff0000, v195
	v_pk_add_f32 v[156:157], v[156:157], v[158:159]
	v_pk_fma_f32 v[156:157], v[36:37], 0.5, v[156:157] op_sel_hi:[1,0,1]
	v_cvt_pk_bf16_f32 v191, v156, v157
	v_pk_fma_f32 v[198:199], v[156:157], v[156:157], v[198:199]
	v_lshlrev_b32_e32 v158, 16, v191
	v_and_b32_e32 v159, 0xffff0000, v191
	v_pk_add_f32 v[196:197], v[156:157], v[158:159] neg_lo:[0,1] neg_hi:[0,1]
	v_cvt_pk_bf16_f32 v195, v196, v197
	global_store_dwordx4 v212, v[188:191], s[10:11] offset:256
	global_store_dwordx4 v212, v[192:195], s[6:7] offset:256
	v_add_f32_e32 v207, v198, v199
	s_waitcnt vmcnt(14)
; __device__ __forceinline__ unsigned pk2(float lo, float hi) { f32x2_t v = {lo, hi}; bf16x2_t b = __builtin_convertvector(v, bf16x2_t); return __builtin_bit_cast(unsigned, b); }
; __device__ __forceinline__ float bflo(unsigned u) { return __uint_as_float(u << 16); }
;     __device__ __forceinline__ void operator()(const f32x4 (&acc)[2][2][4][2], const Unit& u, int wr, int wc, int fr, int fq) const {
;     ...
;                 for (int bj = 0; bj < 2; ++bj) {
;                     const size_t off = (size_t)row * DM + col0 + bj * HALF;
;                     const u32x4 hh = *(const u32x4*)(HI + off), ll = *(const u32x4*)(LO + off);
;                     float hv[8] = {bflo(hh.x) + bflo(ll.x), bfhi(hh.x) + bfhi(ll.x), bflo(hh.y) + bflo(ll.y), bfhi(hh.y) + bfhi(ll.y),
;                                    bflo(hh.z) + bflo(ll.z), bfhi(hh.z) + bfhi(ll.z), bflo(hh.w) + bflo(ll.w), bfhi(hh.w) + bfhi(ll.w)};
;                     float av[8] = {acc[ai][bj][m][0][0], acc[ai][bj][m][0][1], acc[ai][bj][m][0][2], acc[ai][bj][m][0][3], acc[ai][bj][m][1][0], acc[ai][bj][m][1][1], acc[ai][bj][m][1][2], acc[ai][bj][m][1][3]};
;                     if (GATED) { const u32x4 pp = *(const u32x4*)(PP + off);
;                         const float pv[8] = {bflo(pp.x), bfhi(pp.x), bflo(pp.y), bfhi(pp.y), bflo(pp.z), bfhi(pp.z), bflo(pp.w), bfhi(pp.w)};
; #pragma unroll
;                         for (int e = 0; e < 8; ++e) av[e] = fast_sigmoid(av[e] * rs) * pv[e]; }
;                     else {
; #pragma unroll
;                         for (int e = 0; e < 8; ++e) av[e] *= alpha; }
;                     float lo[8];
; #pragma unroll
;                     for (int e = 0; e < 8; ++e) { hv[e] += av[e]; sq += hv[e] * hv[e]; }
;                     u32x4 wh; wh.x = pk2(hv[0], hv[1]); wh.y = pk2(hv[2], hv[3]); wh.z = pk2(hv[4], hv[5]); wh.w = pk2(hv[6], hv[7]);
;                     lo[0] = hv[0] - bflo(wh.x); lo[1] = hv[1] - bfhi(wh.x); lo[2] = hv[2] - bflo(wh.y); lo[3] = hv[3] - bfhi(wh.y);
;                     lo[4] = hv[4] - bflo(wh.z); lo[5] = hv[5] - bfhi(wh.z); lo[6] = hv[6] - bflo(wh.w); lo[7] = hv[7] - bfhi(wh.w);
;                     u32x4 wl; wl.x = pk2(lo[0], lo[1]); wl.y = pk2(lo[2], lo[3]); wl.z = pk2(lo[4], lo[5]); wl.w = pk2(lo[6], lo[7]);
;                     *(u32x4*)(HO + off) = wh; *(u32x4*)(LO + off) = wl;
	v_lshlrev_b32_e32 v156, 16, v140
	v_and_b32_e32 v157, 0xffff0000, v140
	v_lshlrev_b32_e32 v158, 16, v144
	v_and_b32_e32 v159, 0xffff0000, v144
	v_pk_add_f32 v[156:157], v[156:157], v[158:159]
	v_pk_fma_f32 v[156:157], v[30:31], 0.5, v[156:157] op_sel_hi:[1,0,1]
	v_cvt_pk_bf16_f32 v140, v156, v157
	v_pk_mul_f32 v[198:199], v[156:157], v[156:157]
	v_lshlrev_b32_e32 v158, 16, v140
	v_and_b32_e32 v159, 0xffff0000, v140
	v_pk_add_f32 v[196:197], v[156:157], v[158:159] neg_lo:[0,1] neg_hi:[0,1]
	v_cvt_pk_bf16_f32 v144, v196, v197
	v_lshlrev_b32_e32 v156, 16, v141
	v_and_b32_e32 v157, 0xffff0000, v141
	v_lshlrev_b32_e32 v158, 16, v145
	v_and_b32_e32 v159, 0xffff0000, v145
	v_pk_add_f32 v[156:157], v[156:157], v[158:159]
	v_pk_fma_f32 v[156:157], v[32:33], 0.5, v[156:157] op_sel_hi:[1,0,1]
	v_cvt_pk_bf16_f32 v141, v156, v157
	v_pk_fma_f32 v[198:199], v[156:157], v[156:157], v[198:199]
	v_lshlrev_b32_e32 v158, 16, v141
	v_and_b32_e32 v159, 0xffff0000, v141
	v_pk_add_f32 v[196:197], v[156:157], v[158:159] neg_lo:[0,1] neg_hi:[0,1]
	v_cvt_pk_bf16_f32 v145, v196, v197
	v_lshlrev_b32_e32 v156, 16, v142
	v_and_b32_e32 v157, 0xffff0000, v142
	v_lshlrev_b32_e32 v158, 16, v146
	v_and_b32_e32 v159, 0xffff0000, v146
	v_pk_add_f32 v[156:157], v[156:157], v[158:159]
	v_pk_fma_f32 v[156:157], v[26:27], 0.5, v[156:157] op_sel_hi:[1,0,1]
	v_cvt_pk_bf16_f32 v142, v156, v157
	v_pk_fma_f32 v[198:199], v[156:157], v[156:157], v[198:199]
	v_lshlrev_b32_e32 v158, 16, v142
	v_and_b32_e32 v159, 0xffff0000, v142
	v_pk_add_f32 v[196:197], v[156:157], v[158:159] neg_lo:[0,1] neg_hi:[0,1]
	v_cvt_pk_bf16_f32 v146, v196, v197
	v_lshlrev_b32_e32 v156, 16, v143
	v_and_b32_e32 v157, 0xffff0000, v143
	v_lshlrev_b32_e32 v158, 16, v147
	v_and_b32_e32 v159, 0xffff0000, v147
	v_pk_add_f32 v[156:157], v[156:157], v[158:159]
	v_pk_fma_f32 v[156:157], v[28:29], 0.5, v[156:157] op_sel_hi:[1,0,1]
	v_cvt_pk_bf16_f32 v143, v156, v157
	v_pk_fma_f32 v[198:199], v[156:157], v[156:157], v[198:199]
	v_lshlrev_b32_e32 v158, 16, v143
	v_and_b32_e32 v159, 0xffff0000, v143
	v_pk_add_f32 v[196:197], v[156:157], v[158:159] neg_lo:[0,1] neg_hi:[0,1]
	v_cvt_pk_bf16_f32 v147, v196, v197
	global_store_dwordx4 v210, v[140:143], s[10:11]
	global_store_dwordx4 v210, v[144:147], s[6:7]
	s_waitcnt vmcnt(14)
	v_lshlrev_b32_e32 v156, 16, v148
	v_and_b32_e32 v157, 0xffff0000, v148
	v_lshlrev_b32_e32 v158, 16, v152
	v_and_b32_e32 v159, 0xffff0000, v152
	v_pk_add_f32 v[156:157], v[156:157], v[158:159]
	v_pk_fma_f32 v[156:157], v[22:23], 0.5, v[156:157] op_sel_hi:[1,0,1]
	v_cvt_pk_bf16_f32 v148, v156, v157
	v_pk_fma_f32 v[198:199], v[156:157], v[156:157], v[198:199]
	v_lshlrev_b32_e32 v158, 16, v148
	v_and_b32_e32 v159, 0xffff0000, v148
	v_pk_add_f32 v[196:197], v[156:157], v[158:159] neg_lo:[0,1] neg_hi:[0,1]
	v_cvt_pk_bf16_f32 v152, v196, v197
	v_lshlrev_b32_e32 v156, 16, v149
	v_and_b32_e32 v157, 0xffff0000, v149
	v_lshlrev_b32_e32 v158, 16, v153
	v_and_b32_e32 v159, 0xffff0000, v153
	v_pk_add_f32 v[156:157], v[156:157], v[158:159]
	v_pk_fma_f32 v[156:157], v[24:25], 0.5, v[156:157] op_sel_hi:[1,0,1]
	v_cvt_pk_bf16_f32 v149, v156, v157
	v_pk_fma_f32 v[198:199], v[156:157], v[156:157], v[198:199]
	v_lshlrev_b32_e32 v158, 16, v149
	v_and_b32_e32 v159, 0xffff0000, v149
	v_pk_add_f32 v[196:197], v[156:157], v[158:159] neg_lo:[0,1] neg_hi:[0,1]
	v_cvt_pk_bf16_f32 v153, v196, v197
	v_lshlrev_b32_e32 v156, 16, v150
	v_and_b32_e32 v157, 0xffff0000, v150
	v_lshlrev_b32_e32 v158, 16, v154
	v_and_b32_e32 v159, 0xffff0000, v154
	v_pk_add_f32 v[156:157], v[156:157], v[158:159]
	v_pk_fma_f32 v[156:157], v[18:19], 0.5, v[156:157] op_sel_hi:[1,0,1]
	v_cvt_pk_bf16_f32 v150, v156, v157
	v_pk_fma_f32 v[198:199], v[156:157], v[156:157], v[198:199]
	v_lshlrev_b32_e32 v158, 16, v150
	v_and_b32_e32 v159, 0xffff0000, v150
	v_pk_add_f32 v[196:197], v[156:157], v[158:159] neg_lo:[0,1] neg_hi:[0,1]
	v_cvt_pk_bf16_f32 v154, v196, v197
	v_lshlrev_b32_e32 v156, 16, v151
	v_and_b32_e32 v157, 0xffff0000, v151
	v_lshlrev_b32_e32 v158, 16, v155
	v_and_b32_e32 v159, 0xffff0000, v155
	v_pk_add_f32 v[156:157], v[156:157], v[158:159]
	v_pk_fma_f32 v[156:157], v[20:21], 0.5, v[156:157] op_sel_hi:[1,0,1]
	v_cvt_pk_bf16_f32 v151, v156, v157
	v_pk_fma_f32 v[198:199], v[156:157], v[156:157], v[198:199]
	v_lshlrev_b32_e32 v158, 16, v151
	v_and_b32_e32 v159, 0xffff0000, v151
	v_pk_add_f32 v[196:197], v[156:157], v[158:159] neg_lo:[0,1] neg_hi:[0,1]
	v_cvt_pk_bf16_f32 v155, v196, v197
	global_store_dwordx4 v210, v[148:151], s[10:11] offset:256
	global_store_dwordx4 v210, v[152:155], s[6:7] offset:256
	v_add_f32_e32 v208, v198, v199
	s_waitcnt vmcnt(10)
; __device__ __forceinline__ float bflo(unsigned u) { return __uint_as_float(u << 16); }
;     __device__ __forceinline__ void operator()(const f32x4 (&acc)[2][2][4][2], const Unit& u, int wr, int wc, int fr, int fq) const {
;     ...
;                 for (int bj = 0; bj < 2; ++bj) {
;                     const size_t off = (size_t)row * DM + col0 + bj * HALF;
;                     const u32x4 hh = *(const u32x4*)(HI + off), ll = *(const u32x4*)(LO + off);
;                     float hv[8] = {bflo(hh.x) + bflo(ll.x), bfhi(hh.x) + bfhi(ll.x), bflo(hh.y) + bflo(ll.y), bfhi(hh.y) + bfhi(ll.y),
;                                    bflo(hh.z) + bflo(ll.z), bfhi(hh.z) + bfhi(ll.z), bflo(hh.w) + bflo(ll.w), bfhi(hh.w) + bfhi(ll.w)};
;                     float av[8] = {acc[ai][bj][m][0][0], acc[ai][bj][m][0][1], acc[ai][bj][m][0][2], acc[ai][bj][m][0][3], acc[ai][bj][m][1][0], acc[ai][bj][m][1][1], acc[ai][bj][m][1][2], acc[ai][bj][m][1][3]};
;                     if (GATED) { const u32x4 pp = *(const u32x4*)(PP + off);
;                         const float pv[8] = {bflo(pp.x), bfhi(pp.x), bflo(pp.y), bfhi(pp.y), bflo(pp.z), bfhi(pp.z), bflo(pp.w), bfhi(pp.w)};
; #pragma unroll
;                         for (int e = 0; e < 8; ++e) av[e] = fast_sigmoid(av[e] * rs) * pv[e]; }
;                     else {
; #pragma unroll
;                         for (int e = 0; e < 8; ++e) av[e] *= alpha; }
;                     float lo[8];
; #pragma unroll
;                     for (int e = 0; e < 8; ++e) { hv[e] += av[e]; sq += hv[e] * hv[e]; }
;                     u32x4 wh; wh.x = pk2(hv[0], hv[1]); wh.y = pk2(hv[2], hv[3]); wh.z = pk2(hv[4], hv[5]); wh.w = pk2(hv[6], hv[7]);
;                     lo[0] = hv[0] - bflo(wh.x); lo[1] = hv[1] - bfhi(wh.x); lo[2] = hv[2] - bflo(wh.y); lo[3] = hv[3] - bfhi(wh.y);
;                     lo[4] = hv[4] - bflo(wh.z); lo[5] = hv[5] - bfhi(wh.z); lo[6] = hv[6] - bflo(wh.w); lo[7] = hv[7] - bfhi(wh.w);
;                     u32x4 wl; wl.x = pk2(lo[0], lo[1]); wl.y = pk2(lo[2], lo[3]); wl.z = pk2(lo[4], lo[5]); wl.w = pk2(lo[6], lo[7]);
;                     *(u32x4*)(HO + off) = wh; *(u32x4*)(LO + off) = wl;
;                 }
;                 sq += __shfl_xor(sq, 16); sq += __shfl_xor(sq, 32);
;                 if (fq == 0) ssq_out[(size_t)row * 16 + 4 * u.pn + wc] = sq;
	v_lshlrev_b32_e32 v156, 16, v164
	v_and_b32_e32 v157, 0xffff0000, v164
	v_lshlrev_b32_e32 v158, 16, v168
	v_and_b32_e32 v159, 0xffff0000, v168
	v_pk_add_f32 v[156:157], v[156:157], v[158:159]
	v_pk_fma_f32 v[156:157], v[14:15], 0.5, v[156:157] op_sel_hi:[1,0,1]
	v_cvt_pk_bf16_f32 v164, v156, v157
	v_pk_mul_f32 v[198:199], v[156:157], v[156:157]
	v_lshlrev_b32_e32 v158, 16, v164
	v_and_b32_e32 v159, 0xffff0000, v164
	v_pk_add_f32 v[196:197], v[156:157], v[158:159] neg_lo:[0,1] neg_hi:[0,1]
	v_cvt_pk_bf16_f32 v168, v196, v197
	v_lshlrev_b32_e32 v156, 16, v165
	v_and_b32_e32 v157, 0xffff0000, v165
	v_lshlrev_b32_e32 v158, 16, v169
	v_and_b32_e32 v159, 0xffff0000, v169
	v_pk_add_f32 v[156:157], v[156:157], v[158:159]
	v_pk_fma_f32 v[156:157], v[16:17], 0.5, v[156:157] op_sel_hi:[1,0,1]
	v_cvt_pk_bf16_f32 v165, v156, v157
	v_pk_fma_f32 v[198:199], v[156:157], v[156:157], v[198:199]
	v_lshlrev_b32_e32 v158, 16, v165
	v_and_b32_e32 v159, 0xffff0000, v165
	v_pk_add_f32 v[196:197], v[156:157], v[158:159] neg_lo:[0,1] neg_hi:[0,1]
	v_cvt_pk_bf16_f32 v169, v196, v197
	v_lshlrev_b32_e32 v156, 16, v166
	v_and_b32_e32 v157, 0xffff0000, v166
	v_lshlrev_b32_e32 v158, 16, v170
	v_and_b32_e32 v159, 0xffff0000, v170
	v_pk_add_f32 v[156:157], v[156:157], v[158:159]
	v_pk_fma_f32 v[156:157], v[10:11], 0.5, v[156:157] op_sel_hi:[1,0,1]
	v_cvt_pk_bf16_f32 v166, v156, v157
	v_pk_fma_f32 v[198:199], v[156:157], v[156:157], v[198:199]
	v_lshlrev_b32_e32 v158, 16, v166
	v_and_b32_e32 v159, 0xffff0000, v166
	v_pk_add_f32 v[196:197], v[156:157], v[158:159] neg_lo:[0,1] neg_hi:[0,1]
	v_cvt_pk_bf16_f32 v170, v196, v197
	v_lshlrev_b32_e32 v156, 16, v167
	v_and_b32_e32 v157, 0xffff0000, v167
	v_lshlrev_b32_e32 v158, 16, v171
	v_and_b32_e32 v159, 0xffff0000, v171
	v_pk_add_f32 v[156:157], v[156:157], v[158:159]
	v_pk_fma_f32 v[156:157], v[12:13], 0.5, v[156:157] op_sel_hi:[1,0,1]
	v_cvt_pk_bf16_f32 v167, v156, v157
	v_pk_fma_f32 v[198:199], v[156:157], v[156:157], v[198:199]
	v_lshlrev_b32_e32 v158, 16, v167
	v_and_b32_e32 v159, 0xffff0000, v167
	v_pk_add_f32 v[196:197], v[156:157], v[158:159] neg_lo:[0,1] neg_hi:[0,1]
	v_cvt_pk_bf16_f32 v171, v196, v197
	global_store_dwordx4 v211, v[164:167], s[10:11]
	global_store_dwordx4 v211, v[168:171], s[6:7]
	s_waitcnt vmcnt(10)
	v_lshlrev_b32_e32 v156, 16, v172
	v_and_b32_e32 v157, 0xffff0000, v172
	v_lshlrev_b32_e32 v158, 16, v176
	v_and_b32_e32 v159, 0xffff0000, v176
	v_pk_add_f32 v[156:157], v[156:157], v[158:159]
	v_pk_fma_f32 v[156:157], v[6:7], 0.5, v[156:157] op_sel_hi:[1,0,1]
	v_cvt_pk_bf16_f32 v172, v156, v157
	v_pk_fma_f32 v[198:199], v[156:157], v[156:157], v[198:199]
	v_lshlrev_b32_e32 v158, 16, v172
	v_and_b32_e32 v159, 0xffff0000, v172
	v_pk_add_f32 v[196:197], v[156:157], v[158:159] neg_lo:[0,1] neg_hi:[0,1]
	v_cvt_pk_bf16_f32 v176, v196, v197
	v_lshlrev_b32_e32 v156, 16, v173
	v_and_b32_e32 v157, 0xffff0000, v173
	v_lshlrev_b32_e32 v158, 16, v177
	v_and_b32_e32 v159, 0xffff0000, v177
	v_pk_add_f32 v[156:157], v[156:157], v[158:159]
	v_pk_fma_f32 v[156:157], v[8:9], 0.5, v[156:157] op_sel_hi:[1,0,1]
	v_cvt_pk_bf16_f32 v173, v156, v157
	v_pk_fma_f32 v[198:199], v[156:157], v[156:157], v[198:199]
	v_lshlrev_b32_e32 v158, 16, v173
	v_and_b32_e32 v159, 0xffff0000, v173
	v_pk_add_f32 v[196:197], v[156:157], v[158:159] neg_lo:[0,1] neg_hi:[0,1]
	v_cvt_pk_bf16_f32 v177, v196, v197
	v_lshlrev_b32_e32 v156, 16, v174
	v_and_b32_e32 v157, 0xffff0000, v174
	v_lshlrev_b32_e32 v158, 16, v178
	v_and_b32_e32 v159, 0xffff0000, v178
	v_pk_add_f32 v[156:157], v[156:157], v[158:159]
	v_pk_fma_f32 v[156:157], v[2:3], 0.5, v[156:157] op_sel_hi:[1,0,1]
	v_cvt_pk_bf16_f32 v174, v156, v157
	v_pk_fma_f32 v[198:199], v[156:157], v[156:157], v[198:199]
	v_lshlrev_b32_e32 v158, 16, v174
	v_and_b32_e32 v159, 0xffff0000, v174
	v_pk_add_f32 v[196:197], v[156:157], v[158:159] neg_lo:[0,1] neg_hi:[0,1]
	v_cvt_pk_bf16_f32 v178, v196, v197
	v_lshlrev_b32_e32 v156, 16, v175
	v_and_b32_e32 v157, 0xffff0000, v175
	v_lshlrev_b32_e32 v158, 16, v179
	v_and_b32_e32 v159, 0xffff0000, v179
	v_pk_add_f32 v[156:157], v[156:157], v[158:159]
	v_pk_fma_f32 v[156:157], v[4:5], 0.5, v[156:157] op_sel_hi:[1,0,1]
	v_cvt_pk_bf16_f32 v175, v156, v157
	v_pk_fma_f32 v[198:199], v[156:157], v[156:157], v[198:199]
	v_lshlrev_b32_e32 v158, 16, v175
	v_and_b32_e32 v159, 0xffff0000, v175
	v_pk_add_f32 v[196:197], v[156:157], v[158:159] neg_lo:[0,1] neg_hi:[0,1]
	v_cvt_pk_bf16_f32 v179, v196, v197
	global_store_dwordx4 v211, v[172:175], s[10:11] offset:256
	global_store_dwordx4 v211, v[176:179], s[6:7] offset:256
	v_add_f32_e32 v209, v198, v199
	ds_bpermute_b32 v140, v214, v200
	ds_bpermute_b32 v141, v214, v201
	ds_bpermute_b32 v142, v214, v202
	ds_bpermute_b32 v143, v214, v203
	ds_bpermute_b32 v144, v214, v206
	ds_bpermute_b32 v145, v214, v207
	ds_bpermute_b32 v146, v214, v208
	ds_bpermute_b32 v147, v214, v209
	v_readlane_b32 s50, v250, 39
	v_readlane_b32 s51, v250, 40
	s_waitcnt lgkmcnt(0)
	v_add_f32_e32 v200, v200, v140
	v_add_f32_e32 v201, v201, v141
	v_add_f32_e32 v202, v202, v142
	v_add_f32_e32 v203, v203, v143
	v_add_f32_e32 v206, v206, v144
	v_add_f32_e32 v207, v207, v145
	v_add_f32_e32 v208, v208, v146
	v_add_f32_e32 v209, v209, v147
	ds_bpermute_b32 v140, v215, v200
	ds_bpermute_b32 v141, v215, v201
	ds_bpermute_b32 v142, v215, v202
	ds_bpermute_b32 v143, v215, v203
	ds_bpermute_b32 v144, v215, v206
	ds_bpermute_b32 v145, v215, v207
	ds_bpermute_b32 v146, v215, v208
	ds_bpermute_b32 v147, v215, v209
	s_waitcnt lgkmcnt(0)
	v_add_f32_e32 v200, v200, v140
	v_add_f32_e32 v201, v201, v141
	v_add_f32_e32 v202, v202, v142
	v_add_f32_e32 v203, v203, v143
	v_add_f32_e32 v206, v206, v144
	v_add_f32_e32 v207, v207, v145
	v_add_f32_e32 v208, v208, v146
	v_add_f32_e32 v209, v209, v147
	s_and_saveexec_b64 s[12:13], s[42:43]
	s_cbranch_execz .Lepir_f2d_skip
	global_store_dword v216, v200, s[50:51]
	global_store_dword v216, v201, s[50:51] offset:1024
	global_store_dword v216, v202, s[50:51] offset:2048
	global_store_dword v216, v203, s[50:51] offset:3072
	global_store_dword v217, v206, s[50:51]
	global_store_dword v217, v207, s[50:51] offset:1024
	global_store_dword v217, v208, s[50:51] offset:2048
	global_store_dword v217, v209, s[50:51] offset:3072
